# dil lean loop now reads a padded (bank-conflict-free) copy of the dilation-1 bias tables built once per layer in free LDS; keeps norm prefetches
# speedup vs baseline: 1.0253x; 1.0113x over previous
; #define LAS __attribute__((address_space(3)))
; __device__ __forceinline__ void attn_setup(const float* par, int l, LAS unsigned char* lds) {
;     ...
;     LAS float* tl = (LAS float*)(lds + TDIL_OFF);
;     for (int i = tid; i < 6 * TDIL_STRIDE; i += 512) { const int hd = i / TDIL_STRIDE, j = i % TDIL_STRIDE; const int b = j < 1152 ? 0 : (j < 1560 ? 1 : 2), jj = j - (b == 0 ? 0 : (b == 1 ? 1152 : 1560));
;         const int r = (b == 0) ? 1 : (b == 1 ? 4 : 16), f = 16 / r, mm = jj - (64 + 31 * f);
;         tl[i] = (mm >= -64 && mm <= 64) ? (rb[rel_bucket(r * mm) * 10 + 4 + hd] - misc[4 + hd]) * LOG2E : -1e30f; }
; __device__ __forceinline__ void attn_phase(unsigned char* ws, int l, LAS unsigned char* lds, int G) {
;     ...
;     for (int bu = vb; bu < 1152; bu += G) {
;         const int sh = bu >> 6, rem = bu & 63, T0 = (rem >> 1) * 512, rho = (rem & 1) * 8 + wid;
;         dil_unit(lds, proj, sh / 6, sh % 6, T0, rho);
.LBB0_551:
	s_cmpk_gt_i32 s33, 0x47f
	s_waitcnt lgkmcnt(0)
	s_barrier
	s_cbranch_scc1 .LBB0_561
	v_lshlrev_b32_e32 v200, 2, v154
	v_add_u32_e32 v200, 0x15c00, v200
	v_add_u32_e32 v201, 0, v154
	v_lshrrev_b32_e32 v204, 4, v201
	v_add_u32_e32 v201, v201, v204
	v_lshlrev_b32_e32 v201, 2, v201
	v_add_u32_e32 v201, 0x8000, v201
	v_add_u32_e32 v202, 512, v154
	v_lshrrev_b32_e32 v204, 4, v202
	v_add_u32_e32 v202, v202, v204
	v_lshlrev_b32_e32 v202, 2, v202
	v_add_u32_e32 v202, 0x8000, v202
	v_add_u32_e32 v203, 1024, v154
	v_lshrrev_b32_e32 v204, 4, v203
	v_add_u32_e32 v203, v203, v204
	v_lshlrev_b32_e32 v203, 2, v203
	v_add_u32_e32 v203, 0x8000, v203
	v_readfirstlane_b32 s82, v154
	s_nop 3
	s_cmp_lt_u32 s82, 128
	s_cbranch_scc0 .Lpt0_two
	ds_read_b32 v205, v200 offset:0
	ds_read_b32 v206, v200 offset:2048
	ds_read_b32 v207, v200 offset:4096
	ds_read_b32 v208, v200 offset:7168
	ds_read_b32 v209, v200 offset:9216
	ds_read_b32 v210, v200 offset:11264
	ds_read_b32 v211, v200 offset:14336
	ds_read_b32 v212, v200 offset:16384
	ds_read_b32 v213, v200 offset:18432
	ds_read_b32 v214, v200 offset:21504
	ds_read_b32 v215, v200 offset:23552
	ds_read_b32 v216, v200 offset:25600
	ds_read_b32 v217, v200 offset:28672
	ds_read_b32 v218, v200 offset:30720
	ds_read_b32 v219, v200 offset:32768
	ds_read_b32 v220, v200 offset:35840
	ds_read_b32 v221, v200 offset:37888
	ds_read_b32 v222, v200 offset:39936
	s_waitcnt lgkmcnt(0)
	ds_write_b32 v201, v205 offset:0
	ds_write_b32 v202, v206 offset:0
	ds_write_b32 v203, v207 offset:0
	ds_write_b32 v201, v208 offset:4896
	ds_write_b32 v202, v209 offset:4896
	ds_write_b32 v203, v210 offset:4896
	ds_write_b32 v201, v211 offset:9792
	ds_write_b32 v202, v212 offset:9792
	ds_write_b32 v203, v213 offset:9792
	ds_write_b32 v201, v214 offset:14688
	ds_write_b32 v202, v215 offset:14688
	ds_write_b32 v203, v216 offset:14688
	ds_write_b32 v201, v217 offset:19584
	ds_write_b32 v202, v218 offset:19584
	ds_write_b32 v203, v219 offset:19584
	ds_write_b32 v201, v220 offset:24480
	ds_write_b32 v202, v221 offset:24480
	ds_write_b32 v203, v222 offset:24480
	s_branch .Lpt0_done
.Lpt0_two:
	ds_read_b32 v205, v200 offset:0
	ds_read_b32 v206, v200 offset:2048
	ds_read_b32 v207, v200 offset:7168
	ds_read_b32 v208, v200 offset:9216
	ds_read_b32 v209, v200 offset:14336
	ds_read_b32 v210, v200 offset:16384
	ds_read_b32 v211, v200 offset:21504
	ds_read_b32 v212, v200 offset:23552
	ds_read_b32 v213, v200 offset:28672
	ds_read_b32 v214, v200 offset:30720
	ds_read_b32 v215, v200 offset:35840
	ds_read_b32 v216, v200 offset:37888
	s_waitcnt lgkmcnt(0)
	ds_write_b32 v201, v205 offset:0
	ds_write_b32 v202, v206 offset:0
	ds_write_b32 v201, v207 offset:4896
	ds_write_b32 v202, v208 offset:4896
	ds_write_b32 v201, v209 offset:9792
	ds_write_b32 v202, v210 offset:9792
	ds_write_b32 v201, v211 offset:14688
	ds_write_b32 v202, v212 offset:14688
	ds_write_b32 v201, v213 offset:19584
	ds_write_b32 v202, v214 offset:19584
	ds_write_b32 v201, v215 offset:24480
	ds_write_b32 v202, v216 offset:24480
.Lpt0_done:
	s_waitcnt lgkmcnt(0)
	s_barrier
	s_lshr_b32 s64, s20, 6
	s_movk_i32 s65, 0x1800
	v_mov_b32_e32 v81, 0
	s_mov_b64 s[52:53], 0x1200
	s_movk_i32 s66, 0x1000
	s_mov_b64 s[54:55], 0x1500
	s_movk_i32 s67, 0x480
	s_movk_i32 s69, 0xbc
	s_movk_i32 s71, 0x4000
	v_mbcnt_hi_u32_b32 v102, -1, v155
	s_branch .LBB0_554

; #define LAS __attribute__((address_space(3)))
; #define GAS __attribute__((address_space(1)))
; __device__ __forceinline__ void dil_unit(LAS unsigned char* lds, bf16_t* proj, int seq, int hd, int T0, int rho) {
;     ...
;     const int tid = tid_, lane = tid & 63, r32 = lane & 31, hi = lane >> 5, wid = __builtin_amdgcn_readfirstlane(tid >> 6);
;     bf16_t* base = proj + (size_t)seq * SEQ * NIN;
;     LAS unsigned char* wbuf = lds + wid * 4096;
;     const LAS unsigned char* vp = wbuf + ((lane >> 4) & 1) * 32 + (lane & 3) * 8 + (4 * hi + ((lane & 15) >> 2)) * 64;
;     const int P0 = T0 + rho;
;     bf16x8 qr[4];
; #pragma unroll
;     for (int ks = 0; ks < 4; ++ks) qr[ks] = *(const GAS bf16x8*)(base + (size_t)(P0 + 16 * r32) * NIN + PC_LQ + hd * 64 + 16 * ks + 8 * hi);
;     f32x16 o0 = {}, o1 = {}; float l = 0.f;
;     const bool bound = (T0 < 1024) || (T0 >= 15360);
.LBB0_554:
	s_lshr_b32 s82, s33, 8
	s_mul_i32 s82, s82, 13
	s_add_i32 s82, s82, s33
	s_ashr_i32 s2, s33, 6
	s_mul_hi_i32 s7, s2, 0x2aaaaaab
	s_lshl_b32 s3, s82, 8
	s_lshr_b32 s8, s7, 31
	s_and_b32 s6, s3, 0x3e00
	s_lshl_b32 s3, s82, 3
	s_add_i32 s7, s7, s8
	s_and_b32 s3, s3, 8
	s_mul_i32 s8, s7, 6
	s_add_i32 s3, s3, s64
	s_sub_i32 s8, s2, s8
	s_mul_hi_i32 s2, s7, 0x6000000
	s_mul_i32 s7, s7, 0x6000000
	v_mov_b32_e32 v2, v154
	s_add_u32 s56, s48, s7
	s_addc_u32 s57, s49, s2
	v_and_b32_e32 v105, 31, v2
	s_add_i32 s76, s3, s6
	v_lshl_add_u32 v3, v105, 4, s76
	v_mov_b64_e32 v[0:1], s[56:57]
	s_lshl_b32 s58, s8, 6
	v_bfe_u32 v106, v2, 5, 1
	v_mad_u64_u32 v[0:1], s[2:3], v3, s65, v[0:1]
	s_ashr_i32 s59, s58, 31
	v_lshl_add_u64 v[0:1], s[58:59], 1, v[0:1]
	v_lshlrev_b32_e32 v80, 4, v106
	v_lshl_add_u64 v[0:1], v[0:1], 0, v[80:81]
	global_load_dwordx4 v[48:51], v[0:1], off offset:1280
	global_load_dwordx4 v[52:55], v[0:1], off offset:1312
	global_load_dwordx4 v[56:59], v[0:1], off offset:1344
	global_load_dwordx4 v[60:63], v[0:1], off offset:1376
	v_readfirstlane_b32 s2, v2
	s_lshl_b32 s2, s2, 6
	s_and_b32 s2, s2, 0xfffff000
	v_lshlrev_b32_e32 v0, 1, v2
	v_lshlrev_b32_e32 v104, 3, v2
	v_lshlrev_b32_e32 v107, 2, v106
	v_lshrrev_b32_e32 v1, 2, v2
	v_and_b32_e32 v103, 63, v2
	v_and_b32_e32 v0, 32, v0
	v_and_b32_e32 v98, 24, v104
	v_and_or_b32 v1, v1, 3, v107
	s_add_i32 s77, s2, 0
	v_lshlrev_b32_e32 v108, 6, v1
	v_lshlrev_b32_e32 v1, 3, v106
	v_add3_u32 v109, s77, v0, v98
	s_addk_i32 s6, 0xc400
	v_lshrrev_b32_e32 v110, 2, v103
	v_lshlrev_b32_e32 v0, 4, v103
	s_mov_b64 s[2:3], -1
	s_cmp_gt_u32 s6, 0xffffc7ff
	v_lshlrev_b32_e32 v100, 1, v98
	s_mul_i32 s6, s8, 0x1c00
	v_lshlrev_b32_e32 v82, 1, v1
	v_or_b32_e32 v111, 16, v110
	v_add_u32_e32 v112, s77, v0
	s_cbranch_scc0 .LBB0_558
	s_movk_i32 s100, 0x1800
	s_add_i32 s101, s6, 0x15c00
	s_lshl_b32 s90, s58, 1
	s_add_u32 s82, s56, s90
	s_addc_u32 s83, s57, 0
	s_add_u32 s82, s82, 0x1200
	s_addc_u32 s83, s83, 0
	s_sub_i32 s90, s76, 64
	s_mul_i32 s90, s90, 0x1800
	s_add_u32 s84, s82, s90
	s_addc_u32 s85, s83, 0
	s_sub_i32 s90, s76, 256
	s_mul_i32 s90, s90, 0x1800
	s_add_u32 s86, s82, s90
	s_addc_u32 s87, s83, 0
	s_sub_i32 s90, s76, 1024
	s_mul_i32 s90, s90, 0x1800
	s_add_u32 s88, s82, s90
	s_addc_u32 s89, s83, 0
	v_lshlrev_b32_e32 v153, 1, v98
	v_mad_u32_u24 v80, v105, s100, v82
	v_mad_u32_u24 v100, v110, s100, v153
	v_add_u32_e32 v149, 0x18000, v100
	v_lshlrev_b32_e32 v83, 2, v105
	v_mad_u32_u24 v83, v83, s100, v82
	v_lshlrev_b32_e32 v101, 2, v110
	v_mad_u32_u24 v101, v101, s100, v153
	v_add_u32_e32 v150, 0x60000, v101
	v_lshlrev_b32_e32 v99, 4, v105
	v_mad_u32_u24 v99, v99, s100, v82
	v_lshlrev_b32_e32 v148, 4, v110
	v_mad_u32_u24 v148, v148, s100, v153
	v_add_u32_e32 v151, 0x180000, v148
	v_mul_u32_u24_e32 v228, 17, v105
	v_sub_u32_e32 v228, v107, v228
	s_mul_i32 s90, s58, 153
	s_lshr_b32 s90, s90, 1
	s_add_i32 s90, s90, 34876
	v_lshl_add_u32 v228, v228, 2, s90
	v_lshlrev_b32_e32 v229, 2, v105
	v_sub_u32_e32 v229, v107, v229
	s_add_i32 s90, s101, 5104
	v_lshl_add_u32 v229, v229, 2, s90
	v_sub_u32_e32 v230, v107, v105
	s_add_i32 s90, s101, 6364
	v_lshl_add_u32 v230, v230, 2, s90
	v_add_u32_e32 v231, v109, v108
	v_mov_b64_e32 v[232:233], 0
	v_mov_b64_e32 v[0:1], 0
	v_mov_b64_e32 v[2:3], 0
	v_mov_b64_e32 v[4:5], 0
	v_mov_b64_e32 v[6:7], 0
	v_mov_b64_e32 v[8:9], 0
	v_mov_b64_e32 v[10:11], 0
	v_mov_b64_e32 v[12:13], 0
	v_mov_b64_e32 v[14:15], 0
	v_mov_b64_e32 v[16:17], 0
	v_mov_b64_e32 v[18:19], 0
	v_mov_b64_e32 v[20:21], 0
	v_mov_b64_e32 v[22:23], 0
	v_mov_b64_e32 v[24:25], 0
	v_mov_b64_e32 v[26:27], 0
	v_mov_b64_e32 v[28:29], 0
	v_mov_b64_e32 v[30:31], 0
	global_load_dwordx4 v[116:119], v80, s[84:85]
	global_load_dwordx4 v[120:123], v80, s[84:85] offset:32
	global_load_dwordx4 v[124:127], v80, s[84:85] offset:64
	global_load_dwordx4 v[128:131], v80, s[84:85] offset:96
	global_load_dwordx4 v[132:135], v100, s[84:85] offset:768
	global_load_dwordx4 v[136:139], v149, s[84:85] offset:768
	global_load_dwordx4 v[140:143], v100, s[84:85] offset:832
	global_load_dwordx4 v[144:147], v149, s[84:85] offset:832
	s_add_u32 s84, s84, 0x30000
	s_addc_u32 s85, s85, 0
	global_load_dwordx4 v[156:159], v80, s[84:85]
	global_load_dwordx4 v[160:163], v80, s[84:85] offset:32
	global_load_dwordx4 v[164:167], v80, s[84:85] offset:64
	global_load_dwordx4 v[168:171], v80, s[84:85] offset:96
	global_load_dwordx4 v[172:175], v100, s[84:85] offset:768
	global_load_dwordx4 v[176:179], v149, s[84:85] offset:768
	global_load_dwordx4 v[180:183], v100, s[84:85] offset:832
	global_load_dwordx4 v[184:187], v149, s[84:85] offset:832
	s_add_u32 s84, s84, 0x30000
	s_addc_u32 s85, s85, 0
	global_load_dwordx4 v[188:191], v80, s[84:85]
	global_load_dwordx4 v[192:195], v80, s[84:85] offset:32
	global_load_dwordx4 v[196:199], v80, s[84:85] offset:64
	global_load_dwordx4 v[200:203], v80, s[84:85] offset:96
	global_load_dwordx4 v[204:207], v100, s[84:85] offset:768
	global_load_dwordx4 v[208:211], v149, s[84:85] offset:768
	global_load_dwordx4 v[212:215], v100, s[84:85] offset:832
	global_load_dwordx4 v[216:219], v149, s[84:85] offset:832
	s_add_u32 s84, s84, 0x30000
	s_addc_u32 s85, s85, 0
	s_waitcnt vmcnt(16)
	ds_write_b128 v112, v[132:135]
	ds_write_b128 v112, v[136:139] offset:1024
	ds_write_b128 v112, v[140:143] offset:2048
	ds_write_b128 v112, v[144:147] offset:3072
	v_mov_b32_e32 v115, v228
	ds_read2_b32 v[32:33], v115 offset0:0 offset1:1
	ds_read2_b32 v[34:35], v115 offset0:2 offset1:3
	ds_read2_b32 v[36:37], v115 offset0:8 offset1:9
	ds_read2_b32 v[38:39], v115 offset0:10 offset1:11
	ds_read2_b32 v[40:41], v115 offset0:17 offset1:18
	ds_read2_b32 v[42:43], v115 offset0:19 offset1:20
	ds_read2_b32 v[44:45], v115 offset0:25 offset1:26
	ds_read2_b32 v[46:47], v115 offset0:27 offset1:28
	s_waitcnt lgkmcnt(0)
	v_mfma_f32_32x32x16_bf16 v[32:47], v[116:119], v[48:51], v[32:47]
	ds_read_b64_tr_b16 v[72:73], v231
	ds_read_b64_tr_b16 v[74:75], v231 offset:512
	ds_read_b64_tr_b16 v[76:77], v231 offset:2048
	ds_read_b64_tr_b16 v[78:79], v231 offset:2560
	ds_read_b64_tr_b16 v[220:221], v231 offset:1024
	ds_read_b64_tr_b16 v[222:223], v231 offset:1536
	ds_read_b64_tr_b16 v[224:225], v231 offset:3072
	ds_read_b64_tr_b16 v[226:227], v231 offset:3584
	v_mfma_f32_32x32x16_bf16 v[32:47], v[120:123], v[52:55], v[32:47]
	v_mfma_f32_32x32x16_bf16 v[32:47], v[124:127], v[56:59], v[32:47]
	v_mfma_f32_32x32x16_bf16 v[32:47], v[128:131], v[60:63], v[32:47]
	s_nop 11
	v_exp_f32_e32 v32, v32
	v_exp_f32_e32 v33, v33
	v_exp_f32_e32 v34, v34
	v_exp_f32_e32 v35, v35
	v_exp_f32_e32 v36, v36
	v_exp_f32_e32 v37, v37
	v_exp_f32_e32 v38, v38
	v_exp_f32_e32 v39, v39
	v_exp_f32_e32 v40, v40
	v_exp_f32_e32 v41, v41
	v_exp_f32_e32 v42, v42
	v_exp_f32_e32 v43, v43
	v_exp_f32_e32 v44, v44
	v_exp_f32_e32 v45, v45
	v_exp_f32_e32 v46, v46
	v_exp_f32_e32 v47, v47
	v_cvt_pk_bf16_f32 v64, v32, v33
	v_cvt_pk_bf16_f32 v65, v34, v35
	v_cvt_pk_bf16_f32 v66, v36, v37
	v_cvt_pk_bf16_f32 v67, v38, v39
	v_cvt_pk_bf16_f32 v68, v40, v41
	v_cvt_pk_bf16_f32 v69, v42, v43
	v_cvt_pk_bf16_f32 v70, v44, v45
	v_cvt_pk_bf16_f32 v71, v46, v47
	v_pk_add_f32 v[232:233], v[232:233], v[32:33]
	v_pk_add_f32 v[232:233], v[232:233], v[34:35]
	v_pk_add_f32 v[232:233], v[232:233], v[36:37]
	v_pk_add_f32 v[232:233], v[232:233], v[38:39]
	v_pk_add_f32 v[232:233], v[232:233], v[40:41]
	v_pk_add_f32 v[232:233], v[232:233], v[42:43]
	v_pk_add_f32 v[232:233], v[232:233], v[44:45]
	v_pk_add_f32 v[232:233], v[232:233], v[46:47]
	s_waitcnt lgkmcnt(0)
	v_mfma_f32_32x32x16_bf16 v[0:15], v[64:67], v[72:75], v[0:15]
	v_mfma_f32_32x32x16_bf16 v[16:31], v[64:67], v[76:79], v[16:31]
	v_mfma_f32_32x32x16_bf16 v[0:15], v[68:71], v[220:223], v[0:15]
	v_mfma_f32_32x32x16_bf16 v[16:31], v[68:71], v[224:227], v[16:31]
	global_load_dwordx4 v[116:119], v80, s[84:85]
	global_load_dwordx4 v[120:123], v80, s[84:85] offset:32
	global_load_dwordx4 v[124:127], v80, s[84:85] offset:64
	global_load_dwordx4 v[128:131], v80, s[84:85] offset:96
	global_load_dwordx4 v[132:135], v100, s[84:85] offset:768
	global_load_dwordx4 v[136:139], v149, s[84:85] offset:768
	global_load_dwordx4 v[140:143], v100, s[84:85] offset:832
	global_load_dwordx4 v[144:147], v149, s[84:85] offset:832
	s_add_u32 s84, s84, 0x30000
	s_addc_u32 s85, s85, 0
	s_waitcnt vmcnt(16)
	ds_write_b128 v112, v[172:175]
	ds_write_b128 v112, v[176:179] offset:1024
	ds_write_b128 v112, v[180:183] offset:2048
	ds_write_b128 v112, v[184:187] offset:3072
	ds_read2_b32 v[32:33], v115 offset0:34 offset1:35
	ds_read2_b32 v[34:35], v115 offset0:36 offset1:37
	ds_read2_b32 v[36:37], v115 offset0:42 offset1:43
	ds_read2_b32 v[38:39], v115 offset0:44 offset1:45
	ds_read2_b32 v[40:41], v115 offset0:51 offset1:52
	ds_read2_b32 v[42:43], v115 offset0:53 offset1:54
	ds_read2_b32 v[44:45], v115 offset0:59 offset1:60
	ds_read2_b32 v[46:47], v115 offset0:61 offset1:62
	s_waitcnt lgkmcnt(0)
	v_mfma_f32_32x32x16_bf16 v[32:47], v[156:159], v[48:51], v[32:47]
	ds_read_b64_tr_b16 v[72:73], v231
	ds_read_b64_tr_b16 v[74:75], v231 offset:512
	ds_read_b64_tr_b16 v[76:77], v231 offset:2048
	ds_read_b64_tr_b16 v[78:79], v231 offset:2560
	ds_read_b64_tr_b16 v[220:221], v231 offset:1024
	ds_read_b64_tr_b16 v[222:223], v231 offset:1536
	ds_read_b64_tr_b16 v[224:225], v231 offset:3072
	ds_read_b64_tr_b16 v[226:227], v231 offset:3584
	v_mfma_f32_32x32x16_bf16 v[32:47], v[160:163], v[52:55], v[32:47]
	v_mfma_f32_32x32x16_bf16 v[32:47], v[164:167], v[56:59], v[32:47]
	v_mfma_f32_32x32x16_bf16 v[32:47], v[168:171], v[60:63], v[32:47]
	s_nop 11
	v_exp_f32_e32 v32, v32
	v_exp_f32_e32 v33, v33
	v_exp_f32_e32 v34, v34
	v_exp_f32_e32 v35, v35
	v_exp_f32_e32 v36, v36
	v_exp_f32_e32 v37, v37
	v_exp_f32_e32 v38, v38
	v_exp_f32_e32 v39, v39
	v_exp_f32_e32 v40, v40
	v_exp_f32_e32 v41, v41
	v_exp_f32_e32 v42, v42
	v_exp_f32_e32 v43, v43
	v_exp_f32_e32 v44, v44
	v_exp_f32_e32 v45, v45
	v_exp_f32_e32 v46, v46
	v_exp_f32_e32 v47, v47
	v_cvt_pk_bf16_f32 v64, v32, v33
	v_cvt_pk_bf16_f32 v65, v34, v35
	v_cvt_pk_bf16_f32 v66, v36, v37
	v_cvt_pk_bf16_f32 v67, v38, v39
	v_cvt_pk_bf16_f32 v68, v40, v41
	v_cvt_pk_bf16_f32 v69, v42, v43
	v_cvt_pk_bf16_f32 v70, v44, v45
	v_cvt_pk_bf16_f32 v71, v46, v47
	v_pk_add_f32 v[232:233], v[232:233], v[32:33]
	v_pk_add_f32 v[232:233], v[232:233], v[34:35]
	v_pk_add_f32 v[232:233], v[232:233], v[36:37]
	v_pk_add_f32 v[232:233], v[232:233], v[38:39]
	v_pk_add_f32 v[232:233], v[232:233], v[40:41]
	v_pk_add_f32 v[232:233], v[232:233], v[42:43]
	v_pk_add_f32 v[232:233], v[232:233], v[44:45]
	v_pk_add_f32 v[232:233], v[232:233], v[46:47]
	s_waitcnt lgkmcnt(0)
	v_mfma_f32_32x32x16_bf16 v[0:15], v[64:67], v[72:75], v[0:15]
	v_mfma_f32_32x32x16_bf16 v[16:31], v[64:67], v[76:79], v[16:31]
	v_mfma_f32_32x32x16_bf16 v[0:15], v[68:71], v[220:223], v[0:15]
	v_mfma_f32_32x32x16_bf16 v[16:31], v[68:71], v[224:227], v[16:31]
	global_load_dwordx4 v[156:159], v80, s[84:85]
	global_load_dwordx4 v[160:163], v80, s[84:85] offset:32
	global_load_dwordx4 v[164:167], v80, s[84:85] offset:64
	global_load_dwordx4 v[168:171], v80, s[84:85] offset:96
	global_load_dwordx4 v[172:175], v100, s[84:85] offset:768
	global_load_dwordx4 v[176:179], v149, s[84:85] offset:768
	global_load_dwordx4 v[180:183], v100, s[84:85] offset:832
	global_load_dwordx4 v[184:187], v149, s[84:85] offset:832
	s_add_u32 s84, s84, 0x30000
	s_addc_u32 s85, s85, 0
	s_waitcnt vmcnt(16)
	ds_write_b128 v112, v[204:207]
	ds_write_b128 v112, v[208:211] offset:1024
	ds_write_b128 v112, v[212:215] offset:2048
	ds_write_b128 v112, v[216:219] offset:3072
	ds_read2_b32 v[32:33], v115 offset0:68 offset1:69
	ds_read2_b32 v[34:35], v115 offset0:70 offset1:71
	ds_read2_b32 v[36:37], v115 offset0:76 offset1:77
	ds_read2_b32 v[38:39], v115 offset0:78 offset1:79
	ds_read2_b32 v[40:41], v115 offset0:85 offset1:86
	ds_read2_b32 v[42:43], v115 offset0:87 offset1:88
	ds_read2_b32 v[44:45], v115 offset0:93 offset1:94
	ds_read2_b32 v[46:47], v115 offset0:95 offset1:96
	s_waitcnt lgkmcnt(0)
	v_mfma_f32_32x32x16_bf16 v[32:47], v[188:191], v[48:51], v[32:47]
	ds_read_b64_tr_b16 v[72:73], v231
	ds_read_b64_tr_b16 v[74:75], v231 offset:512
	ds_read_b64_tr_b16 v[76:77], v231 offset:2048
	ds_read_b64_tr_b16 v[78:79], v231 offset:2560
	ds_read_b64_tr_b16 v[220:221], v231 offset:1024
	ds_read_b64_tr_b16 v[222:223], v231 offset:1536
	ds_read_b64_tr_b16 v[224:225], v231 offset:3072
	ds_read_b64_tr_b16 v[226:227], v231 offset:3584
	v_mfma_f32_32x32x16_bf16 v[32:47], v[192:195], v[52:55], v[32:47]
	v_mfma_f32_32x32x16_bf16 v[32:47], v[196:199], v[56:59], v[32:47]
	v_mfma_f32_32x32x16_bf16 v[32:47], v[200:203], v[60:63], v[32:47]
	s_nop 11
	v_exp_f32_e32 v32, v32
	v_exp_f32_e32 v33, v33
	v_exp_f32_e32 v34, v34
	v_exp_f32_e32 v35, v35
	v_exp_f32_e32 v36, v36
	v_exp_f32_e32 v37, v37
	v_exp_f32_e32 v38, v38
	v_exp_f32_e32 v39, v39
	v_exp_f32_e32 v40, v40
	v_exp_f32_e32 v41, v41
	v_exp_f32_e32 v42, v42
	v_exp_f32_e32 v43, v43
	v_exp_f32_e32 v44, v44
	v_exp_f32_e32 v45, v45
	v_exp_f32_e32 v46, v46
	v_exp_f32_e32 v47, v47
	v_cvt_pk_bf16_f32 v64, v32, v33
	v_cvt_pk_bf16_f32 v65, v34, v35
	v_cvt_pk_bf16_f32 v66, v36, v37
	v_cvt_pk_bf16_f32 v67, v38, v39
	v_cvt_pk_bf16_f32 v68, v40, v41
	v_cvt_pk_bf16_f32 v69, v42, v43
	v_cvt_pk_bf16_f32 v70, v44, v45
	v_cvt_pk_bf16_f32 v71, v46, v47
	v_pk_add_f32 v[232:233], v[232:233], v[32:33]
	v_pk_add_f32 v[232:233], v[232:233], v[34:35]
	v_pk_add_f32 v[232:233], v[232:233], v[36:37]
	v_pk_add_f32 v[232:233], v[232:233], v[38:39]
	v_pk_add_f32 v[232:233], v[232:233], v[40:41]
	v_pk_add_f32 v[232:233], v[232:233], v[42:43]
	v_pk_add_f32 v[232:233], v[232:233], v[44:45]
	v_pk_add_f32 v[232:233], v[232:233], v[46:47]
	s_waitcnt lgkmcnt(0)
	v_mfma_f32_32x32x16_bf16 v[0:15], v[64:67], v[72:75], v[0:15]
	v_mfma_f32_32x32x16_bf16 v[16:31], v[64:67], v[76:79], v[16:31]
	v_mfma_f32_32x32x16_bf16 v[0:15], v[68:71], v[220:223], v[0:15]
	v_mfma_f32_32x32x16_bf16 v[16:31], v[68:71], v[224:227], v[16:31]
	global_load_dwordx4 v[188:191], v80, s[84:85]
	global_load_dwordx4 v[192:195], v80, s[84:85] offset:32
	global_load_dwordx4 v[196:199], v80, s[84:85] offset:64
	global_load_dwordx4 v[200:203], v80, s[84:85] offset:96
	global_load_dwordx4 v[204:207], v100, s[84:85] offset:768
	global_load_dwordx4 v[208:211], v149, s[84:85] offset:768
	global_load_dwordx4 v[212:215], v100, s[84:85] offset:832
	global_load_dwordx4 v[216:219], v149, s[84:85] offset:832
	s_add_u32 s84, s84, 0x30000
	s_addc_u32 s85, s85, 0
	s_waitcnt vmcnt(16)
	ds_write_b128 v112, v[132:135]
	ds_write_b128 v112, v[136:139] offset:1024
	ds_write_b128 v112, v[140:143] offset:2048
	ds_write_b128 v112, v[144:147] offset:3072
	ds_read2_b32 v[32:33], v115 offset0:102 offset1:103
	ds_read2_b32 v[34:35], v115 offset0:104 offset1:105
	ds_read2_b32 v[36:37], v115 offset0:110 offset1:111
	ds_read2_b32 v[38:39], v115 offset0:112 offset1:113
	ds_read2_b32 v[40:41], v115 offset0:119 offset1:120
	ds_read2_b32 v[42:43], v115 offset0:121 offset1:122
	ds_read2_b32 v[44:45], v115 offset0:127 offset1:128
	ds_read2_b32 v[46:47], v115 offset0:129 offset1:130
	s_waitcnt lgkmcnt(0)
	v_mfma_f32_32x32x16_bf16 v[32:47], v[116:119], v[48:51], v[32:47]
	ds_read_b64_tr_b16 v[72:73], v231
	ds_read_b64_tr_b16 v[74:75], v231 offset:512
	ds_read_b64_tr_b16 v[76:77], v231 offset:2048
	ds_read_b64_tr_b16 v[78:79], v231 offset:2560
	ds_read_b64_tr_b16 v[220:221], v231 offset:1024
	ds_read_b64_tr_b16 v[222:223], v231 offset:1536
	ds_read_b64_tr_b16 v[224:225], v231 offset:3072
	ds_read_b64_tr_b16 v[226:227], v231 offset:3584
	v_mfma_f32_32x32x16_bf16 v[32:47], v[120:123], v[52:55], v[32:47]
	v_mfma_f32_32x32x16_bf16 v[32:47], v[124:127], v[56:59], v[32:47]
	v_mfma_f32_32x32x16_bf16 v[32:47], v[128:131], v[60:63], v[32:47]
	s_nop 11
	v_exp_f32_e32 v32, v32
	v_exp_f32_e32 v33, v33
	v_exp_f32_e32 v34, v34
	v_exp_f32_e32 v35, v35
	v_exp_f32_e32 v36, v36
	v_exp_f32_e32 v37, v37
	v_exp_f32_e32 v38, v38
	v_exp_f32_e32 v39, v39
	v_exp_f32_e32 v40, v40
	v_exp_f32_e32 v41, v41
	v_exp_f32_e32 v42, v42
	v_exp_f32_e32 v43, v43
	v_exp_f32_e32 v44, v44
	v_exp_f32_e32 v45, v45
	v_exp_f32_e32 v46, v46
	v_exp_f32_e32 v47, v47
	v_cvt_pk_bf16_f32 v64, v32, v33
	v_cvt_pk_bf16_f32 v65, v34, v35
	v_cvt_pk_bf16_f32 v66, v36, v37
	v_cvt_pk_bf16_f32 v67, v38, v39
	v_cvt_pk_bf16_f32 v68, v40, v41
	v_cvt_pk_bf16_f32 v69, v42, v43
	v_cvt_pk_bf16_f32 v70, v44, v45
	v_cvt_pk_bf16_f32 v71, v46, v47
	v_pk_add_f32 v[232:233], v[232:233], v[32:33]
	v_pk_add_f32 v[232:233], v[232:233], v[34:35]
	v_pk_add_f32 v[232:233], v[232:233], v[36:37]
	v_pk_add_f32 v[232:233], v[232:233], v[38:39]
	v_pk_add_f32 v[232:233], v[232:233], v[40:41]
	v_pk_add_f32 v[232:233], v[232:233], v[42:43]
	v_pk_add_f32 v[232:233], v[232:233], v[44:45]
	v_pk_add_f32 v[232:233], v[232:233], v[46:47]
	s_waitcnt lgkmcnt(0)
	v_mfma_f32_32x32x16_bf16 v[0:15], v[64:67], v[72:75], v[0:15]
	v_mfma_f32_32x32x16_bf16 v[16:31], v[64:67], v[76:79], v[16:31]
	v_mfma_f32_32x32x16_bf16 v[0:15], v[68:71], v[220:223], v[0:15]
	v_mfma_f32_32x32x16_bf16 v[16:31], v[68:71], v[224:227], v[16:31]
	global_load_dwordx4 v[116:119], v80, s[84:85]
	global_load_dwordx4 v[120:123], v80, s[84:85] offset:32
	global_load_dwordx4 v[124:127], v80, s[84:85] offset:64
	global_load_dwordx4 v[128:131], v80, s[84:85] offset:96
	global_load_dwordx4 v[132:135], v100, s[84:85] offset:768
	global_load_dwordx4 v[136:139], v149, s[84:85] offset:768
	global_load_dwordx4 v[140:143], v100, s[84:85] offset:832
	global_load_dwordx4 v[144:147], v149, s[84:85] offset:832
	s_add_u32 s84, s84, 0x30000
	s_addc_u32 s85, s85, 0
	s_waitcnt vmcnt(16)
	ds_write_b128 v112, v[172:175]
	ds_write_b128 v112, v[176:179] offset:1024
	ds_write_b128 v112, v[180:183] offset:2048
	ds_write_b128 v112, v[184:187] offset:3072
	ds_read2_b32 v[32:33], v115 offset0:136 offset1:137
	ds_read2_b32 v[34:35], v115 offset0:138 offset1:139
	ds_read2_b32 v[36:37], v115 offset0:144 offset1:145
	ds_read2_b32 v[38:39], v115 offset0:146 offset1:147
	ds_read2_b32 v[40:41], v115 offset0:153 offset1:154
	ds_read2_b32 v[42:43], v115 offset0:155 offset1:156
	ds_read2_b32 v[44:45], v115 offset0:161 offset1:162
	ds_read2_b32 v[46:47], v115 offset0:163 offset1:164
	s_waitcnt lgkmcnt(0)
	v_mfma_f32_32x32x16_bf16 v[32:47], v[156:159], v[48:51], v[32:47]
	ds_read_b64_tr_b16 v[72:73], v231
	ds_read_b64_tr_b16 v[74:75], v231 offset:512
	ds_read_b64_tr_b16 v[76:77], v231 offset:2048
	ds_read_b64_tr_b16 v[78:79], v231 offset:2560
	ds_read_b64_tr_b16 v[220:221], v231 offset:1024
	ds_read_b64_tr_b16 v[222:223], v231 offset:1536
	ds_read_b64_tr_b16 v[224:225], v231 offset:3072
	ds_read_b64_tr_b16 v[226:227], v231 offset:3584
	v_mfma_f32_32x32x16_bf16 v[32:47], v[160:163], v[52:55], v[32:47]
	v_mfma_f32_32x32x16_bf16 v[32:47], v[164:167], v[56:59], v[32:47]
	v_mfma_f32_32x32x16_bf16 v[32:47], v[168:171], v[60:63], v[32:47]
	s_nop 11
	v_exp_f32_e32 v32, v32
	v_exp_f32_e32 v33, v33
	v_exp_f32_e32 v34, v34
	v_exp_f32_e32 v35, v35
	v_exp_f32_e32 v36, v36
	v_exp_f32_e32 v37, v37
	v_exp_f32_e32 v38, v38
	v_exp_f32_e32 v39, v39
	v_exp_f32_e32 v40, v40
	v_exp_f32_e32 v41, v41
	v_exp_f32_e32 v42, v42
	v_exp_f32_e32 v43, v43
	v_exp_f32_e32 v44, v44
	v_exp_f32_e32 v45, v45
	v_exp_f32_e32 v46, v46
	v_exp_f32_e32 v47, v47
	v_cvt_pk_bf16_f32 v64, v32, v33
	v_cvt_pk_bf16_f32 v65, v34, v35
	v_cvt_pk_bf16_f32 v66, v36, v37
	v_cvt_pk_bf16_f32 v67, v38, v39
	v_cvt_pk_bf16_f32 v68, v40, v41
	v_cvt_pk_bf16_f32 v69, v42, v43
	v_cvt_pk_bf16_f32 v70, v44, v45
	v_cvt_pk_bf16_f32 v71, v46, v47
	v_pk_add_f32 v[232:233], v[232:233], v[32:33]
	v_pk_add_f32 v[232:233], v[232:233], v[34:35]
	v_pk_add_f32 v[232:233], v[232:233], v[36:37]
	v_pk_add_f32 v[232:233], v[232:233], v[38:39]
	v_pk_add_f32 v[232:233], v[232:233], v[40:41]
	v_pk_add_f32 v[232:233], v[232:233], v[42:43]
	v_pk_add_f32 v[232:233], v[232:233], v[44:45]
	v_pk_add_f32 v[232:233], v[232:233], v[46:47]
	s_waitcnt lgkmcnt(0)
	v_mfma_f32_32x32x16_bf16 v[0:15], v[64:67], v[72:75], v[0:15]
	v_mfma_f32_32x32x16_bf16 v[16:31], v[64:67], v[76:79], v[16:31]
	v_mfma_f32_32x32x16_bf16 v[0:15], v[68:71], v[220:223], v[0:15]
	v_mfma_f32_32x32x16_bf16 v[16:31], v[68:71], v[224:227], v[16:31]
	global_load_dwordx4 v[156:159], v80, s[84:85]
	global_load_dwordx4 v[160:163], v80, s[84:85] offset:32
	global_load_dwordx4 v[164:167], v80, s[84:85] offset:64
	global_load_dwordx4 v[168:171], v80, s[84:85] offset:96
	global_load_dwordx4 v[172:175], v100, s[84:85] offset:768
	global_load_dwordx4 v[176:179], v149, s[84:85] offset:768
	global_load_dwordx4 v[180:183], v100, s[84:85] offset:832
	global_load_dwordx4 v[184:187], v149, s[84:85] offset:832
	s_add_u32 s84, s84, 0x30000
	s_addc_u32 s85, s85, 0
	s_waitcnt vmcnt(16)
	ds_write_b128 v112, v[204:207]
	ds_write_b128 v112, v[208:211] offset:1024
	ds_write_b128 v112, v[212:215] offset:2048
	ds_write_b128 v112, v[216:219] offset:3072
	ds_read2_b32 v[32:33], v115 offset0:170 offset1:171
	ds_read2_b32 v[34:35], v115 offset0:172 offset1:173
	ds_read2_b32 v[36:37], v115 offset0:178 offset1:179
	ds_read2_b32 v[38:39], v115 offset0:180 offset1:181
	ds_read2_b32 v[40:41], v115 offset0:187 offset1:188
	ds_read2_b32 v[42:43], v115 offset0:189 offset1:190
	ds_read2_b32 v[44:45], v115 offset0:195 offset1:196
	ds_read2_b32 v[46:47], v115 offset0:197 offset1:198
	s_waitcnt lgkmcnt(0)
	v_mfma_f32_32x32x16_bf16 v[32:47], v[188:191], v[48:51], v[32:47]
	ds_read_b64_tr_b16 v[72:73], v231
	ds_read_b64_tr_b16 v[74:75], v231 offset:512
	ds_read_b64_tr_b16 v[76:77], v231 offset:2048
	ds_read_b64_tr_b16 v[78:79], v231 offset:2560
	ds_read_b64_tr_b16 v[220:221], v231 offset:1024
	ds_read_b64_tr_b16 v[222:223], v231 offset:1536
	ds_read_b64_tr_b16 v[224:225], v231 offset:3072
	ds_read_b64_tr_b16 v[226:227], v231 offset:3584
	v_mfma_f32_32x32x16_bf16 v[32:47], v[192:195], v[52:55], v[32:47]
	v_mfma_f32_32x32x16_bf16 v[32:47], v[196:199], v[56:59], v[32:47]
	v_mfma_f32_32x32x16_bf16 v[32:47], v[200:203], v[60:63], v[32:47]
	s_nop 11
	v_exp_f32_e32 v32, v32
	v_exp_f32_e32 v33, v33
	v_exp_f32_e32 v34, v34
	v_exp_f32_e32 v35, v35
	v_exp_f32_e32 v36, v36
	v_exp_f32_e32 v37, v37
	v_exp_f32_e32 v38, v38
	v_exp_f32_e32 v39, v39
	v_exp_f32_e32 v40, v40
	v_exp_f32_e32 v41, v41
	v_exp_f32_e32 v42, v42
	v_exp_f32_e32 v43, v43
	v_exp_f32_e32 v44, v44
	v_exp_f32_e32 v45, v45
	v_exp_f32_e32 v46, v46
	v_exp_f32_e32 v47, v47
	v_cvt_pk_bf16_f32 v64, v32, v33
	v_cvt_pk_bf16_f32 v65, v34, v35
	v_cvt_pk_bf16_f32 v66, v36, v37
	v_cvt_pk_bf16_f32 v67, v38, v39
	v_cvt_pk_bf16_f32 v68, v40, v41
	v_cvt_pk_bf16_f32 v69, v42, v43
	v_cvt_pk_bf16_f32 v70, v44, v45
	v_cvt_pk_bf16_f32 v71, v46, v47
	v_pk_add_f32 v[232:233], v[232:233], v[32:33]
	v_pk_add_f32 v[232:233], v[232:233], v[34:35]
	v_pk_add_f32 v[232:233], v[232:233], v[36:37]
	v_pk_add_f32 v[232:233], v[232:233], v[38:39]
	v_pk_add_f32 v[232:233], v[232:233], v[40:41]
	v_pk_add_f32 v[232:233], v[232:233], v[42:43]
	v_pk_add_f32 v[232:233], v[232:233], v[44:45]
	v_pk_add_f32 v[232:233], v[232:233], v[46:47]
	s_waitcnt lgkmcnt(0)
	v_mfma_f32_32x32x16_bf16 v[0:15], v[64:67], v[72:75], v[0:15]
	v_mfma_f32_32x32x16_bf16 v[16:31], v[64:67], v[76:79], v[16:31]
	v_mfma_f32_32x32x16_bf16 v[0:15], v[68:71], v[220:223], v[0:15]
	v_mfma_f32_32x32x16_bf16 v[16:31], v[68:71], v[224:227], v[16:31]
	global_load_dwordx4 v[188:191], v80, s[84:85]
	global_load_dwordx4 v[192:195], v80, s[84:85] offset:32
	global_load_dwordx4 v[196:199], v80, s[84:85] offset:64
	global_load_dwordx4 v[200:203], v80, s[84:85] offset:96
	global_load_dwordx4 v[204:207], v100, s[84:85] offset:768
	global_load_dwordx4 v[208:211], v149, s[84:85] offset:768
	global_load_dwordx4 v[212:215], v100, s[84:85] offset:832
	global_load_dwordx4 v[216:219], v149, s[84:85] offset:832
	s_add_u32 s84, s84, 0x30000
	s_addc_u32 s85, s85, 0
	s_waitcnt vmcnt(16)
	ds_write_b128 v112, v[132:135]
	ds_write_b128 v112, v[136:139] offset:1024
	ds_write_b128 v112, v[140:143] offset:2048
	ds_write_b128 v112, v[144:147] offset:3072
	ds_read2_b32 v[32:33], v115 offset0:204 offset1:205
	ds_read2_b32 v[34:35], v115 offset0:206 offset1:207
	ds_read2_b32 v[36:37], v115 offset0:212 offset1:213
	ds_read2_b32 v[38:39], v115 offset0:214 offset1:215
	ds_read2_b32 v[40:41], v115 offset0:221 offset1:222
	ds_read2_b32 v[42:43], v115 offset0:223 offset1:224
	ds_read2_b32 v[44:45], v115 offset0:229 offset1:230
	ds_read2_b32 v[46:47], v115 offset0:231 offset1:232
	s_waitcnt lgkmcnt(0)
	v_mfma_f32_32x32x16_bf16 v[32:47], v[116:119], v[48:51], v[32:47]
	ds_read_b64_tr_b16 v[72:73], v231
	ds_read_b64_tr_b16 v[74:75], v231 offset:512
	ds_read_b64_tr_b16 v[76:77], v231 offset:2048
	ds_read_b64_tr_b16 v[78:79], v231 offset:2560
	ds_read_b64_tr_b16 v[220:221], v231 offset:1024
	ds_read_b64_tr_b16 v[222:223], v231 offset:1536
	ds_read_b64_tr_b16 v[224:225], v231 offset:3072
	ds_read_b64_tr_b16 v[226:227], v231 offset:3584
	v_mfma_f32_32x32x16_bf16 v[32:47], v[120:123], v[52:55], v[32:47]
	v_mfma_f32_32x32x16_bf16 v[32:47], v[124:127], v[56:59], v[32:47]
	v_mfma_f32_32x32x16_bf16 v[32:47], v[128:131], v[60:63], v[32:47]
	s_nop 11
	v_exp_f32_e32 v32, v32
	v_exp_f32_e32 v33, v33
	v_exp_f32_e32 v34, v34
	v_exp_f32_e32 v35, v35
	v_exp_f32_e32 v36, v36
	v_exp_f32_e32 v37, v37
	v_exp_f32_e32 v38, v38
	v_exp_f32_e32 v39, v39
	v_exp_f32_e32 v40, v40
	v_exp_f32_e32 v41, v41
	v_exp_f32_e32 v42, v42
	v_exp_f32_e32 v43, v43
	v_exp_f32_e32 v44, v44
	v_exp_f32_e32 v45, v45
	v_exp_f32_e32 v46, v46
	v_exp_f32_e32 v47, v47
	v_cvt_pk_bf16_f32 v64, v32, v33
	v_cvt_pk_bf16_f32 v65, v34, v35
	v_cvt_pk_bf16_f32 v66, v36, v37
	v_cvt_pk_bf16_f32 v67, v38, v39
	v_cvt_pk_bf16_f32 v68, v40, v41
	v_cvt_pk_bf16_f32 v69, v42, v43
	v_cvt_pk_bf16_f32 v70, v44, v45
	v_cvt_pk_bf16_f32 v71, v46, v47
	v_pk_add_f32 v[232:233], v[232:233], v[32:33]
	v_pk_add_f32 v[232:233], v[232:233], v[34:35]
	v_pk_add_f32 v[232:233], v[232:233], v[36:37]
	v_pk_add_f32 v[232:233], v[232:233], v[38:39]
	v_pk_add_f32 v[232:233], v[232:233], v[40:41]
	v_pk_add_f32 v[232:233], v[232:233], v[42:43]
	v_pk_add_f32 v[232:233], v[232:233], v[44:45]
	v_pk_add_f32 v[232:233], v[232:233], v[46:47]
	s_waitcnt lgkmcnt(0)
	v_mfma_f32_32x32x16_bf16 v[0:15], v[64:67], v[72:75], v[0:15]
	v_mfma_f32_32x32x16_bf16 v[16:31], v[64:67], v[76:79], v[16:31]
	v_mfma_f32_32x32x16_bf16 v[0:15], v[68:71], v[220:223], v[0:15]
	v_mfma_f32_32x32x16_bf16 v[16:31], v[68:71], v[224:227], v[16:31]
	global_load_dwordx4 v[116:119], v80, s[84:85]
	global_load_dwordx4 v[120:123], v80, s[84:85] offset:32
	global_load_dwordx4 v[124:127], v80, s[84:85] offset:64
	global_load_dwordx4 v[128:131], v80, s[84:85] offset:96
	global_load_dwordx4 v[132:135], v100, s[84:85] offset:768
	global_load_dwordx4 v[136:139], v149, s[84:85] offset:768
	global_load_dwordx4 v[140:143], v100, s[84:85] offset:832
	global_load_dwordx4 v[144:147], v149, s[84:85] offset:832
	s_add_u32 s84, s84, 0x30000
	s_addc_u32 s85, s85, 0
	s_waitcnt vmcnt(16)
	ds_write_b128 v112, v[172:175]
	ds_write_b128 v112, v[176:179] offset:1024
	ds_write_b128 v112, v[180:183] offset:2048
	ds_write_b128 v112, v[184:187] offset:3072
	v_add_u32_e32 v115, 952, v115
	ds_read2_b32 v[32:33], v115 offset0:0 offset1:1
	ds_read2_b32 v[34:35], v115 offset0:2 offset1:3
	ds_read2_b32 v[36:37], v115 offset0:8 offset1:9
	ds_read2_b32 v[38:39], v115 offset0:10 offset1:11
	ds_read2_b32 v[40:41], v115 offset0:17 offset1:18
	ds_read2_b32 v[42:43], v115 offset0:19 offset1:20
	ds_read2_b32 v[44:45], v115 offset0:25 offset1:26
	ds_read2_b32 v[46:47], v115 offset0:27 offset1:28
	s_waitcnt lgkmcnt(0)
	v_mfma_f32_32x32x16_bf16 v[32:47], v[156:159], v[48:51], v[32:47]
	ds_read_b64_tr_b16 v[72:73], v231
	ds_read_b64_tr_b16 v[74:75], v231 offset:512
	ds_read_b64_tr_b16 v[76:77], v231 offset:2048
	ds_read_b64_tr_b16 v[78:79], v231 offset:2560
	ds_read_b64_tr_b16 v[220:221], v231 offset:1024
	ds_read_b64_tr_b16 v[222:223], v231 offset:1536
	ds_read_b64_tr_b16 v[224:225], v231 offset:3072
	ds_read_b64_tr_b16 v[226:227], v231 offset:3584
	v_mfma_f32_32x32x16_bf16 v[32:47], v[160:163], v[52:55], v[32:47]
	v_mfma_f32_32x32x16_bf16 v[32:47], v[164:167], v[56:59], v[32:47]
	v_mfma_f32_32x32x16_bf16 v[32:47], v[168:171], v[60:63], v[32:47]
	s_nop 11
	v_exp_f32_e32 v32, v32
	v_exp_f32_e32 v33, v33
	v_exp_f32_e32 v34, v34
	v_exp_f32_e32 v35, v35
	v_exp_f32_e32 v36, v36
	v_exp_f32_e32 v37, v37
	v_exp_f32_e32 v38, v38
	v_exp_f32_e32 v39, v39
	v_exp_f32_e32 v40, v40
	v_exp_f32_e32 v41, v41
	v_exp_f32_e32 v42, v42
	v_exp_f32_e32 v43, v43
	v_exp_f32_e32 v44, v44
	v_exp_f32_e32 v45, v45
	v_exp_f32_e32 v46, v46
	v_exp_f32_e32 v47, v47
	v_cvt_pk_bf16_f32 v64, v32, v33
	v_cvt_pk_bf16_f32 v65, v34, v35
	v_cvt_pk_bf16_f32 v66, v36, v37
	v_cvt_pk_bf16_f32 v67, v38, v39
	v_cvt_pk_bf16_f32 v68, v40, v41
	v_cvt_pk_bf16_f32 v69, v42, v43
	v_cvt_pk_bf16_f32 v70, v44, v45
	v_cvt_pk_bf16_f32 v71, v46, v47
	v_pk_add_f32 v[232:233], v[232:233], v[32:33]
	v_pk_add_f32 v[232:233], v[232:233], v[34:35]
	v_pk_add_f32 v[232:233], v[232:233], v[36:37]
	v_pk_add_f32 v[232:233], v[232:233], v[38:39]
	v_pk_add_f32 v[232:233], v[232:233], v[40:41]
	v_pk_add_f32 v[232:233], v[232:233], v[42:43]
	v_pk_add_f32 v[232:233], v[232:233], v[44:45]
	v_pk_add_f32 v[232:233], v[232:233], v[46:47]
	s_waitcnt lgkmcnt(0)
	v_mfma_f32_32x32x16_bf16 v[0:15], v[64:67], v[72:75], v[0:15]
	v_mfma_f32_32x32x16_bf16 v[16:31], v[64:67], v[76:79], v[16:31]
	v_mfma_f32_32x32x16_bf16 v[0:15], v[68:71], v[220:223], v[0:15]
	v_mfma_f32_32x32x16_bf16 v[16:31], v[68:71], v[224:227], v[16:31]
	global_load_dwordx4 v[156:159], v80, s[84:85]
	global_load_dwordx4 v[160:163], v80, s[84:85] offset:32
	global_load_dwordx4 v[164:167], v80, s[84:85] offset:64
	global_load_dwordx4 v[168:171], v80, s[84:85] offset:96
	global_load_dwordx4 v[172:175], v100, s[84:85] offset:768
	global_load_dwordx4 v[176:179], v149, s[84:85] offset:768
	global_load_dwordx4 v[180:183], v100, s[84:85] offset:832
	global_load_dwordx4 v[184:187], v149, s[84:85] offset:832
	s_add_u32 s84, s84, 0x30000
	s_addc_u32 s85, s85, 0
	s_waitcnt vmcnt(16)
	ds_write_b128 v112, v[204:207]
	ds_write_b128 v112, v[208:211] offset:1024
	ds_write_b128 v112, v[212:215] offset:2048
	ds_write_b128 v112, v[216:219] offset:3072
	ds_read2_b32 v[32:33], v115 offset0:34 offset1:35
	ds_read2_b32 v[34:35], v115 offset0:36 offset1:37
	ds_read2_b32 v[36:37], v115 offset0:42 offset1:43
	ds_read2_b32 v[38:39], v115 offset0:44 offset1:45
	ds_read2_b32 v[40:41], v115 offset0:51 offset1:52
	ds_read2_b32 v[42:43], v115 offset0:53 offset1:54
	ds_read2_b32 v[44:45], v115 offset0:59 offset1:60
	ds_read2_b32 v[46:47], v115 offset0:61 offset1:62
	s_waitcnt lgkmcnt(0)
	v_mfma_f32_32x32x16_bf16 v[32:47], v[188:191], v[48:51], v[32:47]
	ds_read_b64_tr_b16 v[72:73], v231
	ds_read_b64_tr_b16 v[74:75], v231 offset:512
	ds_read_b64_tr_b16 v[76:77], v231 offset:2048
	ds_read_b64_tr_b16 v[78:79], v231 offset:2560
	ds_read_b64_tr_b16 v[220:221], v231 offset:1024
	ds_read_b64_tr_b16 v[222:223], v231 offset:1536
	ds_read_b64_tr_b16 v[224:225], v231 offset:3072
	ds_read_b64_tr_b16 v[226:227], v231 offset:3584
	v_mfma_f32_32x32x16_bf16 v[32:47], v[192:195], v[52:55], v[32:47]
	v_mfma_f32_32x32x16_bf16 v[32:47], v[196:199], v[56:59], v[32:47]
	v_mfma_f32_32x32x16_bf16 v[32:47], v[200:203], v[60:63], v[32:47]
	s_nop 11
	v_exp_f32_e32 v32, v32
	v_exp_f32_e32 v33, v33
	v_exp_f32_e32 v34, v34
	v_exp_f32_e32 v35, v35
	v_exp_f32_e32 v36, v36
	v_exp_f32_e32 v37, v37
	v_exp_f32_e32 v38, v38
	v_exp_f32_e32 v39, v39
	v_exp_f32_e32 v40, v40
	v_exp_f32_e32 v41, v41
	v_exp_f32_e32 v42, v42
	v_exp_f32_e32 v43, v43
	v_exp_f32_e32 v44, v44
	v_exp_f32_e32 v45, v45
	v_exp_f32_e32 v46, v46
	v_exp_f32_e32 v47, v47
	v_cvt_pk_bf16_f32 v64, v32, v33
	v_cvt_pk_bf16_f32 v65, v34, v35
	v_cvt_pk_bf16_f32 v66, v36, v37
	v_cvt_pk_bf16_f32 v67, v38, v39
	v_cvt_pk_bf16_f32 v68, v40, v41
	v_cvt_pk_bf16_f32 v69, v42, v43
	v_cvt_pk_bf16_f32 v70, v44, v45
	v_cvt_pk_bf16_f32 v71, v46, v47
	v_pk_add_f32 v[232:233], v[232:233], v[32:33]
	v_pk_add_f32 v[232:233], v[232:233], v[34:35]
	v_pk_add_f32 v[232:233], v[232:233], v[36:37]
	v_pk_add_f32 v[232:233], v[232:233], v[38:39]
	v_pk_add_f32 v[232:233], v[232:233], v[40:41]
	v_pk_add_f32 v[232:233], v[232:233], v[42:43]
	v_pk_add_f32 v[232:233], v[232:233], v[44:45]
	v_pk_add_f32 v[232:233], v[232:233], v[46:47]
	s_waitcnt lgkmcnt(0)
	v_mfma_f32_32x32x16_bf16 v[0:15], v[64:67], v[72:75], v[0:15]
	v_mfma_f32_32x32x16_bf16 v[16:31], v[64:67], v[76:79], v[16:31]
	v_mfma_f32_32x32x16_bf16 v[0:15], v[68:71], v[220:223], v[0:15]
	v_mfma_f32_32x32x16_bf16 v[16:31], v[68:71], v[224:227], v[16:31]
	global_load_dwordx4 v[188:191], v80, s[84:85]
	global_load_dwordx4 v[192:195], v80, s[84:85] offset:32
	global_load_dwordx4 v[196:199], v80, s[84:85] offset:64
	global_load_dwordx4 v[200:203], v80, s[84:85] offset:96
	global_load_dwordx4 v[204:207], v100, s[84:85] offset:768
	global_load_dwordx4 v[208:211], v149, s[84:85] offset:768
	global_load_dwordx4 v[212:215], v100, s[84:85] offset:832
	global_load_dwordx4 v[216:219], v149, s[84:85] offset:832
	s_add_u32 s84, s84, 0x30000
	s_addc_u32 s85, s85, 0
	s_waitcnt vmcnt(16)
	ds_write_b128 v112, v[132:135]
	ds_write_b128 v112, v[136:139] offset:1024
	ds_write_b128 v112, v[140:143] offset:2048
	ds_write_b128 v112, v[144:147] offset:3072
	ds_read2_b32 v[32:33], v115 offset0:68 offset1:69
	ds_read2_b32 v[34:35], v115 offset0:70 offset1:71
	ds_read2_b32 v[36:37], v115 offset0:76 offset1:77
	ds_read2_b32 v[38:39], v115 offset0:78 offset1:79
	ds_read2_b32 v[40:41], v115 offset0:85 offset1:86
	ds_read2_b32 v[42:43], v115 offset0:87 offset1:88
	ds_read2_b32 v[44:45], v115 offset0:93 offset1:94
	ds_read2_b32 v[46:47], v115 offset0:95 offset1:96
	s_waitcnt lgkmcnt(0)
	v_mfma_f32_32x32x16_bf16 v[32:47], v[116:119], v[48:51], v[32:47]
	ds_read_b64_tr_b16 v[72:73], v231
	ds_read_b64_tr_b16 v[74:75], v231 offset:512
	ds_read_b64_tr_b16 v[76:77], v231 offset:2048
	ds_read_b64_tr_b16 v[78:79], v231 offset:2560
	ds_read_b64_tr_b16 v[220:221], v231 offset:1024
	ds_read_b64_tr_b16 v[222:223], v231 offset:1536
	ds_read_b64_tr_b16 v[224:225], v231 offset:3072
	ds_read_b64_tr_b16 v[226:227], v231 offset:3584
	v_mfma_f32_32x32x16_bf16 v[32:47], v[120:123], v[52:55], v[32:47]
	v_mfma_f32_32x32x16_bf16 v[32:47], v[124:127], v[56:59], v[32:47]
	v_mfma_f32_32x32x16_bf16 v[32:47], v[128:131], v[60:63], v[32:47]
	s_nop 11
	v_exp_f32_e32 v32, v32
	v_exp_f32_e32 v33, v33
	v_exp_f32_e32 v34, v34
	v_exp_f32_e32 v35, v35
	v_exp_f32_e32 v36, v36
	v_exp_f32_e32 v37, v37
	v_exp_f32_e32 v38, v38
	v_exp_f32_e32 v39, v39
	v_exp_f32_e32 v40, v40
	v_exp_f32_e32 v41, v41
	v_exp_f32_e32 v42, v42
	v_exp_f32_e32 v43, v43
	v_exp_f32_e32 v44, v44
	v_exp_f32_e32 v45, v45
	v_exp_f32_e32 v46, v46
	v_exp_f32_e32 v47, v47
	v_cvt_pk_bf16_f32 v64, v32, v33
	v_cvt_pk_bf16_f32 v65, v34, v35
	v_cvt_pk_bf16_f32 v66, v36, v37
	v_cvt_pk_bf16_f32 v67, v38, v39
	v_cvt_pk_bf16_f32 v68, v40, v41
	v_cvt_pk_bf16_f32 v69, v42, v43
	v_cvt_pk_bf16_f32 v70, v44, v45
	v_cvt_pk_bf16_f32 v71, v46, v47
	v_pk_add_f32 v[232:233], v[232:233], v[32:33]
	v_pk_add_f32 v[232:233], v[232:233], v[34:35]
	v_pk_add_f32 v[232:233], v[232:233], v[36:37]
	v_pk_add_f32 v[232:233], v[232:233], v[38:39]
	v_pk_add_f32 v[232:233], v[232:233], v[40:41]
	v_pk_add_f32 v[232:233], v[232:233], v[42:43]
	v_pk_add_f32 v[232:233], v[232:233], v[44:45]
	v_pk_add_f32 v[232:233], v[232:233], v[46:47]
	s_waitcnt lgkmcnt(0)
	v_mfma_f32_32x32x16_bf16 v[0:15], v[64:67], v[72:75], v[0:15]
	v_mfma_f32_32x32x16_bf16 v[16:31], v[64:67], v[76:79], v[16:31]
	v_mfma_f32_32x32x16_bf16 v[0:15], v[68:71], v[220:223], v[0:15]
	v_mfma_f32_32x32x16_bf16 v[16:31], v[68:71], v[224:227], v[16:31]
	global_load_dwordx4 v[116:119], v80, s[84:85]
	global_load_dwordx4 v[120:123], v80, s[84:85] offset:32
	global_load_dwordx4 v[124:127], v80, s[84:85] offset:64
	global_load_dwordx4 v[128:131], v80, s[84:85] offset:96
	global_load_dwordx4 v[132:135], v100, s[84:85] offset:768
	global_load_dwordx4 v[136:139], v149, s[84:85] offset:768
	global_load_dwordx4 v[140:143], v100, s[84:85] offset:832
	global_load_dwordx4 v[144:147], v149, s[84:85] offset:832
	s_add_u32 s84, s84, 0x30000
	s_addc_u32 s85, s85, 0
	s_waitcnt vmcnt(16)
	ds_write_b128 v112, v[172:175]
	ds_write_b128 v112, v[176:179] offset:1024
	ds_write_b128 v112, v[180:183] offset:2048
	ds_write_b128 v112, v[184:187] offset:3072
	ds_read2_b32 v[32:33], v115 offset0:102 offset1:103
	ds_read2_b32 v[34:35], v115 offset0:104 offset1:105
	ds_read2_b32 v[36:37], v115 offset0:110 offset1:111
	ds_read2_b32 v[38:39], v115 offset0:112 offset1:113
	ds_read2_b32 v[40:41], v115 offset0:119 offset1:120
	ds_read2_b32 v[42:43], v115 offset0:121 offset1:122
	ds_read2_b32 v[44:45], v115 offset0:127 offset1:128
	ds_read2_b32 v[46:47], v115 offset0:129 offset1:130
	s_waitcnt lgkmcnt(0)
	v_mfma_f32_32x32x16_bf16 v[32:47], v[156:159], v[48:51], v[32:47]
	ds_read_b64_tr_b16 v[72:73], v231
	ds_read_b64_tr_b16 v[74:75], v231 offset:512
	ds_read_b64_tr_b16 v[76:77], v231 offset:2048
	ds_read_b64_tr_b16 v[78:79], v231 offset:2560
	ds_read_b64_tr_b16 v[220:221], v231 offset:1024
	ds_read_b64_tr_b16 v[222:223], v231 offset:1536
	ds_read_b64_tr_b16 v[224:225], v231 offset:3072
	ds_read_b64_tr_b16 v[226:227], v231 offset:3584
	v_mfma_f32_32x32x16_bf16 v[32:47], v[160:163], v[52:55], v[32:47]
	v_mfma_f32_32x32x16_bf16 v[32:47], v[164:167], v[56:59], v[32:47]
	v_mfma_f32_32x32x16_bf16 v[32:47], v[168:171], v[60:63], v[32:47]
	s_nop 11
	v_exp_f32_e32 v32, v32
	v_exp_f32_e32 v33, v33
	v_exp_f32_e32 v34, v34
	v_exp_f32_e32 v35, v35
	v_exp_f32_e32 v36, v36
	v_exp_f32_e32 v37, v37
	v_exp_f32_e32 v38, v38
	v_exp_f32_e32 v39, v39
	v_exp_f32_e32 v40, v40
	v_exp_f32_e32 v41, v41
	v_exp_f32_e32 v42, v42
	v_exp_f32_e32 v43, v43
	v_exp_f32_e32 v44, v44
	v_exp_f32_e32 v45, v45
	v_exp_f32_e32 v46, v46
	v_exp_f32_e32 v47, v47
	v_cvt_pk_bf16_f32 v64, v32, v33
	v_cvt_pk_bf16_f32 v65, v34, v35
	v_cvt_pk_bf16_f32 v66, v36, v37
	v_cvt_pk_bf16_f32 v67, v38, v39
	v_cvt_pk_bf16_f32 v68, v40, v41
	v_cvt_pk_bf16_f32 v69, v42, v43
	v_cvt_pk_bf16_f32 v70, v44, v45
	v_cvt_pk_bf16_f32 v71, v46, v47
	v_pk_add_f32 v[232:233], v[232:233], v[32:33]
	v_pk_add_f32 v[232:233], v[232:233], v[34:35]
	v_pk_add_f32 v[232:233], v[232:233], v[36:37]
	v_pk_add_f32 v[232:233], v[232:233], v[38:39]
	v_pk_add_f32 v[232:233], v[232:233], v[40:41]
	v_pk_add_f32 v[232:233], v[232:233], v[42:43]
	v_pk_add_f32 v[232:233], v[232:233], v[44:45]
	v_pk_add_f32 v[232:233], v[232:233], v[46:47]
	s_waitcnt lgkmcnt(0)
	v_mfma_f32_32x32x16_bf16 v[0:15], v[64:67], v[72:75], v[0:15]
	v_mfma_f32_32x32x16_bf16 v[16:31], v[64:67], v[76:79], v[16:31]
	v_mfma_f32_32x32x16_bf16 v[0:15], v[68:71], v[220:223], v[0:15]
	v_mfma_f32_32x32x16_bf16 v[16:31], v[68:71], v[224:227], v[16:31]
	global_load_dwordx4 v[156:159], v80, s[84:85]
	global_load_dwordx4 v[160:163], v80, s[84:85] offset:32
	global_load_dwordx4 v[164:167], v80, s[84:85] offset:64
	global_load_dwordx4 v[168:171], v80, s[84:85] offset:96
	global_load_dwordx4 v[172:175], v100, s[84:85] offset:768
	global_load_dwordx4 v[176:179], v149, s[84:85] offset:768
	global_load_dwordx4 v[180:183], v100, s[84:85] offset:832
	global_load_dwordx4 v[184:187], v149, s[84:85] offset:832
	s_add_u32 s84, s84, 0x30000
	s_addc_u32 s85, s85, 0
	s_waitcnt vmcnt(16)
	ds_write_b128 v112, v[204:207]
	ds_write_b128 v112, v[208:211] offset:1024
	ds_write_b128 v112, v[212:215] offset:2048
	ds_write_b128 v112, v[216:219] offset:3072
	ds_read2_b32 v[32:33], v115 offset0:136 offset1:137
	ds_read2_b32 v[34:35], v115 offset0:138 offset1:139
	ds_read2_b32 v[36:37], v115 offset0:144 offset1:145
	ds_read2_b32 v[38:39], v115 offset0:146 offset1:147
	ds_read2_b32 v[40:41], v115 offset0:153 offset1:154
	ds_read2_b32 v[42:43], v115 offset0:155 offset1:156
	ds_read2_b32 v[44:45], v115 offset0:161 offset1:162
	ds_read2_b32 v[46:47], v115 offset0:163 offset1:164
	s_waitcnt lgkmcnt(0)
	v_mfma_f32_32x32x16_bf16 v[32:47], v[188:191], v[48:51], v[32:47]
	ds_read_b64_tr_b16 v[72:73], v231
	ds_read_b64_tr_b16 v[74:75], v231 offset:512
	ds_read_b64_tr_b16 v[76:77], v231 offset:2048
	ds_read_b64_tr_b16 v[78:79], v231 offset:2560
	ds_read_b64_tr_b16 v[220:221], v231 offset:1024
	ds_read_b64_tr_b16 v[222:223], v231 offset:1536
	ds_read_b64_tr_b16 v[224:225], v231 offset:3072
	ds_read_b64_tr_b16 v[226:227], v231 offset:3584
	v_mfma_f32_32x32x16_bf16 v[32:47], v[192:195], v[52:55], v[32:47]
	v_mfma_f32_32x32x16_bf16 v[32:47], v[196:199], v[56:59], v[32:47]
	v_mfma_f32_32x32x16_bf16 v[32:47], v[200:203], v[60:63], v[32:47]
	s_nop 11
	v_exp_f32_e32 v32, v32
	v_exp_f32_e32 v33, v33
	v_exp_f32_e32 v34, v34
	v_exp_f32_e32 v35, v35
	v_exp_f32_e32 v36, v36
	v_exp_f32_e32 v37, v37
	v_exp_f32_e32 v38, v38
	v_exp_f32_e32 v39, v39
	v_exp_f32_e32 v40, v40
	v_exp_f32_e32 v41, v41
	v_exp_f32_e32 v42, v42
	v_exp_f32_e32 v43, v43
	v_exp_f32_e32 v44, v44
	v_exp_f32_e32 v45, v45
	v_exp_f32_e32 v46, v46
	v_exp_f32_e32 v47, v47
	v_cvt_pk_bf16_f32 v64, v32, v33
	v_cvt_pk_bf16_f32 v65, v34, v35
	v_cvt_pk_bf16_f32 v66, v36, v37
	v_cvt_pk_bf16_f32 v67, v38, v39
	v_cvt_pk_bf16_f32 v68, v40, v41
	v_cvt_pk_bf16_f32 v69, v42, v43
	v_cvt_pk_bf16_f32 v70, v44, v45
	v_cvt_pk_bf16_f32 v71, v46, v47
	v_pk_add_f32 v[232:233], v[232:233], v[32:33]
	v_pk_add_f32 v[232:233], v[232:233], v[34:35]
	v_pk_add_f32 v[232:233], v[232:233], v[36:37]
	v_pk_add_f32 v[232:233], v[232:233], v[38:39]
	v_pk_add_f32 v[232:233], v[232:233], v[40:41]
	v_pk_add_f32 v[232:233], v[232:233], v[42:43]
	v_pk_add_f32 v[232:233], v[232:233], v[44:45]
	v_pk_add_f32 v[232:233], v[232:233], v[46:47]
	s_waitcnt lgkmcnt(0)
	v_mfma_f32_32x32x16_bf16 v[0:15], v[64:67], v[72:75], v[0:15]
	v_mfma_f32_32x32x16_bf16 v[16:31], v[64:67], v[76:79], v[16:31]
	v_mfma_f32_32x32x16_bf16 v[0:15], v[68:71], v[220:223], v[0:15]
	v_mfma_f32_32x32x16_bf16 v[16:31], v[68:71], v[224:227], v[16:31]
	global_load_dwordx4 v[188:191], v80, s[84:85]
	global_load_dwordx4 v[192:195], v80, s[84:85] offset:32
	global_load_dwordx4 v[196:199], v80, s[84:85] offset:64
	global_load_dwordx4 v[200:203], v80, s[84:85] offset:96
	global_load_dwordx4 v[204:207], v100, s[84:85] offset:768
	global_load_dwordx4 v[208:211], v149, s[84:85] offset:768
	global_load_dwordx4 v[212:215], v100, s[84:85] offset:832
	global_load_dwordx4 v[216:219], v149, s[84:85] offset:832
	s_add_u32 s84, s84, 0x30000
	s_addc_u32 s85, s85, 0
	s_waitcnt vmcnt(16)
	ds_write_b128 v112, v[132:135]
	ds_write_b128 v112, v[136:139] offset:1024
	ds_write_b128 v112, v[140:143] offset:2048
	ds_write_b128 v112, v[144:147] offset:3072
	ds_read2_b32 v[32:33], v115 offset0:170 offset1:171
	ds_read2_b32 v[34:35], v115 offset0:172 offset1:173
	ds_read2_b32 v[36:37], v115 offset0:178 offset1:179
	ds_read2_b32 v[38:39], v115 offset0:180 offset1:181
	ds_read2_b32 v[40:41], v115 offset0:187 offset1:188
	ds_read2_b32 v[42:43], v115 offset0:189 offset1:190
	ds_read2_b32 v[44:45], v115 offset0:195 offset1:196
	ds_read2_b32 v[46:47], v115 offset0:197 offset1:198
	s_waitcnt lgkmcnt(0)
	v_mfma_f32_32x32x16_bf16 v[32:47], v[116:119], v[48:51], v[32:47]
	ds_read_b64_tr_b16 v[72:73], v231
	ds_read_b64_tr_b16 v[74:75], v231 offset:512
	ds_read_b64_tr_b16 v[76:77], v231 offset:2048
	ds_read_b64_tr_b16 v[78:79], v231 offset:2560
	ds_read_b64_tr_b16 v[220:221], v231 offset:1024
	ds_read_b64_tr_b16 v[222:223], v231 offset:1536
	ds_read_b64_tr_b16 v[224:225], v231 offset:3072
	ds_read_b64_tr_b16 v[226:227], v231 offset:3584
	v_mfma_f32_32x32x16_bf16 v[32:47], v[120:123], v[52:55], v[32:47]
	v_mfma_f32_32x32x16_bf16 v[32:47], v[124:127], v[56:59], v[32:47]
	v_mfma_f32_32x32x16_bf16 v[32:47], v[128:131], v[60:63], v[32:47]
	s_nop 11
	v_exp_f32_e32 v32, v32
	v_exp_f32_e32 v33, v33
	v_exp_f32_e32 v34, v34
	v_exp_f32_e32 v35, v35
	v_exp_f32_e32 v36, v36
	v_exp_f32_e32 v37, v37
	v_exp_f32_e32 v38, v38
	v_exp_f32_e32 v39, v39
	v_exp_f32_e32 v40, v40
	v_exp_f32_e32 v41, v41
	v_exp_f32_e32 v42, v42
	v_exp_f32_e32 v43, v43
	v_exp_f32_e32 v44, v44
	v_exp_f32_e32 v45, v45
	v_exp_f32_e32 v46, v46
	v_exp_f32_e32 v47, v47
	v_cvt_pk_bf16_f32 v64, v32, v33
	v_cvt_pk_bf16_f32 v65, v34, v35
	v_cvt_pk_bf16_f32 v66, v36, v37
	v_cvt_pk_bf16_f32 v67, v38, v39
	v_cvt_pk_bf16_f32 v68, v40, v41
	v_cvt_pk_bf16_f32 v69, v42, v43
	v_cvt_pk_bf16_f32 v70, v44, v45
	v_cvt_pk_bf16_f32 v71, v46, v47
	v_pk_add_f32 v[232:233], v[232:233], v[32:33]
	v_pk_add_f32 v[232:233], v[232:233], v[34:35]
	v_pk_add_f32 v[232:233], v[232:233], v[36:37]
	v_pk_add_f32 v[232:233], v[232:233], v[38:39]
	v_pk_add_f32 v[232:233], v[232:233], v[40:41]
	v_pk_add_f32 v[232:233], v[232:233], v[42:43]
	v_pk_add_f32 v[232:233], v[232:233], v[44:45]
	v_pk_add_f32 v[232:233], v[232:233], v[46:47]
	s_waitcnt lgkmcnt(0)
	v_mfma_f32_32x32x16_bf16 v[0:15], v[64:67], v[72:75], v[0:15]
	v_mfma_f32_32x32x16_bf16 v[16:31], v[64:67], v[76:79], v[16:31]
	v_mfma_f32_32x32x16_bf16 v[0:15], v[68:71], v[220:223], v[0:15]
	v_mfma_f32_32x32x16_bf16 v[16:31], v[68:71], v[224:227], v[16:31]
	global_load_dwordx4 v[116:119], v80, s[84:85]
	global_load_dwordx4 v[120:123], v80, s[84:85] offset:32
	global_load_dwordx4 v[124:127], v80, s[84:85] offset:64
	global_load_dwordx4 v[128:131], v80, s[84:85] offset:96
	global_load_dwordx4 v[132:135], v100, s[84:85] offset:768
	global_load_dwordx4 v[136:139], v149, s[84:85] offset:768
	global_load_dwordx4 v[140:143], v100, s[84:85] offset:832
	global_load_dwordx4 v[144:147], v149, s[84:85] offset:832
	s_add_u32 s84, s84, 0x30000
	s_addc_u32 s85, s85, 0
	s_waitcnt vmcnt(16)
	ds_write_b128 v112, v[172:175]
	ds_write_b128 v112, v[176:179] offset:1024
	ds_write_b128 v112, v[180:183] offset:2048
	ds_write_b128 v112, v[184:187] offset:3072
	ds_read2_b32 v[32:33], v115 offset0:204 offset1:205
	ds_read2_b32 v[34:35], v115 offset0:206 offset1:207
	ds_read2_b32 v[36:37], v115 offset0:212 offset1:213
	ds_read2_b32 v[38:39], v115 offset0:214 offset1:215
	ds_read2_b32 v[40:41], v115 offset0:221 offset1:222
	ds_read2_b32 v[42:43], v115 offset0:223 offset1:224
	ds_read2_b32 v[44:45], v115 offset0:229 offset1:230
	ds_read2_b32 v[46:47], v115 offset0:231 offset1:232
	s_waitcnt lgkmcnt(0)
	v_mfma_f32_32x32x16_bf16 v[32:47], v[156:159], v[48:51], v[32:47]
	ds_read_b64_tr_b16 v[72:73], v231
	ds_read_b64_tr_b16 v[74:75], v231 offset:512
	ds_read_b64_tr_b16 v[76:77], v231 offset:2048
	ds_read_b64_tr_b16 v[78:79], v231 offset:2560
	ds_read_b64_tr_b16 v[220:221], v231 offset:1024
	ds_read_b64_tr_b16 v[222:223], v231 offset:1536
	ds_read_b64_tr_b16 v[224:225], v231 offset:3072
	ds_read_b64_tr_b16 v[226:227], v231 offset:3584
	v_mfma_f32_32x32x16_bf16 v[32:47], v[160:163], v[52:55], v[32:47]
	v_mfma_f32_32x32x16_bf16 v[32:47], v[164:167], v[56:59], v[32:47]
	v_mfma_f32_32x32x16_bf16 v[32:47], v[168:171], v[60:63], v[32:47]
	s_nop 11
	v_exp_f32_e32 v32, v32
	v_exp_f32_e32 v33, v33
	v_exp_f32_e32 v34, v34
	v_exp_f32_e32 v35, v35
	v_exp_f32_e32 v36, v36
	v_exp_f32_e32 v37, v37
	v_exp_f32_e32 v38, v38
	v_exp_f32_e32 v39, v39
	v_exp_f32_e32 v40, v40
	v_exp_f32_e32 v41, v41
	v_exp_f32_e32 v42, v42
	v_exp_f32_e32 v43, v43
	v_exp_f32_e32 v44, v44
	v_exp_f32_e32 v45, v45
	v_exp_f32_e32 v46, v46
	v_exp_f32_e32 v47, v47
	v_cvt_pk_bf16_f32 v64, v32, v33
	v_cvt_pk_bf16_f32 v65, v34, v35
	v_cvt_pk_bf16_f32 v66, v36, v37
	v_cvt_pk_bf16_f32 v67, v38, v39
	v_cvt_pk_bf16_f32 v68, v40, v41
	v_cvt_pk_bf16_f32 v69, v42, v43
	v_cvt_pk_bf16_f32 v70, v44, v45
	v_cvt_pk_bf16_f32 v71, v46, v47
	v_pk_add_f32 v[232:233], v[232:233], v[32:33]
	v_pk_add_f32 v[232:233], v[232:233], v[34:35]
	v_pk_add_f32 v[232:233], v[232:233], v[36:37]
	v_pk_add_f32 v[232:233], v[232:233], v[38:39]
	v_pk_add_f32 v[232:233], v[232:233], v[40:41]
	v_pk_add_f32 v[232:233], v[232:233], v[42:43]
	v_pk_add_f32 v[232:233], v[232:233], v[44:45]
	v_pk_add_f32 v[232:233], v[232:233], v[46:47]
	s_waitcnt lgkmcnt(0)
	v_mfma_f32_32x32x16_bf16 v[0:15], v[64:67], v[72:75], v[0:15]
	v_mfma_f32_32x32x16_bf16 v[16:31], v[64:67], v[76:79], v[16:31]
	v_mfma_f32_32x32x16_bf16 v[0:15], v[68:71], v[220:223], v[0:15]
	v_mfma_f32_32x32x16_bf16 v[16:31], v[68:71], v[224:227], v[16:31]
	global_load_dwordx4 v[156:159], v80, s[84:85]
	global_load_dwordx4 v[160:163], v80, s[84:85] offset:32
	global_load_dwordx4 v[164:167], v80, s[84:85] offset:64
	global_load_dwordx4 v[168:171], v80, s[84:85] offset:96
	global_load_dwordx4 v[172:175], v100, s[84:85] offset:768
	global_load_dwordx4 v[176:179], v149, s[84:85] offset:768
	global_load_dwordx4 v[180:183], v100, s[84:85] offset:832
	global_load_dwordx4 v[184:187], v149, s[84:85] offset:832
	s_add_u32 s84, s84, 0x30000
	s_addc_u32 s85, s85, 0
	s_waitcnt vmcnt(16)
	ds_write_b128 v112, v[204:207]
	ds_write_b128 v112, v[208:211] offset:1024
	ds_write_b128 v112, v[212:215] offset:2048
	ds_write_b128 v112, v[216:219] offset:3072
	v_add_u32_e32 v115, 952, v115
	ds_read2_b32 v[32:33], v115 offset0:0 offset1:1
	ds_read2_b32 v[34:35], v115 offset0:2 offset1:3
	ds_read2_b32 v[36:37], v115 offset0:8 offset1:9
	ds_read2_b32 v[38:39], v115 offset0:10 offset1:11
	ds_read2_b32 v[40:41], v115 offset0:17 offset1:18
	ds_read2_b32 v[42:43], v115 offset0:19 offset1:20
	ds_read2_b32 v[44:45], v115 offset0:25 offset1:26
	ds_read2_b32 v[46:47], v115 offset0:27 offset1:28
	s_waitcnt lgkmcnt(0)
	v_mfma_f32_32x32x16_bf16 v[32:47], v[188:191], v[48:51], v[32:47]
	ds_read_b64_tr_b16 v[72:73], v231
	ds_read_b64_tr_b16 v[74:75], v231 offset:512
	ds_read_b64_tr_b16 v[76:77], v231 offset:2048
	ds_read_b64_tr_b16 v[78:79], v231 offset:2560
	ds_read_b64_tr_b16 v[220:221], v231 offset:1024
	ds_read_b64_tr_b16 v[222:223], v231 offset:1536
	ds_read_b64_tr_b16 v[224:225], v231 offset:3072
	ds_read_b64_tr_b16 v[226:227], v231 offset:3584
	v_mfma_f32_32x32x16_bf16 v[32:47], v[192:195], v[52:55], v[32:47]
	v_mfma_f32_32x32x16_bf16 v[32:47], v[196:199], v[56:59], v[32:47]
	v_mfma_f32_32x32x16_bf16 v[32:47], v[200:203], v[60:63], v[32:47]
	s_nop 11
	v_exp_f32_e32 v32, v32
	v_exp_f32_e32 v33, v33
	v_exp_f32_e32 v34, v34
	v_exp_f32_e32 v35, v35
	v_exp_f32_e32 v36, v36
	v_exp_f32_e32 v37, v37
	v_exp_f32_e32 v38, v38
	v_exp_f32_e32 v39, v39
	v_exp_f32_e32 v40, v40
	v_exp_f32_e32 v41, v41
	v_exp_f32_e32 v42, v42
	v_exp_f32_e32 v43, v43
	v_exp_f32_e32 v44, v44
	v_exp_f32_e32 v45, v45
	v_exp_f32_e32 v46, v46
	v_exp_f32_e32 v47, v47
	v_cvt_pk_bf16_f32 v64, v32, v33
	v_cvt_pk_bf16_f32 v65, v34, v35
	v_cvt_pk_bf16_f32 v66, v36, v37
	v_cvt_pk_bf16_f32 v67, v38, v39
	v_cvt_pk_bf16_f32 v68, v40, v41
	v_cvt_pk_bf16_f32 v69, v42, v43
	v_cvt_pk_bf16_f32 v70, v44, v45
	v_cvt_pk_bf16_f32 v71, v46, v47
	v_pk_add_f32 v[232:233], v[232:233], v[32:33]
	v_pk_add_f32 v[232:233], v[232:233], v[34:35]
	v_pk_add_f32 v[232:233], v[232:233], v[36:37]
	v_pk_add_f32 v[232:233], v[232:233], v[38:39]
	v_pk_add_f32 v[232:233], v[232:233], v[40:41]
	v_pk_add_f32 v[232:233], v[232:233], v[42:43]
	v_pk_add_f32 v[232:233], v[232:233], v[44:45]
	v_pk_add_f32 v[232:233], v[232:233], v[46:47]
	s_waitcnt lgkmcnt(0)
	v_mfma_f32_32x32x16_bf16 v[0:15], v[64:67], v[72:75], v[0:15]
	v_mfma_f32_32x32x16_bf16 v[16:31], v[64:67], v[76:79], v[16:31]
	v_mfma_f32_32x32x16_bf16 v[0:15], v[68:71], v[220:223], v[0:15]
	v_mfma_f32_32x32x16_bf16 v[16:31], v[68:71], v[224:227], v[16:31]
	global_load_dwordx4 v[188:191], v80, s[84:85]
	global_load_dwordx4 v[192:195], v80, s[84:85] offset:32
	global_load_dwordx4 v[196:199], v80, s[84:85] offset:64
	global_load_dwordx4 v[200:203], v80, s[84:85] offset:96
	global_load_dwordx4 v[204:207], v100, s[84:85] offset:768
	global_load_dwordx4 v[208:211], v149, s[84:85] offset:768
	global_load_dwordx4 v[212:215], v100, s[84:85] offset:832
	global_load_dwordx4 v[216:219], v149, s[84:85] offset:832
	s_add_u32 s84, s84, 0x30000
	s_addc_u32 s85, s85, 0
	s_waitcnt vmcnt(16)
	ds_write_b128 v112, v[132:135]
	ds_write_b128 v112, v[136:139] offset:1024
	ds_write_b128 v112, v[140:143] offset:2048
	ds_write_b128 v112, v[144:147] offset:3072
	ds_read2_b32 v[32:33], v115 offset0:34 offset1:35
	ds_read2_b32 v[34:35], v115 offset0:36 offset1:37
	ds_read2_b32 v[36:37], v115 offset0:42 offset1:43
	ds_read2_b32 v[38:39], v115 offset0:44 offset1:45
	ds_read2_b32 v[40:41], v115 offset0:51 offset1:52
	ds_read2_b32 v[42:43], v115 offset0:53 offset1:54
	ds_read2_b32 v[44:45], v115 offset0:59 offset1:60
	ds_read2_b32 v[46:47], v115 offset0:61 offset1:62
	s_waitcnt lgkmcnt(0)
	v_mfma_f32_32x32x16_bf16 v[32:47], v[116:119], v[48:51], v[32:47]
	ds_read_b64_tr_b16 v[72:73], v231
	ds_read_b64_tr_b16 v[74:75], v231 offset:512
	ds_read_b64_tr_b16 v[76:77], v231 offset:2048
	ds_read_b64_tr_b16 v[78:79], v231 offset:2560
	ds_read_b64_tr_b16 v[220:221], v231 offset:1024
	ds_read_b64_tr_b16 v[222:223], v231 offset:1536
	ds_read_b64_tr_b16 v[224:225], v231 offset:3072
	ds_read_b64_tr_b16 v[226:227], v231 offset:3584
	v_mfma_f32_32x32x16_bf16 v[32:47], v[120:123], v[52:55], v[32:47]
	v_mfma_f32_32x32x16_bf16 v[32:47], v[124:127], v[56:59], v[32:47]
	v_mfma_f32_32x32x16_bf16 v[32:47], v[128:131], v[60:63], v[32:47]
	s_nop 11
	v_exp_f32_e32 v32, v32
	v_exp_f32_e32 v33, v33
	v_exp_f32_e32 v34, v34
	v_exp_f32_e32 v35, v35
	v_exp_f32_e32 v36, v36
	v_exp_f32_e32 v37, v37
	v_exp_f32_e32 v38, v38
	v_exp_f32_e32 v39, v39
	v_exp_f32_e32 v40, v40
	v_exp_f32_e32 v41, v41
	v_exp_f32_e32 v42, v42
	v_exp_f32_e32 v43, v43
	v_exp_f32_e32 v44, v44
	v_exp_f32_e32 v45, v45
	v_exp_f32_e32 v46, v46
	v_exp_f32_e32 v47, v47
	v_cvt_pk_bf16_f32 v64, v32, v33
	v_cvt_pk_bf16_f32 v65, v34, v35
	v_cvt_pk_bf16_f32 v66, v36, v37
	v_cvt_pk_bf16_f32 v67, v38, v39
	v_cvt_pk_bf16_f32 v68, v40, v41
	v_cvt_pk_bf16_f32 v69, v42, v43
	v_cvt_pk_bf16_f32 v70, v44, v45
	v_cvt_pk_bf16_f32 v71, v46, v47
	v_pk_add_f32 v[232:233], v[232:233], v[32:33]
	v_pk_add_f32 v[232:233], v[232:233], v[34:35]
	v_pk_add_f32 v[232:233], v[232:233], v[36:37]
	v_pk_add_f32 v[232:233], v[232:233], v[38:39]
	v_pk_add_f32 v[232:233], v[232:233], v[40:41]
	v_pk_add_f32 v[232:233], v[232:233], v[42:43]
	v_pk_add_f32 v[232:233], v[232:233], v[44:45]
	v_pk_add_f32 v[232:233], v[232:233], v[46:47]
	s_waitcnt lgkmcnt(0)
	v_mfma_f32_32x32x16_bf16 v[0:15], v[64:67], v[72:75], v[0:15]
	v_mfma_f32_32x32x16_bf16 v[16:31], v[64:67], v[76:79], v[16:31]
	v_mfma_f32_32x32x16_bf16 v[0:15], v[68:71], v[220:223], v[0:15]
	v_mfma_f32_32x32x16_bf16 v[16:31], v[68:71], v[224:227], v[16:31]
	global_load_dwordx4 v[116:119], v80, s[84:85]
	global_load_dwordx4 v[120:123], v80, s[84:85] offset:32
	global_load_dwordx4 v[124:127], v80, s[84:85] offset:64
	global_load_dwordx4 v[128:131], v80, s[84:85] offset:96
	global_load_dwordx4 v[132:135], v100, s[84:85] offset:768
	global_load_dwordx4 v[136:139], v149, s[84:85] offset:768
	global_load_dwordx4 v[140:143], v100, s[84:85] offset:832
	global_load_dwordx4 v[144:147], v149, s[84:85] offset:832
	s_add_u32 s84, s84, 0x30000
	s_addc_u32 s85, s85, 0
	s_waitcnt vmcnt(16)
	ds_write_b128 v112, v[172:175]
	ds_write_b128 v112, v[176:179] offset:1024
	ds_write_b128 v112, v[180:183] offset:2048
	ds_write_b128 v112, v[184:187] offset:3072
	ds_read2_b32 v[32:33], v115 offset0:68 offset1:69
	ds_read2_b32 v[34:35], v115 offset0:70 offset1:71
	ds_read2_b32 v[36:37], v115 offset0:76 offset1:77
	ds_read2_b32 v[38:39], v115 offset0:78 offset1:79
	ds_read2_b32 v[40:41], v115 offset0:85 offset1:86
	ds_read2_b32 v[42:43], v115 offset0:87 offset1:88
	ds_read2_b32 v[44:45], v115 offset0:93 offset1:94
	ds_read2_b32 v[46:47], v115 offset0:95 offset1:96
	s_waitcnt lgkmcnt(0)
	v_mfma_f32_32x32x16_bf16 v[32:47], v[156:159], v[48:51], v[32:47]
	ds_read_b64_tr_b16 v[72:73], v231
	ds_read_b64_tr_b16 v[74:75], v231 offset:512
	ds_read_b64_tr_b16 v[76:77], v231 offset:2048
	ds_read_b64_tr_b16 v[78:79], v231 offset:2560
	ds_read_b64_tr_b16 v[220:221], v231 offset:1024
	ds_read_b64_tr_b16 v[222:223], v231 offset:1536
	ds_read_b64_tr_b16 v[224:225], v231 offset:3072
	ds_read_b64_tr_b16 v[226:227], v231 offset:3584
	v_mfma_f32_32x32x16_bf16 v[32:47], v[160:163], v[52:55], v[32:47]
	v_mfma_f32_32x32x16_bf16 v[32:47], v[164:167], v[56:59], v[32:47]
	v_mfma_f32_32x32x16_bf16 v[32:47], v[168:171], v[60:63], v[32:47]
	s_nop 11
	v_exp_f32_e32 v32, v32
	v_exp_f32_e32 v33, v33
	v_exp_f32_e32 v34, v34
	v_exp_f32_e32 v35, v35
	v_exp_f32_e32 v36, v36
	v_exp_f32_e32 v37, v37
	v_exp_f32_e32 v38, v38
	v_exp_f32_e32 v39, v39
	v_exp_f32_e32 v40, v40
	v_exp_f32_e32 v41, v41
	v_exp_f32_e32 v42, v42
	v_exp_f32_e32 v43, v43
	v_exp_f32_e32 v44, v44
	v_exp_f32_e32 v45, v45
	v_exp_f32_e32 v46, v46
	v_exp_f32_e32 v47, v47
	v_cvt_pk_bf16_f32 v64, v32, v33
	v_cvt_pk_bf16_f32 v65, v34, v35
	v_cvt_pk_bf16_f32 v66, v36, v37
	v_cvt_pk_bf16_f32 v67, v38, v39
	v_cvt_pk_bf16_f32 v68, v40, v41
	v_cvt_pk_bf16_f32 v69, v42, v43
	v_cvt_pk_bf16_f32 v70, v44, v45
	v_cvt_pk_bf16_f32 v71, v46, v47
	v_pk_add_f32 v[232:233], v[232:233], v[32:33]
	v_pk_add_f32 v[232:233], v[232:233], v[34:35]
	v_pk_add_f32 v[232:233], v[232:233], v[36:37]
	v_pk_add_f32 v[232:233], v[232:233], v[38:39]
	v_pk_add_f32 v[232:233], v[232:233], v[40:41]
	v_pk_add_f32 v[232:233], v[232:233], v[42:43]
	v_pk_add_f32 v[232:233], v[232:233], v[44:45]
	v_pk_add_f32 v[232:233], v[232:233], v[46:47]
	s_waitcnt lgkmcnt(0)
	v_mfma_f32_32x32x16_bf16 v[0:15], v[64:67], v[72:75], v[0:15]
	v_mfma_f32_32x32x16_bf16 v[16:31], v[64:67], v[76:79], v[16:31]
	v_mfma_f32_32x32x16_bf16 v[0:15], v[68:71], v[220:223], v[0:15]
	v_mfma_f32_32x32x16_bf16 v[16:31], v[68:71], v[224:227], v[16:31]
	global_load_dwordx4 v[156:159], v80, s[84:85]
	global_load_dwordx4 v[160:163], v80, s[84:85] offset:32
	global_load_dwordx4 v[164:167], v80, s[84:85] offset:64
	global_load_dwordx4 v[168:171], v80, s[84:85] offset:96
	global_load_dwordx4 v[172:175], v100, s[84:85] offset:768
	global_load_dwordx4 v[176:179], v149, s[84:85] offset:768
	global_load_dwordx4 v[180:183], v100, s[84:85] offset:832
	global_load_dwordx4 v[184:187], v149, s[84:85] offset:832
	s_waitcnt vmcnt(16)
	ds_write_b128 v112, v[204:207]
	ds_write_b128 v112, v[208:211] offset:1024
	ds_write_b128 v112, v[212:215] offset:2048
	ds_write_b128 v112, v[216:219] offset:3072
	ds_read2_b32 v[32:33], v115 offset0:102 offset1:103
	ds_read2_b32 v[34:35], v115 offset0:104 offset1:105
	ds_read2_b32 v[36:37], v115 offset0:110 offset1:111
	ds_read2_b32 v[38:39], v115 offset0:112 offset1:113
	ds_read2_b32 v[40:41], v115 offset0:119 offset1:120
	ds_read2_b32 v[42:43], v115 offset0:121 offset1:122
	ds_read2_b32 v[44:45], v115 offset0:127 offset1:128
	ds_read2_b32 v[46:47], v115 offset0:129 offset1:130
	s_waitcnt lgkmcnt(0)
	v_mfma_f32_32x32x16_bf16 v[32:47], v[188:191], v[48:51], v[32:47]
	ds_read_b64_tr_b16 v[72:73], v231
	ds_read_b64_tr_b16 v[74:75], v231 offset:512
	ds_read_b64_tr_b16 v[76:77], v231 offset:2048
	ds_read_b64_tr_b16 v[78:79], v231 offset:2560
	ds_read_b64_tr_b16 v[220:221], v231 offset:1024
	ds_read_b64_tr_b16 v[222:223], v231 offset:1536
	ds_read_b64_tr_b16 v[224:225], v231 offset:3072
	ds_read_b64_tr_b16 v[226:227], v231 offset:3584
	v_mfma_f32_32x32x16_bf16 v[32:47], v[192:195], v[52:55], v[32:47]
	v_mfma_f32_32x32x16_bf16 v[32:47], v[196:199], v[56:59], v[32:47]
	v_mfma_f32_32x32x16_bf16 v[32:47], v[200:203], v[60:63], v[32:47]
	s_nop 11
	v_exp_f32_e32 v32, v32
	v_exp_f32_e32 v33, v33
	v_exp_f32_e32 v34, v34
	v_exp_f32_e32 v35, v35
	v_exp_f32_e32 v36, v36
	v_exp_f32_e32 v37, v37
	v_exp_f32_e32 v38, v38
	v_exp_f32_e32 v39, v39
	v_exp_f32_e32 v40, v40
	v_exp_f32_e32 v41, v41
	v_exp_f32_e32 v42, v42
	v_exp_f32_e32 v43, v43
	v_exp_f32_e32 v44, v44
	v_exp_f32_e32 v45, v45
	v_exp_f32_e32 v46, v46
	v_exp_f32_e32 v47, v47
	v_cvt_pk_bf16_f32 v64, v32, v33
	v_cvt_pk_bf16_f32 v65, v34, v35
	v_cvt_pk_bf16_f32 v66, v36, v37
	v_cvt_pk_bf16_f32 v67, v38, v39
	v_cvt_pk_bf16_f32 v68, v40, v41
	v_cvt_pk_bf16_f32 v69, v42, v43
	v_cvt_pk_bf16_f32 v70, v44, v45
	v_cvt_pk_bf16_f32 v71, v46, v47
	v_pk_add_f32 v[232:233], v[232:233], v[32:33]
	v_pk_add_f32 v[232:233], v[232:233], v[34:35]
	v_pk_add_f32 v[232:233], v[232:233], v[36:37]
	v_pk_add_f32 v[232:233], v[232:233], v[38:39]
	v_pk_add_f32 v[232:233], v[232:233], v[40:41]
	v_pk_add_f32 v[232:233], v[232:233], v[42:43]
	v_pk_add_f32 v[232:233], v[232:233], v[44:45]
	v_pk_add_f32 v[232:233], v[232:233], v[46:47]
	s_waitcnt lgkmcnt(0)
	v_mfma_f32_32x32x16_bf16 v[0:15], v[64:67], v[72:75], v[0:15]
	v_mfma_f32_32x32x16_bf16 v[16:31], v[64:67], v[76:79], v[16:31]
	v_mfma_f32_32x32x16_bf16 v[0:15], v[68:71], v[220:223], v[0:15]
	v_mfma_f32_32x32x16_bf16 v[16:31], v[68:71], v[224:227], v[16:31]
	global_load_dwordx4 v[188:191], v83, s[86:87]
	global_load_dwordx4 v[192:195], v83, s[86:87] offset:32
	global_load_dwordx4 v[196:199], v83, s[86:87] offset:64
	global_load_dwordx4 v[200:203], v83, s[86:87] offset:96
	global_load_dwordx4 v[204:207], v101, s[86:87] offset:768
	global_load_dwordx4 v[208:211], v150, s[86:87] offset:768
	global_load_dwordx4 v[212:215], v101, s[86:87] offset:832
	global_load_dwordx4 v[216:219], v150, s[86:87] offset:832
	s_add_u32 s86, s86, 0xc0000
	s_addc_u32 s87, s87, 0
	s_waitcnt vmcnt(16)
	ds_write_b128 v112, v[132:135]
	ds_write_b128 v112, v[136:139] offset:1024
	ds_write_b128 v112, v[140:143] offset:2048
	ds_write_b128 v112, v[144:147] offset:3072
	ds_read2_b32 v[32:33], v115 offset0:136 offset1:137
	ds_read2_b32 v[34:35], v115 offset0:138 offset1:139
	ds_read2_b32 v[36:37], v115 offset0:144 offset1:145
	ds_read2_b32 v[38:39], v115 offset0:146 offset1:147
	ds_read2_b32 v[40:41], v115 offset0:153 offset1:154
	ds_read2_b32 v[42:43], v115 offset0:155 offset1:156
	ds_read2_b32 v[44:45], v115 offset0:161 offset1:162
	ds_read2_b32 v[46:47], v115 offset0:163 offset1:164
	s_waitcnt lgkmcnt(0)
	v_mfma_f32_32x32x16_bf16 v[32:47], v[116:119], v[48:51], v[32:47]
	ds_read_b64_tr_b16 v[72:73], v231
	ds_read_b64_tr_b16 v[74:75], v231 offset:512
	ds_read_b64_tr_b16 v[76:77], v231 offset:2048
	ds_read_b64_tr_b16 v[78:79], v231 offset:2560
	ds_read_b64_tr_b16 v[220:221], v231 offset:1024
	ds_read_b64_tr_b16 v[222:223], v231 offset:1536
	ds_read_b64_tr_b16 v[224:225], v231 offset:3072
	ds_read_b64_tr_b16 v[226:227], v231 offset:3584
	v_mfma_f32_32x32x16_bf16 v[32:47], v[120:123], v[52:55], v[32:47]
	v_mfma_f32_32x32x16_bf16 v[32:47], v[124:127], v[56:59], v[32:47]
	v_mfma_f32_32x32x16_bf16 v[32:47], v[128:131], v[60:63], v[32:47]
	s_nop 11
	v_exp_f32_e32 v32, v32
	v_exp_f32_e32 v33, v33
	v_exp_f32_e32 v34, v34
	v_exp_f32_e32 v35, v35
	v_exp_f32_e32 v36, v36
	v_exp_f32_e32 v37, v37
	v_exp_f32_e32 v38, v38
	v_exp_f32_e32 v39, v39
	v_exp_f32_e32 v40, v40
	v_exp_f32_e32 v41, v41
	v_exp_f32_e32 v42, v42
	v_exp_f32_e32 v43, v43
	v_exp_f32_e32 v44, v44
	v_exp_f32_e32 v45, v45
	v_exp_f32_e32 v46, v46
	v_exp_f32_e32 v47, v47
	v_cvt_pk_bf16_f32 v64, v32, v33
	v_cvt_pk_bf16_f32 v65, v34, v35
	v_cvt_pk_bf16_f32 v66, v36, v37
	v_cvt_pk_bf16_f32 v67, v38, v39
	v_cvt_pk_bf16_f32 v68, v40, v41
	v_cvt_pk_bf16_f32 v69, v42, v43
	v_cvt_pk_bf16_f32 v70, v44, v45
	v_cvt_pk_bf16_f32 v71, v46, v47
	v_pk_add_f32 v[232:233], v[232:233], v[32:33]
	v_pk_add_f32 v[232:233], v[232:233], v[34:35]
	v_pk_add_f32 v[232:233], v[232:233], v[36:37]
	v_pk_add_f32 v[232:233], v[232:233], v[38:39]
	v_pk_add_f32 v[232:233], v[232:233], v[40:41]
	v_pk_add_f32 v[232:233], v[232:233], v[42:43]
	v_pk_add_f32 v[232:233], v[232:233], v[44:45]
	v_pk_add_f32 v[232:233], v[232:233], v[46:47]
	s_waitcnt lgkmcnt(0)
	v_mfma_f32_32x32x16_bf16 v[0:15], v[64:67], v[72:75], v[0:15]
	v_mfma_f32_32x32x16_bf16 v[16:31], v[64:67], v[76:79], v[16:31]
	v_mfma_f32_32x32x16_bf16 v[0:15], v[68:71], v[220:223], v[0:15]
	v_mfma_f32_32x32x16_bf16 v[16:31], v[68:71], v[224:227], v[16:31]
	global_load_dwordx4 v[116:119], v83, s[86:87]
	global_load_dwordx4 v[120:123], v83, s[86:87] offset:32
	global_load_dwordx4 v[124:127], v83, s[86:87] offset:64
	global_load_dwordx4 v[128:131], v83, s[86:87] offset:96
	global_load_dwordx4 v[132:135], v101, s[86:87] offset:768
	global_load_dwordx4 v[136:139], v150, s[86:87] offset:768
	global_load_dwordx4 v[140:143], v101, s[86:87] offset:832
	global_load_dwordx4 v[144:147], v150, s[86:87] offset:832
	s_add_u32 s86, s86, 0xc0000
	s_addc_u32 s87, s87, 0
	s_waitcnt vmcnt(16)
	ds_write_b128 v112, v[172:175]
	ds_write_b128 v112, v[176:179] offset:1024
	ds_write_b128 v112, v[180:183] offset:2048
	ds_write_b128 v112, v[184:187] offset:3072
	ds_read2_b32 v[32:33], v115 offset0:170 offset1:171
	ds_read2_b32 v[34:35], v115 offset0:172 offset1:173
	ds_read2_b32 v[36:37], v115 offset0:178 offset1:179
	ds_read2_b32 v[38:39], v115 offset0:180 offset1:181
	ds_read2_b32 v[40:41], v115 offset0:187 offset1:188
	ds_read2_b32 v[42:43], v115 offset0:189 offset1:190
	ds_read2_b32 v[44:45], v115 offset0:195 offset1:196
	ds_read2_b32 v[46:47], v115 offset0:197 offset1:198
	s_waitcnt lgkmcnt(0)
	v_mfma_f32_32x32x16_bf16 v[32:47], v[156:159], v[48:51], v[32:47]
	ds_read_b64_tr_b16 v[72:73], v231
	ds_read_b64_tr_b16 v[74:75], v231 offset:512
	ds_read_b64_tr_b16 v[76:77], v231 offset:2048
	ds_read_b64_tr_b16 v[78:79], v231 offset:2560
	ds_read_b64_tr_b16 v[220:221], v231 offset:1024
	ds_read_b64_tr_b16 v[222:223], v231 offset:1536
	ds_read_b64_tr_b16 v[224:225], v231 offset:3072
	ds_read_b64_tr_b16 v[226:227], v231 offset:3584
	v_mfma_f32_32x32x16_bf16 v[32:47], v[160:163], v[52:55], v[32:47]
	v_mfma_f32_32x32x16_bf16 v[32:47], v[164:167], v[56:59], v[32:47]
	v_mfma_f32_32x32x16_bf16 v[32:47], v[168:171], v[60:63], v[32:47]
	s_nop 11
	v_exp_f32_e32 v32, v32
	v_exp_f32_e32 v33, v33
	v_exp_f32_e32 v34, v34
	v_exp_f32_e32 v35, v35
	v_exp_f32_e32 v36, v36
	v_exp_f32_e32 v37, v37
	v_exp_f32_e32 v38, v38
	v_exp_f32_e32 v39, v39
	v_exp_f32_e32 v40, v40
	v_exp_f32_e32 v41, v41
	v_exp_f32_e32 v42, v42
	v_exp_f32_e32 v43, v43
	v_exp_f32_e32 v44, v44
	v_exp_f32_e32 v45, v45
	v_exp_f32_e32 v46, v46
	v_exp_f32_e32 v47, v47
	v_cvt_pk_bf16_f32 v64, v32, v33
	v_cvt_pk_bf16_f32 v65, v34, v35
	v_cvt_pk_bf16_f32 v66, v36, v37
	v_cvt_pk_bf16_f32 v67, v38, v39
	v_cvt_pk_bf16_f32 v68, v40, v41
	v_cvt_pk_bf16_f32 v69, v42, v43
	v_cvt_pk_bf16_f32 v70, v44, v45
	v_cvt_pk_bf16_f32 v71, v46, v47
	v_pk_add_f32 v[232:233], v[232:233], v[32:33]
	v_pk_add_f32 v[232:233], v[232:233], v[34:35]
	v_pk_add_f32 v[232:233], v[232:233], v[36:37]
	v_pk_add_f32 v[232:233], v[232:233], v[38:39]
	v_pk_add_f32 v[232:233], v[232:233], v[40:41]
	v_pk_add_f32 v[232:233], v[232:233], v[42:43]
	v_pk_add_f32 v[232:233], v[232:233], v[44:45]
	v_pk_add_f32 v[232:233], v[232:233], v[46:47]
	s_waitcnt lgkmcnt(0)
	v_mfma_f32_32x32x16_bf16 v[0:15], v[64:67], v[72:75], v[0:15]
	v_mfma_f32_32x32x16_bf16 v[16:31], v[64:67], v[76:79], v[16:31]
	v_mfma_f32_32x32x16_bf16 v[0:15], v[68:71], v[220:223], v[0:15]
	v_mfma_f32_32x32x16_bf16 v[16:31], v[68:71], v[224:227], v[16:31]
	global_load_dwordx4 v[156:159], v83, s[86:87]
	global_load_dwordx4 v[160:163], v83, s[86:87] offset:32
	global_load_dwordx4 v[164:167], v83, s[86:87] offset:64
	global_load_dwordx4 v[168:171], v83, s[86:87] offset:96
	global_load_dwordx4 v[172:175], v101, s[86:87] offset:768
	global_load_dwordx4 v[176:179], v150, s[86:87] offset:768
	global_load_dwordx4 v[180:183], v101, s[86:87] offset:832
	global_load_dwordx4 v[184:187], v150, s[86:87] offset:832
	s_add_u32 s86, s86, 0xc0000
	s_addc_u32 s87, s87, 0
	s_waitcnt vmcnt(16)
	ds_write_b128 v112, v[204:207]
	ds_write_b128 v112, v[208:211] offset:1024
	ds_write_b128 v112, v[212:215] offset:2048
	ds_write_b128 v112, v[216:219] offset:3072
	v_mov_b32_e32 v115, v229
	ds_read2_b32 v[32:33], v115 offset0:0 offset1:1
	ds_read2_b32 v[34:35], v115 offset0:2 offset1:3
	ds_read2_b32 v[36:37], v115 offset0:8 offset1:9
	ds_read2_b32 v[38:39], v115 offset0:10 offset1:11
	ds_read2_b32 v[40:41], v115 offset0:16 offset1:17
	ds_read2_b32 v[42:43], v115 offset0:18 offset1:19
	ds_read2_b32 v[44:45], v115 offset0:24 offset1:25
	ds_read2_b32 v[46:47], v115 offset0:26 offset1:27
	s_waitcnt lgkmcnt(0)
	v_mfma_f32_32x32x16_bf16 v[32:47], v[188:191], v[48:51], v[32:47]
	ds_read_b64_tr_b16 v[72:73], v231
	ds_read_b64_tr_b16 v[74:75], v231 offset:512
	ds_read_b64_tr_b16 v[76:77], v231 offset:2048
	ds_read_b64_tr_b16 v[78:79], v231 offset:2560
	ds_read_b64_tr_b16 v[220:221], v231 offset:1024
	ds_read_b64_tr_b16 v[222:223], v231 offset:1536
	ds_read_b64_tr_b16 v[224:225], v231 offset:3072
	ds_read_b64_tr_b16 v[226:227], v231 offset:3584
	v_mfma_f32_32x32x16_bf16 v[32:47], v[192:195], v[52:55], v[32:47]
	v_mfma_f32_32x32x16_bf16 v[32:47], v[196:199], v[56:59], v[32:47]
	v_mfma_f32_32x32x16_bf16 v[32:47], v[200:203], v[60:63], v[32:47]
	s_nop 11
	v_exp_f32_e32 v32, v32
	v_exp_f32_e32 v33, v33
	v_exp_f32_e32 v34, v34
	v_exp_f32_e32 v35, v35
	v_exp_f32_e32 v36, v36
	v_exp_f32_e32 v37, v37
	v_exp_f32_e32 v38, v38
	v_exp_f32_e32 v39, v39
	v_exp_f32_e32 v40, v40
	v_exp_f32_e32 v41, v41
	v_exp_f32_e32 v42, v42
	v_exp_f32_e32 v43, v43
	v_exp_f32_e32 v44, v44
	v_exp_f32_e32 v45, v45
	v_exp_f32_e32 v46, v46
	v_exp_f32_e32 v47, v47
	v_cvt_pk_bf16_f32 v64, v32, v33
	v_cvt_pk_bf16_f32 v65, v34, v35
	v_cvt_pk_bf16_f32 v66, v36, v37
	v_cvt_pk_bf16_f32 v67, v38, v39
	v_cvt_pk_bf16_f32 v68, v40, v41
	v_cvt_pk_bf16_f32 v69, v42, v43
	v_cvt_pk_bf16_f32 v70, v44, v45
	v_cvt_pk_bf16_f32 v71, v46, v47
	v_pk_add_f32 v[232:233], v[232:233], v[32:33]
	v_pk_add_f32 v[232:233], v[232:233], v[34:35]
	v_pk_add_f32 v[232:233], v[232:233], v[36:37]
	v_pk_add_f32 v[232:233], v[232:233], v[38:39]
	v_pk_add_f32 v[232:233], v[232:233], v[40:41]
	v_pk_add_f32 v[232:233], v[232:233], v[42:43]
	v_pk_add_f32 v[232:233], v[232:233], v[44:45]
	v_pk_add_f32 v[232:233], v[232:233], v[46:47]
	s_waitcnt lgkmcnt(0)
	v_mfma_f32_32x32x16_bf16 v[0:15], v[64:67], v[72:75], v[0:15]
	v_mfma_f32_32x32x16_bf16 v[16:31], v[64:67], v[76:79], v[16:31]
	v_mfma_f32_32x32x16_bf16 v[0:15], v[68:71], v[220:223], v[0:15]
	v_mfma_f32_32x32x16_bf16 v[16:31], v[68:71], v[224:227], v[16:31]
	global_load_dwordx4 v[188:191], v83, s[86:87]
	global_load_dwordx4 v[192:195], v83, s[86:87] offset:32
	global_load_dwordx4 v[196:199], v83, s[86:87] offset:64
	global_load_dwordx4 v[200:203], v83, s[86:87] offset:96
	global_load_dwordx4 v[204:207], v101, s[86:87] offset:768
	global_load_dwordx4 v[208:211], v150, s[86:87] offset:768
	global_load_dwordx4 v[212:215], v101, s[86:87] offset:832
	global_load_dwordx4 v[216:219], v150, s[86:87] offset:832
	s_add_u32 s86, s86, 0xc0000
	s_addc_u32 s87, s87, 0
	s_waitcnt vmcnt(16)
	ds_write_b128 v112, v[132:135]
	ds_write_b128 v112, v[136:139] offset:1024
	ds_write_b128 v112, v[140:143] offset:2048
	ds_write_b128 v112, v[144:147] offset:3072
	ds_read2_b32 v[32:33], v115 offset0:32 offset1:33
	ds_read2_b32 v[34:35], v115 offset0:34 offset1:35
	ds_read2_b32 v[36:37], v115 offset0:40 offset1:41
	ds_read2_b32 v[38:39], v115 offset0:42 offset1:43
	ds_read2_b32 v[40:41], v115 offset0:48 offset1:49
	ds_read2_b32 v[42:43], v115 offset0:50 offset1:51
	ds_read2_b32 v[44:45], v115 offset0:56 offset1:57
	ds_read2_b32 v[46:47], v115 offset0:58 offset1:59
	s_waitcnt lgkmcnt(0)
	v_mfma_f32_32x32x16_bf16 v[32:47], v[116:119], v[48:51], v[32:47]
	ds_read_b64_tr_b16 v[72:73], v231
	ds_read_b64_tr_b16 v[74:75], v231 offset:512
	ds_read_b64_tr_b16 v[76:77], v231 offset:2048
	ds_read_b64_tr_b16 v[78:79], v231 offset:2560
	ds_read_b64_tr_b16 v[220:221], v231 offset:1024
	ds_read_b64_tr_b16 v[222:223], v231 offset:1536
	ds_read_b64_tr_b16 v[224:225], v231 offset:3072
	ds_read_b64_tr_b16 v[226:227], v231 offset:3584
	v_mfma_f32_32x32x16_bf16 v[32:47], v[120:123], v[52:55], v[32:47]
	v_mfma_f32_32x32x16_bf16 v[32:47], v[124:127], v[56:59], v[32:47]
	v_mfma_f32_32x32x16_bf16 v[32:47], v[128:131], v[60:63], v[32:47]
	s_nop 11
	v_exp_f32_e32 v32, v32
	v_exp_f32_e32 v33, v33
	v_exp_f32_e32 v34, v34
	v_exp_f32_e32 v35, v35
	v_exp_f32_e32 v36, v36
	v_exp_f32_e32 v37, v37
	v_exp_f32_e32 v38, v38
	v_exp_f32_e32 v39, v39
	v_exp_f32_e32 v40, v40
	v_exp_f32_e32 v41, v41
	v_exp_f32_e32 v42, v42
	v_exp_f32_e32 v43, v43
	v_exp_f32_e32 v44, v44
	v_exp_f32_e32 v45, v45
	v_exp_f32_e32 v46, v46
	v_exp_f32_e32 v47, v47
	v_cvt_pk_bf16_f32 v64, v32, v33
	v_cvt_pk_bf16_f32 v65, v34, v35
	v_cvt_pk_bf16_f32 v66, v36, v37
	v_cvt_pk_bf16_f32 v67, v38, v39
	v_cvt_pk_bf16_f32 v68, v40, v41
	v_cvt_pk_bf16_f32 v69, v42, v43
	v_cvt_pk_bf16_f32 v70, v44, v45
	v_cvt_pk_bf16_f32 v71, v46, v47
	v_pk_add_f32 v[232:233], v[232:233], v[32:33]
	v_pk_add_f32 v[232:233], v[232:233], v[34:35]
	v_pk_add_f32 v[232:233], v[232:233], v[36:37]
	v_pk_add_f32 v[232:233], v[232:233], v[38:39]
	v_pk_add_f32 v[232:233], v[232:233], v[40:41]
	v_pk_add_f32 v[232:233], v[232:233], v[42:43]
	v_pk_add_f32 v[232:233], v[232:233], v[44:45]
	v_pk_add_f32 v[232:233], v[232:233], v[46:47]
	s_waitcnt lgkmcnt(0)
	v_mfma_f32_32x32x16_bf16 v[0:15], v[64:67], v[72:75], v[0:15]
	v_mfma_f32_32x32x16_bf16 v[16:31], v[64:67], v[76:79], v[16:31]
	v_mfma_f32_32x32x16_bf16 v[0:15], v[68:71], v[220:223], v[0:15]
	v_mfma_f32_32x32x16_bf16 v[16:31], v[68:71], v[224:227], v[16:31]
	global_load_dwordx4 v[116:119], v83, s[86:87]
	global_load_dwordx4 v[120:123], v83, s[86:87] offset:32
	global_load_dwordx4 v[124:127], v83, s[86:87] offset:64
	global_load_dwordx4 v[128:131], v83, s[86:87] offset:96
	global_load_dwordx4 v[132:135], v101, s[86:87] offset:768
	global_load_dwordx4 v[136:139], v150, s[86:87] offset:768
	global_load_dwordx4 v[140:143], v101, s[86:87] offset:832
	global_load_dwordx4 v[144:147], v150, s[86:87] offset:832
	s_add_u32 s86, s86, 0xc0000
	s_addc_u32 s87, s87, 0
	s_waitcnt vmcnt(16)
	ds_write_b128 v112, v[172:175]
	ds_write_b128 v112, v[176:179] offset:1024
	ds_write_b128 v112, v[180:183] offset:2048
	ds_write_b128 v112, v[184:187] offset:3072
	ds_read2_b32 v[32:33], v115 offset0:64 offset1:65
	ds_read2_b32 v[34:35], v115 offset0:66 offset1:67
	ds_read2_b32 v[36:37], v115 offset0:72 offset1:73
	ds_read2_b32 v[38:39], v115 offset0:74 offset1:75
	ds_read2_b32 v[40:41], v115 offset0:80 offset1:81
	ds_read2_b32 v[42:43], v115 offset0:82 offset1:83
	ds_read2_b32 v[44:45], v115 offset0:88 offset1:89
	ds_read2_b32 v[46:47], v115 offset0:90 offset1:91
	s_waitcnt lgkmcnt(0)
	v_mfma_f32_32x32x16_bf16 v[32:47], v[156:159], v[48:51], v[32:47]
	ds_read_b64_tr_b16 v[72:73], v231
	ds_read_b64_tr_b16 v[74:75], v231 offset:512
	ds_read_b64_tr_b16 v[76:77], v231 offset:2048
	ds_read_b64_tr_b16 v[78:79], v231 offset:2560
	ds_read_b64_tr_b16 v[220:221], v231 offset:1024
	ds_read_b64_tr_b16 v[222:223], v231 offset:1536
	ds_read_b64_tr_b16 v[224:225], v231 offset:3072
	ds_read_b64_tr_b16 v[226:227], v231 offset:3584
	v_mfma_f32_32x32x16_bf16 v[32:47], v[160:163], v[52:55], v[32:47]
	v_mfma_f32_32x32x16_bf16 v[32:47], v[164:167], v[56:59], v[32:47]
	v_mfma_f32_32x32x16_bf16 v[32:47], v[168:171], v[60:63], v[32:47]
	s_nop 11
	v_exp_f32_e32 v32, v32
	v_exp_f32_e32 v33, v33
	v_exp_f32_e32 v34, v34
	v_exp_f32_e32 v35, v35
	v_exp_f32_e32 v36, v36
	v_exp_f32_e32 v37, v37
	v_exp_f32_e32 v38, v38
	v_exp_f32_e32 v39, v39
	v_exp_f32_e32 v40, v40
	v_exp_f32_e32 v41, v41
	v_exp_f32_e32 v42, v42
	v_exp_f32_e32 v43, v43
	v_exp_f32_e32 v44, v44
	v_exp_f32_e32 v45, v45
	v_exp_f32_e32 v46, v46
	v_exp_f32_e32 v47, v47
	v_cvt_pk_bf16_f32 v64, v32, v33
	v_cvt_pk_bf16_f32 v65, v34, v35
	v_cvt_pk_bf16_f32 v66, v36, v37
	v_cvt_pk_bf16_f32 v67, v38, v39
	v_cvt_pk_bf16_f32 v68, v40, v41
	v_cvt_pk_bf16_f32 v69, v42, v43
	v_cvt_pk_bf16_f32 v70, v44, v45
	v_cvt_pk_bf16_f32 v71, v46, v47
	v_pk_add_f32 v[232:233], v[232:233], v[32:33]
	v_pk_add_f32 v[232:233], v[232:233], v[34:35]
	v_pk_add_f32 v[232:233], v[232:233], v[36:37]
	v_pk_add_f32 v[232:233], v[232:233], v[38:39]
	v_pk_add_f32 v[232:233], v[232:233], v[40:41]
	v_pk_add_f32 v[232:233], v[232:233], v[42:43]
	v_pk_add_f32 v[232:233], v[232:233], v[44:45]
	v_pk_add_f32 v[232:233], v[232:233], v[46:47]
	s_waitcnt lgkmcnt(0)
	v_mfma_f32_32x32x16_bf16 v[0:15], v[64:67], v[72:75], v[0:15]
	v_mfma_f32_32x32x16_bf16 v[16:31], v[64:67], v[76:79], v[16:31]
	v_mfma_f32_32x32x16_bf16 v[0:15], v[68:71], v[220:223], v[0:15]
	v_mfma_f32_32x32x16_bf16 v[16:31], v[68:71], v[224:227], v[16:31]
	global_load_dwordx4 v[156:159], v83, s[86:87]
	global_load_dwordx4 v[160:163], v83, s[86:87] offset:32
	global_load_dwordx4 v[164:167], v83, s[86:87] offset:64
	global_load_dwordx4 v[168:171], v83, s[86:87] offset:96
	global_load_dwordx4 v[172:175], v101, s[86:87] offset:768
	global_load_dwordx4 v[176:179], v150, s[86:87] offset:768
	global_load_dwordx4 v[180:183], v101, s[86:87] offset:832
	global_load_dwordx4 v[184:187], v150, s[86:87] offset:832
	s_add_u32 s86, s86, 0xc0000
	s_addc_u32 s87, s87, 0
	s_waitcnt vmcnt(16)
	ds_write_b128 v112, v[204:207]
	ds_write_b128 v112, v[208:211] offset:1024
	ds_write_b128 v112, v[212:215] offset:2048
	ds_write_b128 v112, v[216:219] offset:3072
	ds_read2_b32 v[32:33], v115 offset0:96 offset1:97
	ds_read2_b32 v[34:35], v115 offset0:98 offset1:99
	ds_read2_b32 v[36:37], v115 offset0:104 offset1:105
	ds_read2_b32 v[38:39], v115 offset0:106 offset1:107
	ds_read2_b32 v[40:41], v115 offset0:112 offset1:113
	ds_read2_b32 v[42:43], v115 offset0:114 offset1:115
	ds_read2_b32 v[44:45], v115 offset0:120 offset1:121
	ds_read2_b32 v[46:47], v115 offset0:122 offset1:123
	s_waitcnt lgkmcnt(0)
	v_mfma_f32_32x32x16_bf16 v[32:47], v[188:191], v[48:51], v[32:47]
	ds_read_b64_tr_b16 v[72:73], v231
	ds_read_b64_tr_b16 v[74:75], v231 offset:512
	ds_read_b64_tr_b16 v[76:77], v231 offset:2048
	ds_read_b64_tr_b16 v[78:79], v231 offset:2560
	ds_read_b64_tr_b16 v[220:221], v231 offset:1024
	ds_read_b64_tr_b16 v[222:223], v231 offset:1536
	ds_read_b64_tr_b16 v[224:225], v231 offset:3072
	ds_read_b64_tr_b16 v[226:227], v231 offset:3584
	v_mfma_f32_32x32x16_bf16 v[32:47], v[192:195], v[52:55], v[32:47]
	v_mfma_f32_32x32x16_bf16 v[32:47], v[196:199], v[56:59], v[32:47]
	v_mfma_f32_32x32x16_bf16 v[32:47], v[200:203], v[60:63], v[32:47]
	s_nop 11
	v_exp_f32_e32 v32, v32
	v_exp_f32_e32 v33, v33
	v_exp_f32_e32 v34, v34
	v_exp_f32_e32 v35, v35
	v_exp_f32_e32 v36, v36
	v_exp_f32_e32 v37, v37
	v_exp_f32_e32 v38, v38
	v_exp_f32_e32 v39, v39
	v_exp_f32_e32 v40, v40
	v_exp_f32_e32 v41, v41
	v_exp_f32_e32 v42, v42
	v_exp_f32_e32 v43, v43
	v_exp_f32_e32 v44, v44
	v_exp_f32_e32 v45, v45
	v_exp_f32_e32 v46, v46
	v_exp_f32_e32 v47, v47
	v_cvt_pk_bf16_f32 v64, v32, v33
	v_cvt_pk_bf16_f32 v65, v34, v35
	v_cvt_pk_bf16_f32 v66, v36, v37
	v_cvt_pk_bf16_f32 v67, v38, v39
	v_cvt_pk_bf16_f32 v68, v40, v41
	v_cvt_pk_bf16_f32 v69, v42, v43
	v_cvt_pk_bf16_f32 v70, v44, v45
	v_cvt_pk_bf16_f32 v71, v46, v47
	v_pk_add_f32 v[232:233], v[232:233], v[32:33]
	v_pk_add_f32 v[232:233], v[232:233], v[34:35]
	v_pk_add_f32 v[232:233], v[232:233], v[36:37]
	v_pk_add_f32 v[232:233], v[232:233], v[38:39]
	v_pk_add_f32 v[232:233], v[232:233], v[40:41]
	v_pk_add_f32 v[232:233], v[232:233], v[42:43]
	v_pk_add_f32 v[232:233], v[232:233], v[44:45]
	v_pk_add_f32 v[232:233], v[232:233], v[46:47]
	s_waitcnt lgkmcnt(0)
	v_mfma_f32_32x32x16_bf16 v[0:15], v[64:67], v[72:75], v[0:15]
	v_mfma_f32_32x32x16_bf16 v[16:31], v[64:67], v[76:79], v[16:31]
	v_mfma_f32_32x32x16_bf16 v[0:15], v[68:71], v[220:223], v[0:15]
	v_mfma_f32_32x32x16_bf16 v[16:31], v[68:71], v[224:227], v[16:31]
	global_load_dwordx4 v[188:191], v83, s[86:87]
	global_load_dwordx4 v[192:195], v83, s[86:87] offset:32
	global_load_dwordx4 v[196:199], v83, s[86:87] offset:64
	global_load_dwordx4 v[200:203], v83, s[86:87] offset:96
	global_load_dwordx4 v[204:207], v101, s[86:87] offset:768
	global_load_dwordx4 v[208:211], v150, s[86:87] offset:768
	global_load_dwordx4 v[212:215], v101, s[86:87] offset:832
	global_load_dwordx4 v[216:219], v150, s[86:87] offset:832
	s_add_u32 s86, s86, 0xc0000
	s_addc_u32 s87, s87, 0
	s_waitcnt vmcnt(16)
	ds_write_b128 v112, v[132:135]
	ds_write_b128 v112, v[136:139] offset:1024
	ds_write_b128 v112, v[140:143] offset:2048
	ds_write_b128 v112, v[144:147] offset:3072
	ds_read2_b32 v[32:33], v115 offset0:128 offset1:129
	ds_read2_b32 v[34:35], v115 offset0:130 offset1:131
	ds_read2_b32 v[36:37], v115 offset0:136 offset1:137
	ds_read2_b32 v[38:39], v115 offset0:138 offset1:139
	ds_read2_b32 v[40:41], v115 offset0:144 offset1:145
	ds_read2_b32 v[42:43], v115 offset0:146 offset1:147
	ds_read2_b32 v[44:45], v115 offset0:152 offset1:153
	ds_read2_b32 v[46:47], v115 offset0:154 offset1:155
	s_waitcnt lgkmcnt(0)
	v_mfma_f32_32x32x16_bf16 v[32:47], v[116:119], v[48:51], v[32:47]
	ds_read_b64_tr_b16 v[72:73], v231
	ds_read_b64_tr_b16 v[74:75], v231 offset:512
	ds_read_b64_tr_b16 v[76:77], v231 offset:2048
	ds_read_b64_tr_b16 v[78:79], v231 offset:2560
	ds_read_b64_tr_b16 v[220:221], v231 offset:1024
	ds_read_b64_tr_b16 v[222:223], v231 offset:1536
	ds_read_b64_tr_b16 v[224:225], v231 offset:3072
	ds_read_b64_tr_b16 v[226:227], v231 offset:3584
	v_mfma_f32_32x32x16_bf16 v[32:47], v[120:123], v[52:55], v[32:47]
	v_mfma_f32_32x32x16_bf16 v[32:47], v[124:127], v[56:59], v[32:47]
	v_mfma_f32_32x32x16_bf16 v[32:47], v[128:131], v[60:63], v[32:47]
	s_nop 11
	v_exp_f32_e32 v32, v32
	v_exp_f32_e32 v33, v33
	v_exp_f32_e32 v34, v34
	v_exp_f32_e32 v35, v35
	v_exp_f32_e32 v36, v36
	v_exp_f32_e32 v37, v37
	v_exp_f32_e32 v38, v38
	v_exp_f32_e32 v39, v39
	v_exp_f32_e32 v40, v40
	v_exp_f32_e32 v41, v41
	v_exp_f32_e32 v42, v42
	v_exp_f32_e32 v43, v43
	v_exp_f32_e32 v44, v44
	v_exp_f32_e32 v45, v45
	v_exp_f32_e32 v46, v46
	v_exp_f32_e32 v47, v47
	v_cvt_pk_bf16_f32 v64, v32, v33
	v_cvt_pk_bf16_f32 v65, v34, v35
	v_cvt_pk_bf16_f32 v66, v36, v37
	v_cvt_pk_bf16_f32 v67, v38, v39
	v_cvt_pk_bf16_f32 v68, v40, v41
	v_cvt_pk_bf16_f32 v69, v42, v43
	v_cvt_pk_bf16_f32 v70, v44, v45
	v_cvt_pk_bf16_f32 v71, v46, v47
	v_pk_add_f32 v[232:233], v[232:233], v[32:33]
	v_pk_add_f32 v[232:233], v[232:233], v[34:35]
	v_pk_add_f32 v[232:233], v[232:233], v[36:37]
	v_pk_add_f32 v[232:233], v[232:233], v[38:39]
	v_pk_add_f32 v[232:233], v[232:233], v[40:41]
	v_pk_add_f32 v[232:233], v[232:233], v[42:43]
	v_pk_add_f32 v[232:233], v[232:233], v[44:45]
	v_pk_add_f32 v[232:233], v[232:233], v[46:47]
	s_waitcnt lgkmcnt(0)
	v_mfma_f32_32x32x16_bf16 v[0:15], v[64:67], v[72:75], v[0:15]
	v_mfma_f32_32x32x16_bf16 v[16:31], v[64:67], v[76:79], v[16:31]
	v_mfma_f32_32x32x16_bf16 v[0:15], v[68:71], v[220:223], v[0:15]
	v_mfma_f32_32x32x16_bf16 v[16:31], v[68:71], v[224:227], v[16:31]
	global_load_dwordx4 v[116:119], v83, s[86:87]
	global_load_dwordx4 v[120:123], v83, s[86:87] offset:32
	global_load_dwordx4 v[124:127], v83, s[86:87] offset:64
	global_load_dwordx4 v[128:131], v83, s[86:87] offset:96
	global_load_dwordx4 v[132:135], v101, s[86:87] offset:768
	global_load_dwordx4 v[136:139], v150, s[86:87] offset:768
	global_load_dwordx4 v[140:143], v101, s[86:87] offset:832
	global_load_dwordx4 v[144:147], v150, s[86:87] offset:832
	s_waitcnt vmcnt(16)
	ds_write_b128 v112, v[172:175]
	ds_write_b128 v112, v[176:179] offset:1024
	ds_write_b128 v112, v[180:183] offset:2048
	ds_write_b128 v112, v[184:187] offset:3072
	ds_read2_b32 v[32:33], v115 offset0:160 offset1:161
	ds_read2_b32 v[34:35], v115 offset0:162 offset1:163
	ds_read2_b32 v[36:37], v115 offset0:168 offset1:169
	ds_read2_b32 v[38:39], v115 offset0:170 offset1:171
	ds_read2_b32 v[40:41], v115 offset0:176 offset1:177
	ds_read2_b32 v[42:43], v115 offset0:178 offset1:179
	ds_read2_b32 v[44:45], v115 offset0:184 offset1:185
	ds_read2_b32 v[46:47], v115 offset0:186 offset1:187
	s_waitcnt lgkmcnt(0)
	v_mfma_f32_32x32x16_bf16 v[32:47], v[156:159], v[48:51], v[32:47]
	ds_read_b64_tr_b16 v[72:73], v231
	ds_read_b64_tr_b16 v[74:75], v231 offset:512
	ds_read_b64_tr_b16 v[76:77], v231 offset:2048
	ds_read_b64_tr_b16 v[78:79], v231 offset:2560
	ds_read_b64_tr_b16 v[220:221], v231 offset:1024
	ds_read_b64_tr_b16 v[222:223], v231 offset:1536
	ds_read_b64_tr_b16 v[224:225], v231 offset:3072
	ds_read_b64_tr_b16 v[226:227], v231 offset:3584
	v_mfma_f32_32x32x16_bf16 v[32:47], v[160:163], v[52:55], v[32:47]
	v_mfma_f32_32x32x16_bf16 v[32:47], v[164:167], v[56:59], v[32:47]
	v_mfma_f32_32x32x16_bf16 v[32:47], v[168:171], v[60:63], v[32:47]
	s_nop 11
	v_exp_f32_e32 v32, v32
	v_exp_f32_e32 v33, v33
	v_exp_f32_e32 v34, v34
	v_exp_f32_e32 v35, v35
	v_exp_f32_e32 v36, v36
	v_exp_f32_e32 v37, v37
	v_exp_f32_e32 v38, v38
	v_exp_f32_e32 v39, v39
	v_exp_f32_e32 v40, v40
	v_exp_f32_e32 v41, v41
	v_exp_f32_e32 v42, v42
	v_exp_f32_e32 v43, v43
	v_exp_f32_e32 v44, v44
	v_exp_f32_e32 v45, v45
	v_exp_f32_e32 v46, v46
	v_exp_f32_e32 v47, v47
	v_cvt_pk_bf16_f32 v64, v32, v33
	v_cvt_pk_bf16_f32 v65, v34, v35
	v_cvt_pk_bf16_f32 v66, v36, v37
	v_cvt_pk_bf16_f32 v67, v38, v39
	v_cvt_pk_bf16_f32 v68, v40, v41
	v_cvt_pk_bf16_f32 v69, v42, v43
	v_cvt_pk_bf16_f32 v70, v44, v45
	v_cvt_pk_bf16_f32 v71, v46, v47
	v_pk_add_f32 v[232:233], v[232:233], v[32:33]
	v_pk_add_f32 v[232:233], v[232:233], v[34:35]
	v_pk_add_f32 v[232:233], v[232:233], v[36:37]
	v_pk_add_f32 v[232:233], v[232:233], v[38:39]
	v_pk_add_f32 v[232:233], v[232:233], v[40:41]
	v_pk_add_f32 v[232:233], v[232:233], v[42:43]
	v_pk_add_f32 v[232:233], v[232:233], v[44:45]
	v_pk_add_f32 v[232:233], v[232:233], v[46:47]
	s_waitcnt lgkmcnt(0)
	v_mfma_f32_32x32x16_bf16 v[0:15], v[64:67], v[72:75], v[0:15]
	v_mfma_f32_32x32x16_bf16 v[16:31], v[64:67], v[76:79], v[16:31]
	v_mfma_f32_32x32x16_bf16 v[0:15], v[68:71], v[220:223], v[0:15]
	v_mfma_f32_32x32x16_bf16 v[16:31], v[68:71], v[224:227], v[16:31]
	global_load_dwordx4 v[156:159], v99, s[88:89]
	global_load_dwordx4 v[160:163], v99, s[88:89] offset:32
	global_load_dwordx4 v[164:167], v99, s[88:89] offset:64
	global_load_dwordx4 v[168:171], v99, s[88:89] offset:96
	global_load_dwordx4 v[172:175], v148, s[88:89] offset:768
	global_load_dwordx4 v[176:179], v151, s[88:89] offset:768
	global_load_dwordx4 v[180:183], v148, s[88:89] offset:832
	global_load_dwordx4 v[184:187], v151, s[88:89] offset:832
	s_add_u32 s88, s88, 0x300000
	s_addc_u32 s89, s89, 0
	s_waitcnt vmcnt(16)
	ds_write_b128 v112, v[204:207]
	ds_write_b128 v112, v[208:211] offset:1024
	ds_write_b128 v112, v[212:215] offset:2048
	ds_write_b128 v112, v[216:219] offset:3072
	ds_read2_b32 v[32:33], v115 offset0:192 offset1:193
	ds_read2_b32 v[34:35], v115 offset0:194 offset1:195
	ds_read2_b32 v[36:37], v115 offset0:200 offset1:201
	ds_read2_b32 v[38:39], v115 offset0:202 offset1:203
	ds_read2_b32 v[40:41], v115 offset0:208 offset1:209
	ds_read2_b32 v[42:43], v115 offset0:210 offset1:211
	ds_read2_b32 v[44:45], v115 offset0:216 offset1:217
	ds_read2_b32 v[46:47], v115 offset0:218 offset1:219
	s_waitcnt lgkmcnt(0)
	v_mfma_f32_32x32x16_bf16 v[32:47], v[188:191], v[48:51], v[32:47]
	ds_read_b64_tr_b16 v[72:73], v231
	ds_read_b64_tr_b16 v[74:75], v231 offset:512
	ds_read_b64_tr_b16 v[76:77], v231 offset:2048
	ds_read_b64_tr_b16 v[78:79], v231 offset:2560
	ds_read_b64_tr_b16 v[220:221], v231 offset:1024
	ds_read_b64_tr_b16 v[222:223], v231 offset:1536
	ds_read_b64_tr_b16 v[224:225], v231 offset:3072
	ds_read_b64_tr_b16 v[226:227], v231 offset:3584
	v_mfma_f32_32x32x16_bf16 v[32:47], v[192:195], v[52:55], v[32:47]
	v_mfma_f32_32x32x16_bf16 v[32:47], v[196:199], v[56:59], v[32:47]
	v_mfma_f32_32x32x16_bf16 v[32:47], v[200:203], v[60:63], v[32:47]
	s_nop 11
	v_exp_f32_e32 v32, v32
	v_exp_f32_e32 v33, v33
	v_exp_f32_e32 v34, v34
	v_exp_f32_e32 v35, v35
	v_exp_f32_e32 v36, v36
	v_exp_f32_e32 v37, v37
	v_exp_f32_e32 v38, v38
	v_exp_f32_e32 v39, v39
	v_exp_f32_e32 v40, v40
	v_exp_f32_e32 v41, v41
	v_exp_f32_e32 v42, v42
	v_exp_f32_e32 v43, v43
	v_exp_f32_e32 v44, v44
	v_exp_f32_e32 v45, v45
	v_exp_f32_e32 v46, v46
	v_exp_f32_e32 v47, v47
	v_cvt_pk_bf16_f32 v64, v32, v33
	v_cvt_pk_bf16_f32 v65, v34, v35
	v_cvt_pk_bf16_f32 v66, v36, v37
	v_cvt_pk_bf16_f32 v67, v38, v39
	v_cvt_pk_bf16_f32 v68, v40, v41
	v_cvt_pk_bf16_f32 v69, v42, v43
	v_cvt_pk_bf16_f32 v70, v44, v45
	v_cvt_pk_bf16_f32 v71, v46, v47
	v_pk_add_f32 v[232:233], v[232:233], v[32:33]
	v_pk_add_f32 v[232:233], v[232:233], v[34:35]
	v_pk_add_f32 v[232:233], v[232:233], v[36:37]
	v_pk_add_f32 v[232:233], v[232:233], v[38:39]
	v_pk_add_f32 v[232:233], v[232:233], v[40:41]
	v_pk_add_f32 v[232:233], v[232:233], v[42:43]
	v_pk_add_f32 v[232:233], v[232:233], v[44:45]
	v_pk_add_f32 v[232:233], v[232:233], v[46:47]
	s_waitcnt lgkmcnt(0)
	v_mfma_f32_32x32x16_bf16 v[0:15], v[64:67], v[72:75], v[0:15]
	v_mfma_f32_32x32x16_bf16 v[16:31], v[64:67], v[76:79], v[16:31]
	v_mfma_f32_32x32x16_bf16 v[0:15], v[68:71], v[220:223], v[0:15]
	v_mfma_f32_32x32x16_bf16 v[16:31], v[68:71], v[224:227], v[16:31]
	global_load_dwordx4 v[188:191], v99, s[88:89]
	global_load_dwordx4 v[192:195], v99, s[88:89] offset:32
	global_load_dwordx4 v[196:199], v99, s[88:89] offset:64
	global_load_dwordx4 v[200:203], v99, s[88:89] offset:96
	global_load_dwordx4 v[204:207], v148, s[88:89] offset:768
	global_load_dwordx4 v[208:211], v151, s[88:89] offset:768
	global_load_dwordx4 v[212:215], v148, s[88:89] offset:832
	global_load_dwordx4 v[216:219], v151, s[88:89] offset:832
	s_add_u32 s88, s88, 0x300000
	s_addc_u32 s89, s89, 0
	s_waitcnt vmcnt(16)
	ds_write_b128 v112, v[132:135]
	ds_write_b128 v112, v[136:139] offset:1024
	ds_write_b128 v112, v[140:143] offset:2048
	ds_write_b128 v112, v[144:147] offset:3072
	ds_read2_b32 v[32:33], v115 offset0:224 offset1:225
	ds_read2_b32 v[34:35], v115 offset0:226 offset1:227
	ds_read2_b32 v[36:37], v115 offset0:232 offset1:233
	ds_read2_b32 v[38:39], v115 offset0:234 offset1:235
	ds_read2_b32 v[40:41], v115 offset0:240 offset1:241
	ds_read2_b32 v[42:43], v115 offset0:242 offset1:243
	ds_read2_b32 v[44:45], v115 offset0:248 offset1:249
	ds_read2_b32 v[46:47], v115 offset0:250 offset1:251
	s_waitcnt lgkmcnt(0)
	v_mfma_f32_32x32x16_bf16 v[32:47], v[116:119], v[48:51], v[32:47]
	ds_read_b64_tr_b16 v[72:73], v231
	ds_read_b64_tr_b16 v[74:75], v231 offset:512
	ds_read_b64_tr_b16 v[76:77], v231 offset:2048
	ds_read_b64_tr_b16 v[78:79], v231 offset:2560
	ds_read_b64_tr_b16 v[220:221], v231 offset:1024
	ds_read_b64_tr_b16 v[222:223], v231 offset:1536
	ds_read_b64_tr_b16 v[224:225], v231 offset:3072
	ds_read_b64_tr_b16 v[226:227], v231 offset:3584
	v_mfma_f32_32x32x16_bf16 v[32:47], v[120:123], v[52:55], v[32:47]
	v_mfma_f32_32x32x16_bf16 v[32:47], v[124:127], v[56:59], v[32:47]
	v_mfma_f32_32x32x16_bf16 v[32:47], v[128:131], v[60:63], v[32:47]
	s_nop 11
	v_exp_f32_e32 v32, v32
	v_exp_f32_e32 v33, v33
	v_exp_f32_e32 v34, v34
	v_exp_f32_e32 v35, v35
	v_exp_f32_e32 v36, v36
	v_exp_f32_e32 v37, v37
	v_exp_f32_e32 v38, v38
	v_exp_f32_e32 v39, v39
	v_exp_f32_e32 v40, v40
	v_exp_f32_e32 v41, v41
	v_exp_f32_e32 v42, v42
	v_exp_f32_e32 v43, v43
	v_exp_f32_e32 v44, v44
	v_exp_f32_e32 v45, v45
	v_exp_f32_e32 v46, v46
	v_exp_f32_e32 v47, v47
	v_cvt_pk_bf16_f32 v64, v32, v33
	v_cvt_pk_bf16_f32 v65, v34, v35
	v_cvt_pk_bf16_f32 v66, v36, v37
	v_cvt_pk_bf16_f32 v67, v38, v39
	v_cvt_pk_bf16_f32 v68, v40, v41
	v_cvt_pk_bf16_f32 v69, v42, v43
	v_cvt_pk_bf16_f32 v70, v44, v45
	v_cvt_pk_bf16_f32 v71, v46, v47
	v_pk_add_f32 v[232:233], v[232:233], v[32:33]
	v_pk_add_f32 v[232:233], v[232:233], v[34:35]
	v_pk_add_f32 v[232:233], v[232:233], v[36:37]
	v_pk_add_f32 v[232:233], v[232:233], v[38:39]
	v_pk_add_f32 v[232:233], v[232:233], v[40:41]
	v_pk_add_f32 v[232:233], v[232:233], v[42:43]
	v_pk_add_f32 v[232:233], v[232:233], v[44:45]
	v_pk_add_f32 v[232:233], v[232:233], v[46:47]
	s_waitcnt lgkmcnt(0)
	v_mfma_f32_32x32x16_bf16 v[0:15], v[64:67], v[72:75], v[0:15]
	v_mfma_f32_32x32x16_bf16 v[16:31], v[64:67], v[76:79], v[16:31]
	v_mfma_f32_32x32x16_bf16 v[0:15], v[68:71], v[220:223], v[0:15]
	v_mfma_f32_32x32x16_bf16 v[16:31], v[68:71], v[224:227], v[16:31]
	global_load_dwordx4 v[116:119], v99, s[88:89]
	global_load_dwordx4 v[120:123], v99, s[88:89] offset:32
	global_load_dwordx4 v[124:127], v99, s[88:89] offset:64
	global_load_dwordx4 v[128:131], v99, s[88:89] offset:96
	global_load_dwordx4 v[132:135], v148, s[88:89] offset:768
	global_load_dwordx4 v[136:139], v151, s[88:89] offset:768
	global_load_dwordx4 v[140:143], v148, s[88:89] offset:832
	global_load_dwordx4 v[144:147], v151, s[88:89] offset:832
	s_add_u32 s88, s88, 0x300000
	s_addc_u32 s89, s89, 0
	s_waitcnt vmcnt(16)
	ds_write_b128 v112, v[172:175]
	ds_write_b128 v112, v[176:179] offset:1024
	ds_write_b128 v112, v[180:183] offset:2048
	ds_write_b128 v112, v[184:187] offset:3072
	v_mov_b32_e32 v115, v230
	ds_read2_b32 v[32:33], v115 offset0:0 offset1:1
	ds_read2_b32 v[34:35], v115 offset0:2 offset1:3
	ds_read2_b32 v[36:37], v115 offset0:8 offset1:9
	ds_read2_b32 v[38:39], v115 offset0:10 offset1:11
	ds_read2_b32 v[40:41], v115 offset0:16 offset1:17
	ds_read2_b32 v[42:43], v115 offset0:18 offset1:19
	ds_read2_b32 v[44:45], v115 offset0:24 offset1:25
	ds_read2_b32 v[46:47], v115 offset0:26 offset1:27
	s_waitcnt lgkmcnt(0)
	v_mfma_f32_32x32x16_bf16 v[32:47], v[156:159], v[48:51], v[32:47]
	ds_read_b64_tr_b16 v[72:73], v231
	ds_read_b64_tr_b16 v[74:75], v231 offset:512
	ds_read_b64_tr_b16 v[76:77], v231 offset:2048
	ds_read_b64_tr_b16 v[78:79], v231 offset:2560
	ds_read_b64_tr_b16 v[220:221], v231 offset:1024
	ds_read_b64_tr_b16 v[222:223], v231 offset:1536
	ds_read_b64_tr_b16 v[224:225], v231 offset:3072
	ds_read_b64_tr_b16 v[226:227], v231 offset:3584
	v_mfma_f32_32x32x16_bf16 v[32:47], v[160:163], v[52:55], v[32:47]
	v_mfma_f32_32x32x16_bf16 v[32:47], v[164:167], v[56:59], v[32:47]
	v_mfma_f32_32x32x16_bf16 v[32:47], v[168:171], v[60:63], v[32:47]
	s_nop 11
	v_exp_f32_e32 v32, v32
	v_exp_f32_e32 v33, v33
	v_exp_f32_e32 v34, v34
	v_exp_f32_e32 v35, v35
	v_exp_f32_e32 v36, v36
	v_exp_f32_e32 v37, v37
	v_exp_f32_e32 v38, v38
	v_exp_f32_e32 v39, v39
	v_exp_f32_e32 v40, v40
	v_exp_f32_e32 v41, v41
	v_exp_f32_e32 v42, v42
	v_exp_f32_e32 v43, v43
	v_exp_f32_e32 v44, v44
	v_exp_f32_e32 v45, v45
	v_exp_f32_e32 v46, v46
	v_exp_f32_e32 v47, v47
	v_cvt_pk_bf16_f32 v64, v32, v33
	v_cvt_pk_bf16_f32 v65, v34, v35
	v_cvt_pk_bf16_f32 v66, v36, v37
	v_cvt_pk_bf16_f32 v67, v38, v39
	v_cvt_pk_bf16_f32 v68, v40, v41
	v_cvt_pk_bf16_f32 v69, v42, v43
	v_cvt_pk_bf16_f32 v70, v44, v45
	v_cvt_pk_bf16_f32 v71, v46, v47
	v_pk_add_f32 v[232:233], v[232:233], v[32:33]
	v_pk_add_f32 v[232:233], v[232:233], v[34:35]
	v_pk_add_f32 v[232:233], v[232:233], v[36:37]
	v_pk_add_f32 v[232:233], v[232:233], v[38:39]
	v_pk_add_f32 v[232:233], v[232:233], v[40:41]
	v_pk_add_f32 v[232:233], v[232:233], v[42:43]
	v_pk_add_f32 v[232:233], v[232:233], v[44:45]
	v_pk_add_f32 v[232:233], v[232:233], v[46:47]
	s_waitcnt lgkmcnt(0)
	v_mfma_f32_32x32x16_bf16 v[0:15], v[64:67], v[72:75], v[0:15]
	v_mfma_f32_32x32x16_bf16 v[16:31], v[64:67], v[76:79], v[16:31]
	v_mfma_f32_32x32x16_bf16 v[0:15], v[68:71], v[220:223], v[0:15]
	v_mfma_f32_32x32x16_bf16 v[16:31], v[68:71], v[224:227], v[16:31]
	global_load_dwordx4 v[156:159], v99, s[88:89]
	global_load_dwordx4 v[160:163], v99, s[88:89] offset:32
	global_load_dwordx4 v[164:167], v99, s[88:89] offset:64
	global_load_dwordx4 v[168:171], v99, s[88:89] offset:96
	global_load_dwordx4 v[172:175], v148, s[88:89] offset:768
	global_load_dwordx4 v[176:179], v151, s[88:89] offset:768
	global_load_dwordx4 v[180:183], v148, s[88:89] offset:832
	global_load_dwordx4 v[184:187], v151, s[88:89] offset:832
	s_add_u32 s88, s88, 0x300000
	s_addc_u32 s89, s89, 0
	s_waitcnt vmcnt(16)
	ds_write_b128 v112, v[204:207]
	ds_write_b128 v112, v[208:211] offset:1024
	ds_write_b128 v112, v[212:215] offset:2048
	ds_write_b128 v112, v[216:219] offset:3072
	ds_read2_b32 v[32:33], v115 offset0:32 offset1:33
	ds_read2_b32 v[34:35], v115 offset0:34 offset1:35
	ds_read2_b32 v[36:37], v115 offset0:40 offset1:41
	ds_read2_b32 v[38:39], v115 offset0:42 offset1:43
	ds_read2_b32 v[40:41], v115 offset0:48 offset1:49
	ds_read2_b32 v[42:43], v115 offset0:50 offset1:51
	ds_read2_b32 v[44:45], v115 offset0:56 offset1:57
	ds_read2_b32 v[46:47], v115 offset0:58 offset1:59
	s_waitcnt lgkmcnt(0)
	v_mfma_f32_32x32x16_bf16 v[32:47], v[188:191], v[48:51], v[32:47]
	ds_read_b64_tr_b16 v[72:73], v231
	ds_read_b64_tr_b16 v[74:75], v231 offset:512
	ds_read_b64_tr_b16 v[76:77], v231 offset:2048
	ds_read_b64_tr_b16 v[78:79], v231 offset:2560
	ds_read_b64_tr_b16 v[220:221], v231 offset:1024
	ds_read_b64_tr_b16 v[222:223], v231 offset:1536
	ds_read_b64_tr_b16 v[224:225], v231 offset:3072
	ds_read_b64_tr_b16 v[226:227], v231 offset:3584
	v_mfma_f32_32x32x16_bf16 v[32:47], v[192:195], v[52:55], v[32:47]
	v_mfma_f32_32x32x16_bf16 v[32:47], v[196:199], v[56:59], v[32:47]
	v_mfma_f32_32x32x16_bf16 v[32:47], v[200:203], v[60:63], v[32:47]
	s_nop 11
	v_exp_f32_e32 v32, v32
	v_exp_f32_e32 v33, v33
	v_exp_f32_e32 v34, v34
	v_exp_f32_e32 v35, v35
	v_exp_f32_e32 v36, v36
	v_exp_f32_e32 v37, v37
	v_exp_f32_e32 v38, v38
	v_exp_f32_e32 v39, v39
	v_exp_f32_e32 v40, v40
	v_exp_f32_e32 v41, v41
	v_exp_f32_e32 v42, v42
	v_exp_f32_e32 v43, v43
	v_exp_f32_e32 v44, v44
	v_exp_f32_e32 v45, v45
	v_exp_f32_e32 v46, v46
	v_exp_f32_e32 v47, v47
	v_cvt_pk_bf16_f32 v64, v32, v33
	v_cvt_pk_bf16_f32 v65, v34, v35
	v_cvt_pk_bf16_f32 v66, v36, v37
	v_cvt_pk_bf16_f32 v67, v38, v39
	v_cvt_pk_bf16_f32 v68, v40, v41
	v_cvt_pk_bf16_f32 v69, v42, v43
	v_cvt_pk_bf16_f32 v70, v44, v45
	v_cvt_pk_bf16_f32 v71, v46, v47
	v_pk_add_f32 v[232:233], v[232:233], v[32:33]
	v_pk_add_f32 v[232:233], v[232:233], v[34:35]
	v_pk_add_f32 v[232:233], v[232:233], v[36:37]
	v_pk_add_f32 v[232:233], v[232:233], v[38:39]
	v_pk_add_f32 v[232:233], v[232:233], v[40:41]
	v_pk_add_f32 v[232:233], v[232:233], v[42:43]
	v_pk_add_f32 v[232:233], v[232:233], v[44:45]
	v_pk_add_f32 v[232:233], v[232:233], v[46:47]
	s_waitcnt lgkmcnt(0)
	v_mfma_f32_32x32x16_bf16 v[0:15], v[64:67], v[72:75], v[0:15]
	v_mfma_f32_32x32x16_bf16 v[16:31], v[64:67], v[76:79], v[16:31]
	v_mfma_f32_32x32x16_bf16 v[0:15], v[68:71], v[220:223], v[0:15]
	v_mfma_f32_32x32x16_bf16 v[16:31], v[68:71], v[224:227], v[16:31]
	global_load_dwordx4 v[188:191], v99, s[88:89]
	global_load_dwordx4 v[192:195], v99, s[88:89] offset:32
	global_load_dwordx4 v[196:199], v99, s[88:89] offset:64
	global_load_dwordx4 v[200:203], v99, s[88:89] offset:96
	global_load_dwordx4 v[204:207], v148, s[88:89] offset:768
	global_load_dwordx4 v[208:211], v151, s[88:89] offset:768
	global_load_dwordx4 v[212:215], v148, s[88:89] offset:832
	global_load_dwordx4 v[216:219], v151, s[88:89] offset:832
	s_waitcnt vmcnt(16)
	ds_write_b128 v112, v[132:135]
	ds_write_b128 v112, v[136:139] offset:1024
	ds_write_b128 v112, v[140:143] offset:2048
	ds_write_b128 v112, v[144:147] offset:3072
	ds_read2_b32 v[32:33], v115 offset0:64 offset1:65
	ds_read2_b32 v[34:35], v115 offset0:66 offset1:67
	ds_read2_b32 v[36:37], v115 offset0:72 offset1:73
	ds_read2_b32 v[38:39], v115 offset0:74 offset1:75
	ds_read2_b32 v[40:41], v115 offset0:80 offset1:81
	ds_read2_b32 v[42:43], v115 offset0:82 offset1:83
	ds_read2_b32 v[44:45], v115 offset0:88 offset1:89
	ds_read2_b32 v[46:47], v115 offset0:90 offset1:91
	s_waitcnt lgkmcnt(0)
	v_mfma_f32_32x32x16_bf16 v[32:47], v[116:119], v[48:51], v[32:47]
	ds_read_b64_tr_b16 v[72:73], v231
	ds_read_b64_tr_b16 v[74:75], v231 offset:512
	ds_read_b64_tr_b16 v[76:77], v231 offset:2048
	ds_read_b64_tr_b16 v[78:79], v231 offset:2560
	ds_read_b64_tr_b16 v[220:221], v231 offset:1024
	ds_read_b64_tr_b16 v[222:223], v231 offset:1536
	ds_read_b64_tr_b16 v[224:225], v231 offset:3072
	ds_read_b64_tr_b16 v[226:227], v231 offset:3584
	v_mfma_f32_32x32x16_bf16 v[32:47], v[120:123], v[52:55], v[32:47]
	v_mfma_f32_32x32x16_bf16 v[32:47], v[124:127], v[56:59], v[32:47]
	v_mfma_f32_32x32x16_bf16 v[32:47], v[128:131], v[60:63], v[32:47]
	s_nop 11
	v_exp_f32_e32 v32, v32
	v_exp_f32_e32 v33, v33
	v_exp_f32_e32 v34, v34
	v_exp_f32_e32 v35, v35
	v_exp_f32_e32 v36, v36
	v_exp_f32_e32 v37, v37
	v_exp_f32_e32 v38, v38
	v_exp_f32_e32 v39, v39
	v_exp_f32_e32 v40, v40
	v_exp_f32_e32 v41, v41
	v_exp_f32_e32 v42, v42
	v_exp_f32_e32 v43, v43
	v_exp_f32_e32 v44, v44
	v_exp_f32_e32 v45, v45
	v_exp_f32_e32 v46, v46
	v_exp_f32_e32 v47, v47
	v_cvt_pk_bf16_f32 v64, v32, v33
	v_cvt_pk_bf16_f32 v65, v34, v35
	v_cvt_pk_bf16_f32 v66, v36, v37
	v_cvt_pk_bf16_f32 v67, v38, v39
	v_cvt_pk_bf16_f32 v68, v40, v41
	v_cvt_pk_bf16_f32 v69, v42, v43
	v_cvt_pk_bf16_f32 v70, v44, v45
	v_cvt_pk_bf16_f32 v71, v46, v47
	v_pk_add_f32 v[232:233], v[232:233], v[32:33]
	v_pk_add_f32 v[232:233], v[232:233], v[34:35]
	v_pk_add_f32 v[232:233], v[232:233], v[36:37]
	v_pk_add_f32 v[232:233], v[232:233], v[38:39]
	v_pk_add_f32 v[232:233], v[232:233], v[40:41]
	v_pk_add_f32 v[232:233], v[232:233], v[42:43]
	v_pk_add_f32 v[232:233], v[232:233], v[44:45]
	v_pk_add_f32 v[232:233], v[232:233], v[46:47]
	s_waitcnt lgkmcnt(0)
	v_mfma_f32_32x32x16_bf16 v[0:15], v[64:67], v[72:75], v[0:15]
	v_mfma_f32_32x32x16_bf16 v[16:31], v[64:67], v[76:79], v[16:31]
	v_mfma_f32_32x32x16_bf16 v[0:15], v[68:71], v[220:223], v[0:15]
	v_mfma_f32_32x32x16_bf16 v[16:31], v[68:71], v[224:227], v[16:31]
	s_waitcnt vmcnt(8)
	ds_write_b128 v112, v[172:175]
	ds_write_b128 v112, v[176:179] offset:1024
	ds_write_b128 v112, v[180:183] offset:2048
	ds_write_b128 v112, v[184:187] offset:3072
	ds_read2_b32 v[32:33], v115 offset0:96 offset1:97
	ds_read2_b32 v[34:35], v115 offset0:98 offset1:99
	ds_read2_b32 v[36:37], v115 offset0:104 offset1:105
	ds_read2_b32 v[38:39], v115 offset0:106 offset1:107
	ds_read2_b32 v[40:41], v115 offset0:112 offset1:113
	ds_read2_b32 v[42:43], v115 offset0:114 offset1:115
	ds_read2_b32 v[44:45], v115 offset0:120 offset1:121
	ds_read2_b32 v[46:47], v115 offset0:122 offset1:123
	s_waitcnt lgkmcnt(0)
; __device__ __forceinline__ int crow(int r, int hi) { return (r & 3) + 8 * (r >> 2) + 4 * hi; }
; __device__ __forceinline__ void dil_unit(LAS unsigned char* lds, bf16_t* proj, int seq, int hd, int T0, int rho) {
;     ...
;     l += __shfl_xor(l, 32);
; #pragma unroll
;     for (int rr = 0; rr < 16; ++rr) {
;         const int j = crow(rr, hi);
;         const float il = __builtin_amdgcn_rcpf(__shfl(l, j));
	v_mfma_f32_32x32x16_bf16 v[32:47], v[156:159], v[48:51], v[32:47]
	ds_read_b64_tr_b16 v[72:73], v231
	ds_read_b64_tr_b16 v[74:75], v231 offset:512
	ds_read_b64_tr_b16 v[76:77], v231 offset:2048
	ds_read_b64_tr_b16 v[78:79], v231 offset:2560
	ds_read_b64_tr_b16 v[220:221], v231 offset:1024
	ds_read_b64_tr_b16 v[222:223], v231 offset:1536
	ds_read_b64_tr_b16 v[224:225], v231 offset:3072
	ds_read_b64_tr_b16 v[226:227], v231 offset:3584
	v_mfma_f32_32x32x16_bf16 v[32:47], v[160:163], v[52:55], v[32:47]
	v_mfma_f32_32x32x16_bf16 v[32:47], v[164:167], v[56:59], v[32:47]
	v_mfma_f32_32x32x16_bf16 v[32:47], v[168:171], v[60:63], v[32:47]
	s_nop 11
	v_exp_f32_e32 v32, v32
	v_exp_f32_e32 v33, v33
	v_exp_f32_e32 v34, v34
	v_exp_f32_e32 v35, v35
	v_exp_f32_e32 v36, v36
	v_exp_f32_e32 v37, v37
	v_exp_f32_e32 v38, v38
	v_exp_f32_e32 v39, v39
	v_exp_f32_e32 v40, v40
	v_exp_f32_e32 v41, v41
	v_exp_f32_e32 v42, v42
	v_exp_f32_e32 v43, v43
	v_exp_f32_e32 v44, v44
	v_exp_f32_e32 v45, v45
	v_exp_f32_e32 v46, v46
	v_exp_f32_e32 v47, v47
	v_cvt_pk_bf16_f32 v64, v32, v33
	v_cvt_pk_bf16_f32 v65, v34, v35
	v_cvt_pk_bf16_f32 v66, v36, v37
	v_cvt_pk_bf16_f32 v67, v38, v39
	v_cvt_pk_bf16_f32 v68, v40, v41
	v_cvt_pk_bf16_f32 v69, v42, v43
	v_cvt_pk_bf16_f32 v70, v44, v45
	v_cvt_pk_bf16_f32 v71, v46, v47
	v_pk_add_f32 v[232:233], v[232:233], v[32:33]
	v_pk_add_f32 v[232:233], v[232:233], v[34:35]
	v_pk_add_f32 v[232:233], v[232:233], v[36:37]
	v_pk_add_f32 v[232:233], v[232:233], v[38:39]
	v_pk_add_f32 v[232:233], v[232:233], v[40:41]
	v_pk_add_f32 v[232:233], v[232:233], v[42:43]
	v_pk_add_f32 v[232:233], v[232:233], v[44:45]
	v_pk_add_f32 v[232:233], v[232:233], v[46:47]
	s_waitcnt lgkmcnt(0)
	v_mfma_f32_32x32x16_bf16 v[0:15], v[64:67], v[72:75], v[0:15]
	v_mfma_f32_32x32x16_bf16 v[16:31], v[64:67], v[76:79], v[16:31]
	v_mfma_f32_32x32x16_bf16 v[0:15], v[68:71], v[220:223], v[0:15]
	v_mfma_f32_32x32x16_bf16 v[16:31], v[68:71], v[224:227], v[16:31]
	s_waitcnt vmcnt(0)
	ds_write_b128 v112, v[204:207]
	ds_write_b128 v112, v[208:211] offset:1024
	ds_write_b128 v112, v[212:215] offset:2048
	ds_write_b128 v112, v[216:219] offset:3072
	ds_read2_b32 v[32:33], v115 offset0:128 offset1:129
	ds_read2_b32 v[34:35], v115 offset0:130 offset1:131
	ds_read2_b32 v[36:37], v115 offset0:136 offset1:137
	ds_read2_b32 v[38:39], v115 offset0:138 offset1:139
	ds_read2_b32 v[40:41], v115 offset0:144 offset1:145
	ds_read2_b32 v[42:43], v115 offset0:146 offset1:147
	ds_read2_b32 v[44:45], v115 offset0:152 offset1:153
	ds_read2_b32 v[46:47], v115 offset0:154 offset1:155
	s_waitcnt lgkmcnt(0)
	v_mfma_f32_32x32x16_bf16 v[32:47], v[188:191], v[48:51], v[32:47]
	ds_read_b64_tr_b16 v[72:73], v231
	ds_read_b64_tr_b16 v[74:75], v231 offset:512
	ds_read_b64_tr_b16 v[76:77], v231 offset:2048
	ds_read_b64_tr_b16 v[78:79], v231 offset:2560
	ds_read_b64_tr_b16 v[220:221], v231 offset:1024
	ds_read_b64_tr_b16 v[222:223], v231 offset:1536
	ds_read_b64_tr_b16 v[224:225], v231 offset:3072
	ds_read_b64_tr_b16 v[226:227], v231 offset:3584
	v_mfma_f32_32x32x16_bf16 v[32:47], v[192:195], v[52:55], v[32:47]
	v_mfma_f32_32x32x16_bf16 v[32:47], v[196:199], v[56:59], v[32:47]
	v_mfma_f32_32x32x16_bf16 v[32:47], v[200:203], v[60:63], v[32:47]
	s_nop 11
	v_exp_f32_e32 v32, v32
	v_exp_f32_e32 v33, v33
	v_exp_f32_e32 v34, v34
	v_exp_f32_e32 v35, v35
	v_exp_f32_e32 v36, v36
	v_exp_f32_e32 v37, v37
	v_exp_f32_e32 v38, v38
	v_exp_f32_e32 v39, v39
	v_exp_f32_e32 v40, v40
	v_exp_f32_e32 v41, v41
	v_exp_f32_e32 v42, v42
	v_exp_f32_e32 v43, v43
	v_exp_f32_e32 v44, v44
	v_exp_f32_e32 v45, v45
	v_exp_f32_e32 v46, v46
	v_exp_f32_e32 v47, v47
	v_cvt_pk_bf16_f32 v64, v32, v33
	v_cvt_pk_bf16_f32 v65, v34, v35
	v_cvt_pk_bf16_f32 v66, v36, v37
	v_cvt_pk_bf16_f32 v67, v38, v39
	v_cvt_pk_bf16_f32 v68, v40, v41
	v_cvt_pk_bf16_f32 v69, v42, v43
	v_cvt_pk_bf16_f32 v70, v44, v45
	v_cvt_pk_bf16_f32 v71, v46, v47
	v_pk_add_f32 v[232:233], v[232:233], v[32:33]
	v_pk_add_f32 v[232:233], v[232:233], v[34:35]
	v_pk_add_f32 v[232:233], v[232:233], v[36:37]
	v_pk_add_f32 v[232:233], v[232:233], v[38:39]
	v_pk_add_f32 v[232:233], v[232:233], v[40:41]
	v_pk_add_f32 v[232:233], v[232:233], v[42:43]
	v_pk_add_f32 v[232:233], v[232:233], v[44:45]
	v_pk_add_f32 v[232:233], v[232:233], v[46:47]
	s_waitcnt lgkmcnt(0)
	v_mfma_f32_32x32x16_bf16 v[0:15], v[64:67], v[72:75], v[0:15]
	v_mfma_f32_32x32x16_bf16 v[16:31], v[64:67], v[76:79], v[16:31]
	v_mfma_f32_32x32x16_bf16 v[0:15], v[68:71], v[220:223], v[0:15]
	v_mfma_f32_32x32x16_bf16 v[16:31], v[68:71], v[224:227], v[16:31]
	v_add_f32_e32 v113, v232, v233
	v_or_b32_e32 v114, 1, v107
	v_or_b32_e32 v97, 2, v107
	v_or_b32_e32 v96, 3, v107
	v_or_b32_e32 v95, 8, v107
	v_or_b32_e32 v94, 9, v107
	v_or_b32_e32 v93, 10, v107
	v_or_b32_e32 v92, 11, v107
	v_or_b32_e32 v91, 16, v107
	v_or_b32_e32 v90, 17, v107
	v_or_b32_e32 v89, 18, v107
	v_or_b32_e32 v88, 19, v107
	v_or_b32_e32 v87, 24, v107
	v_or_b32_e32 v86, 25, v107
	v_or_b32_e32 v85, 26, v107
	v_or_b32_e32 v84, 27, v107
	s_nop 11
	s_branch .LBB0_553

; #define LAS __attribute__((address_space(3)))
; __device__ __forceinline__ void attn_setup(const float* par, int l, LAS unsigned char* lds) {
;     ...
;     LAS float* tl = (LAS float*)(lds + TDIL_OFF);
;     for (int i = tid; i < 6 * TDIL_STRIDE; i += 512) { const int hd = i / TDIL_STRIDE, j = i % TDIL_STRIDE; const int b = j < 1152 ? 0 : (j < 1560 ? 1 : 2), jj = j - (b == 0 ? 0 : (b == 1 ? 1152 : 1560));
;         const int r = (b == 0) ? 1 : (b == 1 ? 4 : 16), f = 16 / r, mm = jj - (64 + 31 * f);
;         tl[i] = (mm >= -64 && mm <= 64) ? (rb[rel_bucket(r * mm) * 10 + 4 + hd] - misc[4 + hd]) * LOG2E : -1e30f; }
; __device__ __forceinline__ void attn_phase(unsigned char* ws, int l, LAS unsigned char* lds, int G) {
;     ...
;     __syncthreads();
;     for (int bu = vb; bu < 1152; bu += G) {
.LBB0_1263:
	s_cmpk_gt_i32 s60, 0x47f
	s_waitcnt lgkmcnt(0)
	s_barrier
	s_cbranch_scc1 .LBB0_1273
	v_lshlrev_b32_e32 v200, 2, v154
	v_add_u32_e32 v200, 0x15c00, v200
	v_add_u32_e32 v201, 0, v154
	v_lshrrev_b32_e32 v204, 4, v201
	v_add_u32_e32 v201, v201, v204
	v_lshlrev_b32_e32 v201, 2, v201
	v_add_u32_e32 v201, 0x8000, v201
	v_add_u32_e32 v202, 512, v154
	v_lshrrev_b32_e32 v204, 4, v202
	v_add_u32_e32 v202, v202, v204
	v_lshlrev_b32_e32 v202, 2, v202
	v_add_u32_e32 v202, 0x8000, v202
	v_add_u32_e32 v203, 1024, v154
	v_lshrrev_b32_e32 v204, 4, v203
	v_add_u32_e32 v203, v203, v204
	v_lshlrev_b32_e32 v203, 2, v203
	v_add_u32_e32 v203, 0x8000, v203
	v_readfirstlane_b32 s82, v154
	s_nop 3
	s_cmp_lt_u32 s82, 128
	s_cbranch_scc0 .Lpt1_two
	ds_read_b32 v205, v200 offset:0
	ds_read_b32 v206, v200 offset:2048
	ds_read_b32 v207, v200 offset:4096
	ds_read_b32 v208, v200 offset:7168
	ds_read_b32 v209, v200 offset:9216
	ds_read_b32 v210, v200 offset:11264
	ds_read_b32 v211, v200 offset:14336
	ds_read_b32 v212, v200 offset:16384
	ds_read_b32 v213, v200 offset:18432
	ds_read_b32 v214, v200 offset:21504
	ds_read_b32 v215, v200 offset:23552
	ds_read_b32 v216, v200 offset:25600
	ds_read_b32 v217, v200 offset:28672
	ds_read_b32 v218, v200 offset:30720
	ds_read_b32 v219, v200 offset:32768
	ds_read_b32 v220, v200 offset:35840
	ds_read_b32 v221, v200 offset:37888
	ds_read_b32 v222, v200 offset:39936
	s_waitcnt lgkmcnt(0)
	ds_write_b32 v201, v205 offset:0
	ds_write_b32 v202, v206 offset:0
	ds_write_b32 v203, v207 offset:0
	ds_write_b32 v201, v208 offset:4896
	ds_write_b32 v202, v209 offset:4896
	ds_write_b32 v203, v210 offset:4896
	ds_write_b32 v201, v211 offset:9792
	ds_write_b32 v202, v212 offset:9792
	ds_write_b32 v203, v213 offset:9792
	ds_write_b32 v201, v214 offset:14688
	ds_write_b32 v202, v215 offset:14688
	ds_write_b32 v203, v216 offset:14688
	ds_write_b32 v201, v217 offset:19584
	ds_write_b32 v202, v218 offset:19584
	ds_write_b32 v203, v219 offset:19584
	ds_write_b32 v201, v220 offset:24480
	ds_write_b32 v202, v221 offset:24480
	ds_write_b32 v203, v222 offset:24480
	s_branch .Lpt1_done

; __device__ __forceinline__ void attn_phase(unsigned char* ws, int l, LAS unsigned char* lds, int G) {
;     ...
;     for (int bu = vb; bu < 1152; bu += G) {
;         const int sh = bu >> 6, rem = bu & 63, T0 = (rem >> 1) * 512, rho = (rem & 1) * 8 + wid;
;         dil_unit(lds, proj, sh / 6, sh % 6, T0, rho);
.Lpt1_done:
	s_waitcnt lgkmcnt(0)
	s_barrier
	s_lshr_b32 s61, s22, 6
	s_movk_i32 s62, 0x1800
	v_mov_b32_e32 v81, 0
	s_mov_b64 s[46:47], 0x1200
	s_movk_i32 s63, 0x1000
	s_mov_b64 s[48:49], 0x1500
	s_movk_i32 s64, 0x480
	s_movk_i32 s65, 0xbc
	s_movk_i32 s66, 0x4000
	v_mbcnt_hi_u32_b32 v102, -1, v155
	s_branch .LBB0_1266

; #define LAS __attribute__((address_space(3)))
; #define GAS __attribute__((address_space(1)))
; __device__ __forceinline__ void dil_unit(LAS unsigned char* lds, bf16_t* proj, int seq, int hd, int T0, int rho) {
;     int tid_ = threadIdx.x; asm volatile("" : "+v"(tid_));
;     const int tid = tid_, lane = tid & 63, r32 = lane & 31, hi = lane >> 5, wid = __builtin_amdgcn_readfirstlane(tid >> 6);
;     bf16_t* base = proj + (size_t)seq * SEQ * NIN;
;     LAS unsigned char* wbuf = lds + wid * 4096;
;     const LAS unsigned char* vp = wbuf + ((lane >> 4) & 1) * 32 + (lane & 3) * 8 + (4 * hi + ((lane & 15) >> 2)) * 64;
;     const int P0 = T0 + rho;
;     bf16x8 qr[4];
; #pragma unroll
;     for (int ks = 0; ks < 4; ++ks) qr[ks] = *(const GAS bf16x8*)(base + (size_t)(P0 + 16 * r32) * NIN + PC_LQ + hd * 64 + 16 * ks + 8 * hi);
;     f32x16 o0 = {}, o1 = {}; float l = 0.f;
;     const bool bound = (T0 < 1024) || (T0 >= 15360);
.LBB0_1266:
	s_lshr_b32 s82, s60, 8
	s_mul_i32 s82, s82, 13
	s_add_i32 s82, s82, s60
	s_ashr_i32 s4, s60, 6
	s_mul_hi_i32 s9, s4, 0x2aaaaaab
	s_lshl_b32 s5, s82, 8
	s_lshr_b32 s10, s9, 31
	s_and_b32 s8, s5, 0x3e00
	s_lshl_b32 s5, s82, 3
	s_add_i32 s9, s9, s10
	s_and_b32 s5, s5, 8
	s_mul_i32 s10, s9, 6
	s_add_i32 s5, s5, s61
	s_sub_i32 s10, s4, s10
	s_mul_hi_i32 s4, s9, 0x6000000
	s_mul_i32 s9, s9, 0x6000000
	v_mov_b32_e32 v2, v154
	s_add_u32 s52, s44, s9
	s_addc_u32 s53, s45, s4
	v_and_b32_e32 v105, 31, v2
	s_add_i32 s67, s5, s8
	v_lshl_add_u32 v3, v105, 4, s67
	v_mov_b64_e32 v[0:1], s[52:53]
	s_lshl_b32 s54, s10, 6
	v_bfe_u32 v106, v2, 5, 1
	v_mad_u64_u32 v[0:1], s[4:5], v3, s62, v[0:1]
	s_ashr_i32 s55, s54, 31
	v_lshl_add_u64 v[0:1], s[54:55], 1, v[0:1]
	v_lshlrev_b32_e32 v80, 4, v106
	v_lshl_add_u64 v[0:1], v[0:1], 0, v[80:81]
	global_load_dwordx4 v[48:51], v[0:1], off offset:1280
	global_load_dwordx4 v[52:55], v[0:1], off offset:1312
	global_load_dwordx4 v[56:59], v[0:1], off offset:1344
	global_load_dwordx4 v[60:63], v[0:1], off offset:1376
	v_readfirstlane_b32 s4, v2
	s_lshl_b32 s4, s4, 6
	s_and_b32 s4, s4, 0xfffff000
	v_lshlrev_b32_e32 v0, 1, v2
	v_lshlrev_b32_e32 v104, 3, v2
	v_lshlrev_b32_e32 v107, 2, v106
	v_lshrrev_b32_e32 v1, 2, v2
	v_and_b32_e32 v103, 63, v2
	v_and_b32_e32 v0, 32, v0
	v_and_b32_e32 v98, 24, v104
	v_and_or_b32 v1, v1, 3, v107
	s_add_i32 s69, s4, 0
	v_lshlrev_b32_e32 v108, 6, v1
	v_lshlrev_b32_e32 v1, 3, v106
	v_add3_u32 v109, s69, v0, v98
	s_addk_i32 s8, 0xc400
	v_lshrrev_b32_e32 v110, 2, v103
	v_lshlrev_b32_e32 v0, 4, v103
	s_mov_b64 s[4:5], -1
	s_cmp_gt_u32 s8, 0xffffc7ff
	v_lshlrev_b32_e32 v100, 1, v98
	s_mul_i32 s8, s10, 0x1c00
	v_lshlrev_b32_e32 v82, 1, v1
	v_or_b32_e32 v111, 16, v110
	v_add_u32_e32 v112, s69, v0
	s_cbranch_scc0 .LBB0_1270
	s_movk_i32 s100, 0x1800
	s_add_i32 s101, s8, 0x15c00
	s_lshl_b32 s90, s54, 1
	s_add_u32 s82, s52, s90
	s_addc_u32 s83, s53, 0
	s_add_u32 s82, s82, 0x1200
	s_addc_u32 s83, s83, 0
	s_sub_i32 s90, s67, 64
	s_mul_i32 s90, s90, 0x1800
	s_add_u32 s84, s82, s90
	s_addc_u32 s85, s83, 0
	s_sub_i32 s90, s67, 256
	s_mul_i32 s90, s90, 0x1800
	s_add_u32 s86, s82, s90
	s_addc_u32 s87, s83, 0
	s_sub_i32 s90, s67, 1024
	s_mul_i32 s90, s90, 0x1800
	s_add_u32 s88, s82, s90
	s_addc_u32 s89, s83, 0
	v_lshlrev_b32_e32 v153, 1, v98
	v_mad_u32_u24 v80, v105, s100, v82
	v_mad_u32_u24 v100, v110, s100, v153
	v_add_u32_e32 v149, 0x18000, v100
	v_lshlrev_b32_e32 v83, 2, v105
	v_mad_u32_u24 v83, v83, s100, v82
	v_lshlrev_b32_e32 v101, 2, v110
	v_mad_u32_u24 v101, v101, s100, v153
	v_add_u32_e32 v150, 0x60000, v101
	v_lshlrev_b32_e32 v99, 4, v105
	v_mad_u32_u24 v99, v99, s100, v82
	v_lshlrev_b32_e32 v148, 4, v110
	v_mad_u32_u24 v148, v148, s100, v153
	v_add_u32_e32 v151, 0x180000, v148
	v_mul_u32_u24_e32 v228, 17, v105
	v_sub_u32_e32 v228, v107, v228
	s_mul_i32 s90, s54, 153
	s_lshr_b32 s90, s90, 1
	s_add_i32 s90, s90, 34876
	v_lshl_add_u32 v228, v228, 2, s90
	v_lshlrev_b32_e32 v229, 2, v105
	v_sub_u32_e32 v229, v107, v229
	s_add_i32 s90, s101, 5104
	v_lshl_add_u32 v229, v229, 2, s90
	v_sub_u32_e32 v230, v107, v105
	s_add_i32 s90, s101, 6364
	v_lshl_add_u32 v230, v230, 2, s90
	v_add_u32_e32 v231, v109, v108
	v_mov_b64_e32 v[232:233], 0
	v_mov_b64_e32 v[0:1], 0
	v_mov_b64_e32 v[2:3], 0
	v_mov_b64_e32 v[4:5], 0
	v_mov_b64_e32 v[6:7], 0
	v_mov_b64_e32 v[8:9], 0
	v_mov_b64_e32 v[10:11], 0
	v_mov_b64_e32 v[12:13], 0
	v_mov_b64_e32 v[14:15], 0
	v_mov_b64_e32 v[16:17], 0
	v_mov_b64_e32 v[18:19], 0
	v_mov_b64_e32 v[20:21], 0
	v_mov_b64_e32 v[22:23], 0
	v_mov_b64_e32 v[24:25], 0
	v_mov_b64_e32 v[26:27], 0
	v_mov_b64_e32 v[28:29], 0
	v_mov_b64_e32 v[30:31], 0
	global_load_dwordx4 v[116:119], v80, s[84:85]
	global_load_dwordx4 v[120:123], v80, s[84:85] offset:32
	global_load_dwordx4 v[124:127], v80, s[84:85] offset:64
	global_load_dwordx4 v[128:131], v80, s[84:85] offset:96
	global_load_dwordx4 v[132:135], v100, s[84:85] offset:768
	global_load_dwordx4 v[136:139], v149, s[84:85] offset:768
	global_load_dwordx4 v[140:143], v100, s[84:85] offset:832
	global_load_dwordx4 v[144:147], v149, s[84:85] offset:832
	s_add_u32 s84, s84, 0x30000
	s_addc_u32 s85, s85, 0
	global_load_dwordx4 v[156:159], v80, s[84:85]
	global_load_dwordx4 v[160:163], v80, s[84:85] offset:32
	global_load_dwordx4 v[164:167], v80, s[84:85] offset:64
	global_load_dwordx4 v[168:171], v80, s[84:85] offset:96
	global_load_dwordx4 v[172:175], v100, s[84:85] offset:768
	global_load_dwordx4 v[176:179], v149, s[84:85] offset:768
	global_load_dwordx4 v[180:183], v100, s[84:85] offset:832
	global_load_dwordx4 v[184:187], v149, s[84:85] offset:832
	s_add_u32 s84, s84, 0x30000
	s_addc_u32 s85, s85, 0
	global_load_dwordx4 v[188:191], v80, s[84:85]
	global_load_dwordx4 v[192:195], v80, s[84:85] offset:32
	global_load_dwordx4 v[196:199], v80, s[84:85] offset:64
	global_load_dwordx4 v[200:203], v80, s[84:85] offset:96
	global_load_dwordx4 v[204:207], v100, s[84:85] offset:768
	global_load_dwordx4 v[208:211], v149, s[84:85] offset:768
	global_load_dwordx4 v[212:215], v100, s[84:85] offset:832
	global_load_dwordx4 v[216:219], v149, s[84:85] offset:832
	s_add_u32 s84, s84, 0x30000
	s_addc_u32 s85, s85, 0
	s_waitcnt vmcnt(16)
	ds_write_b128 v112, v[132:135]
	ds_write_b128 v112, v[136:139] offset:1024
	ds_write_b128 v112, v[140:143] offset:2048
	ds_write_b128 v112, v[144:147] offset:3072
	v_mov_b32_e32 v115, v228
	ds_read2_b32 v[32:33], v115 offset0:0 offset1:1
	ds_read2_b32 v[34:35], v115 offset0:2 offset1:3
	ds_read2_b32 v[36:37], v115 offset0:8 offset1:9
	ds_read2_b32 v[38:39], v115 offset0:10 offset1:11
	ds_read2_b32 v[40:41], v115 offset0:17 offset1:18
	ds_read2_b32 v[42:43], v115 offset0:19 offset1:20
	ds_read2_b32 v[44:45], v115 offset0:25 offset1:26
	ds_read2_b32 v[46:47], v115 offset0:27 offset1:28
	s_waitcnt lgkmcnt(0)
	v_mfma_f32_32x32x16_bf16 v[32:47], v[116:119], v[48:51], v[32:47]
	ds_read_b64_tr_b16 v[72:73], v231
	ds_read_b64_tr_b16 v[74:75], v231 offset:512
	ds_read_b64_tr_b16 v[76:77], v231 offset:2048
	ds_read_b64_tr_b16 v[78:79], v231 offset:2560
	ds_read_b64_tr_b16 v[220:221], v231 offset:1024
	ds_read_b64_tr_b16 v[222:223], v231 offset:1536
	ds_read_b64_tr_b16 v[224:225], v231 offset:3072
	ds_read_b64_tr_b16 v[226:227], v231 offset:3584
	v_mfma_f32_32x32x16_bf16 v[32:47], v[120:123], v[52:55], v[32:47]
	v_mfma_f32_32x32x16_bf16 v[32:47], v[124:127], v[56:59], v[32:47]
	v_mfma_f32_32x32x16_bf16 v[32:47], v[128:131], v[60:63], v[32:47]
	s_nop 11
	v_exp_f32_e32 v32, v32
	v_exp_f32_e32 v33, v33
	v_exp_f32_e32 v34, v34
	v_exp_f32_e32 v35, v35
	v_exp_f32_e32 v36, v36
	v_exp_f32_e32 v37, v37
	v_exp_f32_e32 v38, v38
	v_exp_f32_e32 v39, v39
	v_exp_f32_e32 v40, v40
	v_exp_f32_e32 v41, v41
	v_exp_f32_e32 v42, v42
	v_exp_f32_e32 v43, v43
	v_exp_f32_e32 v44, v44
	v_exp_f32_e32 v45, v45
	v_exp_f32_e32 v46, v46
	v_exp_f32_e32 v47, v47
	v_cvt_pk_bf16_f32 v64, v32, v33
	v_cvt_pk_bf16_f32 v65, v34, v35
	v_cvt_pk_bf16_f32 v66, v36, v37
	v_cvt_pk_bf16_f32 v67, v38, v39
	v_cvt_pk_bf16_f32 v68, v40, v41
	v_cvt_pk_bf16_f32 v69, v42, v43
	v_cvt_pk_bf16_f32 v70, v44, v45
	v_cvt_pk_bf16_f32 v71, v46, v47
	v_pk_add_f32 v[232:233], v[232:233], v[32:33]
	v_pk_add_f32 v[232:233], v[232:233], v[34:35]
	v_pk_add_f32 v[232:233], v[232:233], v[36:37]
	v_pk_add_f32 v[232:233], v[232:233], v[38:39]
	v_pk_add_f32 v[232:233], v[232:233], v[40:41]
	v_pk_add_f32 v[232:233], v[232:233], v[42:43]
	v_pk_add_f32 v[232:233], v[232:233], v[44:45]
	v_pk_add_f32 v[232:233], v[232:233], v[46:47]
	s_waitcnt lgkmcnt(0)
	v_mfma_f32_32x32x16_bf16 v[0:15], v[64:67], v[72:75], v[0:15]
	v_mfma_f32_32x32x16_bf16 v[16:31], v[64:67], v[76:79], v[16:31]
	v_mfma_f32_32x32x16_bf16 v[0:15], v[68:71], v[220:223], v[0:15]
	v_mfma_f32_32x32x16_bf16 v[16:31], v[68:71], v[224:227], v[16:31]
	global_load_dwordx4 v[116:119], v80, s[84:85]
	global_load_dwordx4 v[120:123], v80, s[84:85] offset:32
	global_load_dwordx4 v[124:127], v80, s[84:85] offset:64
	global_load_dwordx4 v[128:131], v80, s[84:85] offset:96
	global_load_dwordx4 v[132:135], v100, s[84:85] offset:768
	global_load_dwordx4 v[136:139], v149, s[84:85] offset:768
	global_load_dwordx4 v[140:143], v100, s[84:85] offset:832
	global_load_dwordx4 v[144:147], v149, s[84:85] offset:832
	s_add_u32 s84, s84, 0x30000
	s_addc_u32 s85, s85, 0
	s_waitcnt vmcnt(16)
	ds_write_b128 v112, v[172:175]
	ds_write_b128 v112, v[176:179] offset:1024
	ds_write_b128 v112, v[180:183] offset:2048
	ds_write_b128 v112, v[184:187] offset:3072
	ds_read2_b32 v[32:33], v115 offset0:34 offset1:35
	ds_read2_b32 v[34:35], v115 offset0:36 offset1:37
	ds_read2_b32 v[36:37], v115 offset0:42 offset1:43
	ds_read2_b32 v[38:39], v115 offset0:44 offset1:45
	ds_read2_b32 v[40:41], v115 offset0:51 offset1:52
	ds_read2_b32 v[42:43], v115 offset0:53 offset1:54
	ds_read2_b32 v[44:45], v115 offset0:59 offset1:60
	ds_read2_b32 v[46:47], v115 offset0:61 offset1:62
	s_waitcnt lgkmcnt(0)
	v_mfma_f32_32x32x16_bf16 v[32:47], v[156:159], v[48:51], v[32:47]
	ds_read_b64_tr_b16 v[72:73], v231
	ds_read_b64_tr_b16 v[74:75], v231 offset:512
	ds_read_b64_tr_b16 v[76:77], v231 offset:2048
	ds_read_b64_tr_b16 v[78:79], v231 offset:2560
	ds_read_b64_tr_b16 v[220:221], v231 offset:1024
	ds_read_b64_tr_b16 v[222:223], v231 offset:1536
	ds_read_b64_tr_b16 v[224:225], v231 offset:3072
	ds_read_b64_tr_b16 v[226:227], v231 offset:3584
	v_mfma_f32_32x32x16_bf16 v[32:47], v[160:163], v[52:55], v[32:47]
	v_mfma_f32_32x32x16_bf16 v[32:47], v[164:167], v[56:59], v[32:47]
	v_mfma_f32_32x32x16_bf16 v[32:47], v[168:171], v[60:63], v[32:47]
	s_nop 11
	v_exp_f32_e32 v32, v32
	v_exp_f32_e32 v33, v33
	v_exp_f32_e32 v34, v34
	v_exp_f32_e32 v35, v35
	v_exp_f32_e32 v36, v36
	v_exp_f32_e32 v37, v37
	v_exp_f32_e32 v38, v38
	v_exp_f32_e32 v39, v39
	v_exp_f32_e32 v40, v40
	v_exp_f32_e32 v41, v41
	v_exp_f32_e32 v42, v42
	v_exp_f32_e32 v43, v43
	v_exp_f32_e32 v44, v44
	v_exp_f32_e32 v45, v45
	v_exp_f32_e32 v46, v46
	v_exp_f32_e32 v47, v47
	v_cvt_pk_bf16_f32 v64, v32, v33
	v_cvt_pk_bf16_f32 v65, v34, v35
	v_cvt_pk_bf16_f32 v66, v36, v37
	v_cvt_pk_bf16_f32 v67, v38, v39
	v_cvt_pk_bf16_f32 v68, v40, v41
	v_cvt_pk_bf16_f32 v69, v42, v43
	v_cvt_pk_bf16_f32 v70, v44, v45
	v_cvt_pk_bf16_f32 v71, v46, v47
	v_pk_add_f32 v[232:233], v[232:233], v[32:33]
	v_pk_add_f32 v[232:233], v[232:233], v[34:35]
	v_pk_add_f32 v[232:233], v[232:233], v[36:37]
	v_pk_add_f32 v[232:233], v[232:233], v[38:39]
	v_pk_add_f32 v[232:233], v[232:233], v[40:41]
	v_pk_add_f32 v[232:233], v[232:233], v[42:43]
	v_pk_add_f32 v[232:233], v[232:233], v[44:45]
	v_pk_add_f32 v[232:233], v[232:233], v[46:47]
	s_waitcnt lgkmcnt(0)
	v_mfma_f32_32x32x16_bf16 v[0:15], v[64:67], v[72:75], v[0:15]
	v_mfma_f32_32x32x16_bf16 v[16:31], v[64:67], v[76:79], v[16:31]
	v_mfma_f32_32x32x16_bf16 v[0:15], v[68:71], v[220:223], v[0:15]
	v_mfma_f32_32x32x16_bf16 v[16:31], v[68:71], v[224:227], v[16:31]
	global_load_dwordx4 v[156:159], v80, s[84:85]
	global_load_dwordx4 v[160:163], v80, s[84:85] offset:32
	global_load_dwordx4 v[164:167], v80, s[84:85] offset:64
	global_load_dwordx4 v[168:171], v80, s[84:85] offset:96
	global_load_dwordx4 v[172:175], v100, s[84:85] offset:768
	global_load_dwordx4 v[176:179], v149, s[84:85] offset:768
	global_load_dwordx4 v[180:183], v100, s[84:85] offset:832
	global_load_dwordx4 v[184:187], v149, s[84:85] offset:832
	s_add_u32 s84, s84, 0x30000
	s_addc_u32 s85, s85, 0
	s_waitcnt vmcnt(16)
	ds_write_b128 v112, v[204:207]
	ds_write_b128 v112, v[208:211] offset:1024
	ds_write_b128 v112, v[212:215] offset:2048
	ds_write_b128 v112, v[216:219] offset:3072
	ds_read2_b32 v[32:33], v115 offset0:68 offset1:69
	ds_read2_b32 v[34:35], v115 offset0:70 offset1:71
	ds_read2_b32 v[36:37], v115 offset0:76 offset1:77
	ds_read2_b32 v[38:39], v115 offset0:78 offset1:79
	ds_read2_b32 v[40:41], v115 offset0:85 offset1:86
	ds_read2_b32 v[42:43], v115 offset0:87 offset1:88
	ds_read2_b32 v[44:45], v115 offset0:93 offset1:94
	ds_read2_b32 v[46:47], v115 offset0:95 offset1:96
	s_waitcnt lgkmcnt(0)
	v_mfma_f32_32x32x16_bf16 v[32:47], v[188:191], v[48:51], v[32:47]
	ds_read_b64_tr_b16 v[72:73], v231
	ds_read_b64_tr_b16 v[74:75], v231 offset:512
	ds_read_b64_tr_b16 v[76:77], v231 offset:2048
	ds_read_b64_tr_b16 v[78:79], v231 offset:2560
	ds_read_b64_tr_b16 v[220:221], v231 offset:1024
	ds_read_b64_tr_b16 v[222:223], v231 offset:1536
	ds_read_b64_tr_b16 v[224:225], v231 offset:3072
	ds_read_b64_tr_b16 v[226:227], v231 offset:3584
	v_mfma_f32_32x32x16_bf16 v[32:47], v[192:195], v[52:55], v[32:47]
	v_mfma_f32_32x32x16_bf16 v[32:47], v[196:199], v[56:59], v[32:47]
	v_mfma_f32_32x32x16_bf16 v[32:47], v[200:203], v[60:63], v[32:47]
	s_nop 11
	v_exp_f32_e32 v32, v32
	v_exp_f32_e32 v33, v33
	v_exp_f32_e32 v34, v34
	v_exp_f32_e32 v35, v35
	v_exp_f32_e32 v36, v36
	v_exp_f32_e32 v37, v37
	v_exp_f32_e32 v38, v38
	v_exp_f32_e32 v39, v39
	v_exp_f32_e32 v40, v40
	v_exp_f32_e32 v41, v41
	v_exp_f32_e32 v42, v42
	v_exp_f32_e32 v43, v43
	v_exp_f32_e32 v44, v44
	v_exp_f32_e32 v45, v45
	v_exp_f32_e32 v46, v46
	v_exp_f32_e32 v47, v47
	v_cvt_pk_bf16_f32 v64, v32, v33
	v_cvt_pk_bf16_f32 v65, v34, v35
	v_cvt_pk_bf16_f32 v66, v36, v37
	v_cvt_pk_bf16_f32 v67, v38, v39
	v_cvt_pk_bf16_f32 v68, v40, v41
	v_cvt_pk_bf16_f32 v69, v42, v43
	v_cvt_pk_bf16_f32 v70, v44, v45
	v_cvt_pk_bf16_f32 v71, v46, v47
	v_pk_add_f32 v[232:233], v[232:233], v[32:33]
	v_pk_add_f32 v[232:233], v[232:233], v[34:35]
	v_pk_add_f32 v[232:233], v[232:233], v[36:37]
	v_pk_add_f32 v[232:233], v[232:233], v[38:39]
	v_pk_add_f32 v[232:233], v[232:233], v[40:41]
	v_pk_add_f32 v[232:233], v[232:233], v[42:43]
	v_pk_add_f32 v[232:233], v[232:233], v[44:45]
	v_pk_add_f32 v[232:233], v[232:233], v[46:47]
	s_waitcnt lgkmcnt(0)
	v_mfma_f32_32x32x16_bf16 v[0:15], v[64:67], v[72:75], v[0:15]
	v_mfma_f32_32x32x16_bf16 v[16:31], v[64:67], v[76:79], v[16:31]
	v_mfma_f32_32x32x16_bf16 v[0:15], v[68:71], v[220:223], v[0:15]
	v_mfma_f32_32x32x16_bf16 v[16:31], v[68:71], v[224:227], v[16:31]
	global_load_dwordx4 v[188:191], v80, s[84:85]
	global_load_dwordx4 v[192:195], v80, s[84:85] offset:32
	global_load_dwordx4 v[196:199], v80, s[84:85] offset:64
	global_load_dwordx4 v[200:203], v80, s[84:85] offset:96
	global_load_dwordx4 v[204:207], v100, s[84:85] offset:768
	global_load_dwordx4 v[208:211], v149, s[84:85] offset:768
	global_load_dwordx4 v[212:215], v100, s[84:85] offset:832
	global_load_dwordx4 v[216:219], v149, s[84:85] offset:832
	s_add_u32 s84, s84, 0x30000
	s_addc_u32 s85, s85, 0
	s_waitcnt vmcnt(16)
	ds_write_b128 v112, v[132:135]
	ds_write_b128 v112, v[136:139] offset:1024
	ds_write_b128 v112, v[140:143] offset:2048
	ds_write_b128 v112, v[144:147] offset:3072
	ds_read2_b32 v[32:33], v115 offset0:102 offset1:103
	ds_read2_b32 v[34:35], v115 offset0:104 offset1:105
	ds_read2_b32 v[36:37], v115 offset0:110 offset1:111
	ds_read2_b32 v[38:39], v115 offset0:112 offset1:113
	ds_read2_b32 v[40:41], v115 offset0:119 offset1:120
	ds_read2_b32 v[42:43], v115 offset0:121 offset1:122
	ds_read2_b32 v[44:45], v115 offset0:127 offset1:128
	ds_read2_b32 v[46:47], v115 offset0:129 offset1:130
	s_waitcnt lgkmcnt(0)
	v_mfma_f32_32x32x16_bf16 v[32:47], v[116:119], v[48:51], v[32:47]
	ds_read_b64_tr_b16 v[72:73], v231
	ds_read_b64_tr_b16 v[74:75], v231 offset:512
	ds_read_b64_tr_b16 v[76:77], v231 offset:2048
	ds_read_b64_tr_b16 v[78:79], v231 offset:2560
	ds_read_b64_tr_b16 v[220:221], v231 offset:1024
	ds_read_b64_tr_b16 v[222:223], v231 offset:1536
	ds_read_b64_tr_b16 v[224:225], v231 offset:3072
	ds_read_b64_tr_b16 v[226:227], v231 offset:3584
	v_mfma_f32_32x32x16_bf16 v[32:47], v[120:123], v[52:55], v[32:47]
	v_mfma_f32_32x32x16_bf16 v[32:47], v[124:127], v[56:59], v[32:47]
	v_mfma_f32_32x32x16_bf16 v[32:47], v[128:131], v[60:63], v[32:47]
	s_nop 11
	v_exp_f32_e32 v32, v32
	v_exp_f32_e32 v33, v33
	v_exp_f32_e32 v34, v34
	v_exp_f32_e32 v35, v35
	v_exp_f32_e32 v36, v36
	v_exp_f32_e32 v37, v37
	v_exp_f32_e32 v38, v38
	v_exp_f32_e32 v39, v39
	v_exp_f32_e32 v40, v40
	v_exp_f32_e32 v41, v41
	v_exp_f32_e32 v42, v42
	v_exp_f32_e32 v43, v43
	v_exp_f32_e32 v44, v44
	v_exp_f32_e32 v45, v45
	v_exp_f32_e32 v46, v46
	v_exp_f32_e32 v47, v47
	v_cvt_pk_bf16_f32 v64, v32, v33
	v_cvt_pk_bf16_f32 v65, v34, v35
	v_cvt_pk_bf16_f32 v66, v36, v37
	v_cvt_pk_bf16_f32 v67, v38, v39
	v_cvt_pk_bf16_f32 v68, v40, v41
	v_cvt_pk_bf16_f32 v69, v42, v43
	v_cvt_pk_bf16_f32 v70, v44, v45
	v_cvt_pk_bf16_f32 v71, v46, v47
	v_pk_add_f32 v[232:233], v[232:233], v[32:33]
	v_pk_add_f32 v[232:233], v[232:233], v[34:35]
	v_pk_add_f32 v[232:233], v[232:233], v[36:37]
	v_pk_add_f32 v[232:233], v[232:233], v[38:39]
	v_pk_add_f32 v[232:233], v[232:233], v[40:41]
	v_pk_add_f32 v[232:233], v[232:233], v[42:43]
	v_pk_add_f32 v[232:233], v[232:233], v[44:45]
	v_pk_add_f32 v[232:233], v[232:233], v[46:47]
	s_waitcnt lgkmcnt(0)
	v_mfma_f32_32x32x16_bf16 v[0:15], v[64:67], v[72:75], v[0:15]
	v_mfma_f32_32x32x16_bf16 v[16:31], v[64:67], v[76:79], v[16:31]
	v_mfma_f32_32x32x16_bf16 v[0:15], v[68:71], v[220:223], v[0:15]
	v_mfma_f32_32x32x16_bf16 v[16:31], v[68:71], v[224:227], v[16:31]
	global_load_dwordx4 v[116:119], v80, s[84:85]
	global_load_dwordx4 v[120:123], v80, s[84:85] offset:32
	global_load_dwordx4 v[124:127], v80, s[84:85] offset:64
	global_load_dwordx4 v[128:131], v80, s[84:85] offset:96
	global_load_dwordx4 v[132:135], v100, s[84:85] offset:768
	global_load_dwordx4 v[136:139], v149, s[84:85] offset:768
	global_load_dwordx4 v[140:143], v100, s[84:85] offset:832
	global_load_dwordx4 v[144:147], v149, s[84:85] offset:832
	s_add_u32 s84, s84, 0x30000
	s_addc_u32 s85, s85, 0
	s_waitcnt vmcnt(16)
	ds_write_b128 v112, v[172:175]
	ds_write_b128 v112, v[176:179] offset:1024
	ds_write_b128 v112, v[180:183] offset:2048
	ds_write_b128 v112, v[184:187] offset:3072
	ds_read2_b32 v[32:33], v115 offset0:136 offset1:137
	ds_read2_b32 v[34:35], v115 offset0:138 offset1:139
	ds_read2_b32 v[36:37], v115 offset0:144 offset1:145
	ds_read2_b32 v[38:39], v115 offset0:146 offset1:147
	ds_read2_b32 v[40:41], v115 offset0:153 offset1:154
	ds_read2_b32 v[42:43], v115 offset0:155 offset1:156
	ds_read2_b32 v[44:45], v115 offset0:161 offset1:162
	ds_read2_b32 v[46:47], v115 offset0:163 offset1:164
	s_waitcnt lgkmcnt(0)
	v_mfma_f32_32x32x16_bf16 v[32:47], v[156:159], v[48:51], v[32:47]
	ds_read_b64_tr_b16 v[72:73], v231
	ds_read_b64_tr_b16 v[74:75], v231 offset:512
	ds_read_b64_tr_b16 v[76:77], v231 offset:2048
	ds_read_b64_tr_b16 v[78:79], v231 offset:2560
	ds_read_b64_tr_b16 v[220:221], v231 offset:1024
	ds_read_b64_tr_b16 v[222:223], v231 offset:1536
	ds_read_b64_tr_b16 v[224:225], v231 offset:3072
	ds_read_b64_tr_b16 v[226:227], v231 offset:3584
	v_mfma_f32_32x32x16_bf16 v[32:47], v[160:163], v[52:55], v[32:47]
	v_mfma_f32_32x32x16_bf16 v[32:47], v[164:167], v[56:59], v[32:47]
	v_mfma_f32_32x32x16_bf16 v[32:47], v[168:171], v[60:63], v[32:47]
	s_nop 11
	v_exp_f32_e32 v32, v32
	v_exp_f32_e32 v33, v33
	v_exp_f32_e32 v34, v34
	v_exp_f32_e32 v35, v35
	v_exp_f32_e32 v36, v36
	v_exp_f32_e32 v37, v37
	v_exp_f32_e32 v38, v38
	v_exp_f32_e32 v39, v39
	v_exp_f32_e32 v40, v40
	v_exp_f32_e32 v41, v41
	v_exp_f32_e32 v42, v42
	v_exp_f32_e32 v43, v43
	v_exp_f32_e32 v44, v44
	v_exp_f32_e32 v45, v45
	v_exp_f32_e32 v46, v46
	v_exp_f32_e32 v47, v47
	v_cvt_pk_bf16_f32 v64, v32, v33
	v_cvt_pk_bf16_f32 v65, v34, v35
	v_cvt_pk_bf16_f32 v66, v36, v37
	v_cvt_pk_bf16_f32 v67, v38, v39
	v_cvt_pk_bf16_f32 v68, v40, v41
	v_cvt_pk_bf16_f32 v69, v42, v43
	v_cvt_pk_bf16_f32 v70, v44, v45
	v_cvt_pk_bf16_f32 v71, v46, v47
	v_pk_add_f32 v[232:233], v[232:233], v[32:33]
	v_pk_add_f32 v[232:233], v[232:233], v[34:35]
	v_pk_add_f32 v[232:233], v[232:233], v[36:37]
	v_pk_add_f32 v[232:233], v[232:233], v[38:39]
	v_pk_add_f32 v[232:233], v[232:233], v[40:41]
	v_pk_add_f32 v[232:233], v[232:233], v[42:43]
	v_pk_add_f32 v[232:233], v[232:233], v[44:45]
	v_pk_add_f32 v[232:233], v[232:233], v[46:47]
	s_waitcnt lgkmcnt(0)
	v_mfma_f32_32x32x16_bf16 v[0:15], v[64:67], v[72:75], v[0:15]
	v_mfma_f32_32x32x16_bf16 v[16:31], v[64:67], v[76:79], v[16:31]
	v_mfma_f32_32x32x16_bf16 v[0:15], v[68:71], v[220:223], v[0:15]
	v_mfma_f32_32x32x16_bf16 v[16:31], v[68:71], v[224:227], v[16:31]
	global_load_dwordx4 v[156:159], v80, s[84:85]
	global_load_dwordx4 v[160:163], v80, s[84:85] offset:32
	global_load_dwordx4 v[164:167], v80, s[84:85] offset:64
	global_load_dwordx4 v[168:171], v80, s[84:85] offset:96
	global_load_dwordx4 v[172:175], v100, s[84:85] offset:768
	global_load_dwordx4 v[176:179], v149, s[84:85] offset:768
	global_load_dwordx4 v[180:183], v100, s[84:85] offset:832
	global_load_dwordx4 v[184:187], v149, s[84:85] offset:832
	s_add_u32 s84, s84, 0x30000
	s_addc_u32 s85, s85, 0
	s_waitcnt vmcnt(16)
	ds_write_b128 v112, v[204:207]
	ds_write_b128 v112, v[208:211] offset:1024
	ds_write_b128 v112, v[212:215] offset:2048
	ds_write_b128 v112, v[216:219] offset:3072
	ds_read2_b32 v[32:33], v115 offset0:170 offset1:171
	ds_read2_b32 v[34:35], v115 offset0:172 offset1:173
	ds_read2_b32 v[36:37], v115 offset0:178 offset1:179
	ds_read2_b32 v[38:39], v115 offset0:180 offset1:181
	ds_read2_b32 v[40:41], v115 offset0:187 offset1:188
	ds_read2_b32 v[42:43], v115 offset0:189 offset1:190
	ds_read2_b32 v[44:45], v115 offset0:195 offset1:196
	ds_read2_b32 v[46:47], v115 offset0:197 offset1:198
	s_waitcnt lgkmcnt(0)
	v_mfma_f32_32x32x16_bf16 v[32:47], v[188:191], v[48:51], v[32:47]
	ds_read_b64_tr_b16 v[72:73], v231
	ds_read_b64_tr_b16 v[74:75], v231 offset:512
	ds_read_b64_tr_b16 v[76:77], v231 offset:2048
	ds_read_b64_tr_b16 v[78:79], v231 offset:2560
	ds_read_b64_tr_b16 v[220:221], v231 offset:1024
	ds_read_b64_tr_b16 v[222:223], v231 offset:1536
	ds_read_b64_tr_b16 v[224:225], v231 offset:3072
	ds_read_b64_tr_b16 v[226:227], v231 offset:3584
	v_mfma_f32_32x32x16_bf16 v[32:47], v[192:195], v[52:55], v[32:47]
	v_mfma_f32_32x32x16_bf16 v[32:47], v[196:199], v[56:59], v[32:47]
	v_mfma_f32_32x32x16_bf16 v[32:47], v[200:203], v[60:63], v[32:47]
	s_nop 11
	v_exp_f32_e32 v32, v32
	v_exp_f32_e32 v33, v33
	v_exp_f32_e32 v34, v34
	v_exp_f32_e32 v35, v35
	v_exp_f32_e32 v36, v36
	v_exp_f32_e32 v37, v37
	v_exp_f32_e32 v38, v38
	v_exp_f32_e32 v39, v39
	v_exp_f32_e32 v40, v40
	v_exp_f32_e32 v41, v41
	v_exp_f32_e32 v42, v42
	v_exp_f32_e32 v43, v43
	v_exp_f32_e32 v44, v44
	v_exp_f32_e32 v45, v45
	v_exp_f32_e32 v46, v46
	v_exp_f32_e32 v47, v47
	v_cvt_pk_bf16_f32 v64, v32, v33
	v_cvt_pk_bf16_f32 v65, v34, v35
	v_cvt_pk_bf16_f32 v66, v36, v37
	v_cvt_pk_bf16_f32 v67, v38, v39
	v_cvt_pk_bf16_f32 v68, v40, v41
	v_cvt_pk_bf16_f32 v69, v42, v43
	v_cvt_pk_bf16_f32 v70, v44, v45
	v_cvt_pk_bf16_f32 v71, v46, v47
	v_pk_add_f32 v[232:233], v[232:233], v[32:33]
	v_pk_add_f32 v[232:233], v[232:233], v[34:35]
	v_pk_add_f32 v[232:233], v[232:233], v[36:37]
	v_pk_add_f32 v[232:233], v[232:233], v[38:39]
	v_pk_add_f32 v[232:233], v[232:233], v[40:41]
	v_pk_add_f32 v[232:233], v[232:233], v[42:43]
	v_pk_add_f32 v[232:233], v[232:233], v[44:45]
	v_pk_add_f32 v[232:233], v[232:233], v[46:47]
	s_waitcnt lgkmcnt(0)
	v_mfma_f32_32x32x16_bf16 v[0:15], v[64:67], v[72:75], v[0:15]
	v_mfma_f32_32x32x16_bf16 v[16:31], v[64:67], v[76:79], v[16:31]
	v_mfma_f32_32x32x16_bf16 v[0:15], v[68:71], v[220:223], v[0:15]
	v_mfma_f32_32x32x16_bf16 v[16:31], v[68:71], v[224:227], v[16:31]
	global_load_dwordx4 v[188:191], v80, s[84:85]
	global_load_dwordx4 v[192:195], v80, s[84:85] offset:32
	global_load_dwordx4 v[196:199], v80, s[84:85] offset:64
	global_load_dwordx4 v[200:203], v80, s[84:85] offset:96
	global_load_dwordx4 v[204:207], v100, s[84:85] offset:768
	global_load_dwordx4 v[208:211], v149, s[84:85] offset:768
	global_load_dwordx4 v[212:215], v100, s[84:85] offset:832
	global_load_dwordx4 v[216:219], v149, s[84:85] offset:832
	s_add_u32 s84, s84, 0x30000
	s_addc_u32 s85, s85, 0
	s_waitcnt vmcnt(16)
	ds_write_b128 v112, v[132:135]
	ds_write_b128 v112, v[136:139] offset:1024
	ds_write_b128 v112, v[140:143] offset:2048
	ds_write_b128 v112, v[144:147] offset:3072
	ds_read2_b32 v[32:33], v115 offset0:204 offset1:205
	ds_read2_b32 v[34:35], v115 offset0:206 offset1:207
	ds_read2_b32 v[36:37], v115 offset0:212 offset1:213
	ds_read2_b32 v[38:39], v115 offset0:214 offset1:215
	ds_read2_b32 v[40:41], v115 offset0:221 offset1:222
	ds_read2_b32 v[42:43], v115 offset0:223 offset1:224
	ds_read2_b32 v[44:45], v115 offset0:229 offset1:230
	ds_read2_b32 v[46:47], v115 offset0:231 offset1:232
	s_waitcnt lgkmcnt(0)
	v_mfma_f32_32x32x16_bf16 v[32:47], v[116:119], v[48:51], v[32:47]
	ds_read_b64_tr_b16 v[72:73], v231
	ds_read_b64_tr_b16 v[74:75], v231 offset:512
	ds_read_b64_tr_b16 v[76:77], v231 offset:2048
	ds_read_b64_tr_b16 v[78:79], v231 offset:2560
	ds_read_b64_tr_b16 v[220:221], v231 offset:1024
	ds_read_b64_tr_b16 v[222:223], v231 offset:1536
	ds_read_b64_tr_b16 v[224:225], v231 offset:3072
	ds_read_b64_tr_b16 v[226:227], v231 offset:3584
	v_mfma_f32_32x32x16_bf16 v[32:47], v[120:123], v[52:55], v[32:47]
	v_mfma_f32_32x32x16_bf16 v[32:47], v[124:127], v[56:59], v[32:47]
	v_mfma_f32_32x32x16_bf16 v[32:47], v[128:131], v[60:63], v[32:47]
	s_nop 11
	v_exp_f32_e32 v32, v32
	v_exp_f32_e32 v33, v33
	v_exp_f32_e32 v34, v34
	v_exp_f32_e32 v35, v35
	v_exp_f32_e32 v36, v36
	v_exp_f32_e32 v37, v37
	v_exp_f32_e32 v38, v38
	v_exp_f32_e32 v39, v39
	v_exp_f32_e32 v40, v40
	v_exp_f32_e32 v41, v41
	v_exp_f32_e32 v42, v42
	v_exp_f32_e32 v43, v43
	v_exp_f32_e32 v44, v44
	v_exp_f32_e32 v45, v45
	v_exp_f32_e32 v46, v46
	v_exp_f32_e32 v47, v47
	v_cvt_pk_bf16_f32 v64, v32, v33
	v_cvt_pk_bf16_f32 v65, v34, v35
	v_cvt_pk_bf16_f32 v66, v36, v37
	v_cvt_pk_bf16_f32 v67, v38, v39
	v_cvt_pk_bf16_f32 v68, v40, v41
	v_cvt_pk_bf16_f32 v69, v42, v43
	v_cvt_pk_bf16_f32 v70, v44, v45
	v_cvt_pk_bf16_f32 v71, v46, v47
	v_pk_add_f32 v[232:233], v[232:233], v[32:33]
	v_pk_add_f32 v[232:233], v[232:233], v[34:35]
	v_pk_add_f32 v[232:233], v[232:233], v[36:37]
	v_pk_add_f32 v[232:233], v[232:233], v[38:39]
	v_pk_add_f32 v[232:233], v[232:233], v[40:41]
	v_pk_add_f32 v[232:233], v[232:233], v[42:43]
	v_pk_add_f32 v[232:233], v[232:233], v[44:45]
	v_pk_add_f32 v[232:233], v[232:233], v[46:47]
	s_waitcnt lgkmcnt(0)
	v_mfma_f32_32x32x16_bf16 v[0:15], v[64:67], v[72:75], v[0:15]
	v_mfma_f32_32x32x16_bf16 v[16:31], v[64:67], v[76:79], v[16:31]
	v_mfma_f32_32x32x16_bf16 v[0:15], v[68:71], v[220:223], v[0:15]
	v_mfma_f32_32x32x16_bf16 v[16:31], v[68:71], v[224:227], v[16:31]
	global_load_dwordx4 v[116:119], v80, s[84:85]
	global_load_dwordx4 v[120:123], v80, s[84:85] offset:32
	global_load_dwordx4 v[124:127], v80, s[84:85] offset:64
	global_load_dwordx4 v[128:131], v80, s[84:85] offset:96
	global_load_dwordx4 v[132:135], v100, s[84:85] offset:768
	global_load_dwordx4 v[136:139], v149, s[84:85] offset:768
	global_load_dwordx4 v[140:143], v100, s[84:85] offset:832
	global_load_dwordx4 v[144:147], v149, s[84:85] offset:832
	s_add_u32 s84, s84, 0x30000
	s_addc_u32 s85, s85, 0
	s_waitcnt vmcnt(16)
	ds_write_b128 v112, v[172:175]
	ds_write_b128 v112, v[176:179] offset:1024
	ds_write_b128 v112, v[180:183] offset:2048
	ds_write_b128 v112, v[184:187] offset:3072
	v_add_u32_e32 v115, 952, v115
	ds_read2_b32 v[32:33], v115 offset0:0 offset1:1
	ds_read2_b32 v[34:35], v115 offset0:2 offset1:3
	ds_read2_b32 v[36:37], v115 offset0:8 offset1:9
	ds_read2_b32 v[38:39], v115 offset0:10 offset1:11
	ds_read2_b32 v[40:41], v115 offset0:17 offset1:18
	ds_read2_b32 v[42:43], v115 offset0:19 offset1:20
	ds_read2_b32 v[44:45], v115 offset0:25 offset1:26
	ds_read2_b32 v[46:47], v115 offset0:27 offset1:28
	s_waitcnt lgkmcnt(0)
	v_mfma_f32_32x32x16_bf16 v[32:47], v[156:159], v[48:51], v[32:47]
	ds_read_b64_tr_b16 v[72:73], v231
	ds_read_b64_tr_b16 v[74:75], v231 offset:512
	ds_read_b64_tr_b16 v[76:77], v231 offset:2048
	ds_read_b64_tr_b16 v[78:79], v231 offset:2560
	ds_read_b64_tr_b16 v[220:221], v231 offset:1024
	ds_read_b64_tr_b16 v[222:223], v231 offset:1536
	ds_read_b64_tr_b16 v[224:225], v231 offset:3072
	ds_read_b64_tr_b16 v[226:227], v231 offset:3584
	v_mfma_f32_32x32x16_bf16 v[32:47], v[160:163], v[52:55], v[32:47]
	v_mfma_f32_32x32x16_bf16 v[32:47], v[164:167], v[56:59], v[32:47]
	v_mfma_f32_32x32x16_bf16 v[32:47], v[168:171], v[60:63], v[32:47]
	s_nop 11
	v_exp_f32_e32 v32, v32
	v_exp_f32_e32 v33, v33
	v_exp_f32_e32 v34, v34
	v_exp_f32_e32 v35, v35
	v_exp_f32_e32 v36, v36
	v_exp_f32_e32 v37, v37
	v_exp_f32_e32 v38, v38
	v_exp_f32_e32 v39, v39
	v_exp_f32_e32 v40, v40
	v_exp_f32_e32 v41, v41
	v_exp_f32_e32 v42, v42
	v_exp_f32_e32 v43, v43
	v_exp_f32_e32 v44, v44
	v_exp_f32_e32 v45, v45
	v_exp_f32_e32 v46, v46
	v_exp_f32_e32 v47, v47
	v_cvt_pk_bf16_f32 v64, v32, v33
	v_cvt_pk_bf16_f32 v65, v34, v35
	v_cvt_pk_bf16_f32 v66, v36, v37
	v_cvt_pk_bf16_f32 v67, v38, v39
	v_cvt_pk_bf16_f32 v68, v40, v41
	v_cvt_pk_bf16_f32 v69, v42, v43
	v_cvt_pk_bf16_f32 v70, v44, v45
	v_cvt_pk_bf16_f32 v71, v46, v47
	v_pk_add_f32 v[232:233], v[232:233], v[32:33]
	v_pk_add_f32 v[232:233], v[232:233], v[34:35]
	v_pk_add_f32 v[232:233], v[232:233], v[36:37]
	v_pk_add_f32 v[232:233], v[232:233], v[38:39]
	v_pk_add_f32 v[232:233], v[232:233], v[40:41]
	v_pk_add_f32 v[232:233], v[232:233], v[42:43]
	v_pk_add_f32 v[232:233], v[232:233], v[44:45]
	v_pk_add_f32 v[232:233], v[232:233], v[46:47]
	s_waitcnt lgkmcnt(0)
	v_mfma_f32_32x32x16_bf16 v[0:15], v[64:67], v[72:75], v[0:15]
	v_mfma_f32_32x32x16_bf16 v[16:31], v[64:67], v[76:79], v[16:31]
	v_mfma_f32_32x32x16_bf16 v[0:15], v[68:71], v[220:223], v[0:15]
	v_mfma_f32_32x32x16_bf16 v[16:31], v[68:71], v[224:227], v[16:31]
	global_load_dwordx4 v[156:159], v80, s[84:85]
	global_load_dwordx4 v[160:163], v80, s[84:85] offset:32
	global_load_dwordx4 v[164:167], v80, s[84:85] offset:64
	global_load_dwordx4 v[168:171], v80, s[84:85] offset:96
	global_load_dwordx4 v[172:175], v100, s[84:85] offset:768
	global_load_dwordx4 v[176:179], v149, s[84:85] offset:768
	global_load_dwordx4 v[180:183], v100, s[84:85] offset:832
	global_load_dwordx4 v[184:187], v149, s[84:85] offset:832
	s_add_u32 s84, s84, 0x30000
	s_addc_u32 s85, s85, 0
	s_waitcnt vmcnt(16)
	ds_write_b128 v112, v[204:207]
	ds_write_b128 v112, v[208:211] offset:1024
	ds_write_b128 v112, v[212:215] offset:2048
	ds_write_b128 v112, v[216:219] offset:3072
	ds_read2_b32 v[32:33], v115 offset0:34 offset1:35
	ds_read2_b32 v[34:35], v115 offset0:36 offset1:37
	ds_read2_b32 v[36:37], v115 offset0:42 offset1:43
	ds_read2_b32 v[38:39], v115 offset0:44 offset1:45
	ds_read2_b32 v[40:41], v115 offset0:51 offset1:52
	ds_read2_b32 v[42:43], v115 offset0:53 offset1:54
	ds_read2_b32 v[44:45], v115 offset0:59 offset1:60
	ds_read2_b32 v[46:47], v115 offset0:61 offset1:62
	s_waitcnt lgkmcnt(0)
	v_mfma_f32_32x32x16_bf16 v[32:47], v[188:191], v[48:51], v[32:47]
	ds_read_b64_tr_b16 v[72:73], v231
	ds_read_b64_tr_b16 v[74:75], v231 offset:512
	ds_read_b64_tr_b16 v[76:77], v231 offset:2048
	ds_read_b64_tr_b16 v[78:79], v231 offset:2560
	ds_read_b64_tr_b16 v[220:221], v231 offset:1024
	ds_read_b64_tr_b16 v[222:223], v231 offset:1536
	ds_read_b64_tr_b16 v[224:225], v231 offset:3072
	ds_read_b64_tr_b16 v[226:227], v231 offset:3584
	v_mfma_f32_32x32x16_bf16 v[32:47], v[192:195], v[52:55], v[32:47]
	v_mfma_f32_32x32x16_bf16 v[32:47], v[196:199], v[56:59], v[32:47]
	v_mfma_f32_32x32x16_bf16 v[32:47], v[200:203], v[60:63], v[32:47]
	s_nop 11
	v_exp_f32_e32 v32, v32
	v_exp_f32_e32 v33, v33
	v_exp_f32_e32 v34, v34
	v_exp_f32_e32 v35, v35
	v_exp_f32_e32 v36, v36
	v_exp_f32_e32 v37, v37
	v_exp_f32_e32 v38, v38
	v_exp_f32_e32 v39, v39
	v_exp_f32_e32 v40, v40
	v_exp_f32_e32 v41, v41
	v_exp_f32_e32 v42, v42
	v_exp_f32_e32 v43, v43
	v_exp_f32_e32 v44, v44
	v_exp_f32_e32 v45, v45
	v_exp_f32_e32 v46, v46
	v_exp_f32_e32 v47, v47
	v_cvt_pk_bf16_f32 v64, v32, v33
	v_cvt_pk_bf16_f32 v65, v34, v35
	v_cvt_pk_bf16_f32 v66, v36, v37
	v_cvt_pk_bf16_f32 v67, v38, v39
	v_cvt_pk_bf16_f32 v68, v40, v41
	v_cvt_pk_bf16_f32 v69, v42, v43
	v_cvt_pk_bf16_f32 v70, v44, v45
	v_cvt_pk_bf16_f32 v71, v46, v47
	v_pk_add_f32 v[232:233], v[232:233], v[32:33]
	v_pk_add_f32 v[232:233], v[232:233], v[34:35]
	v_pk_add_f32 v[232:233], v[232:233], v[36:37]
	v_pk_add_f32 v[232:233], v[232:233], v[38:39]
	v_pk_add_f32 v[232:233], v[232:233], v[40:41]
	v_pk_add_f32 v[232:233], v[232:233], v[42:43]
	v_pk_add_f32 v[232:233], v[232:233], v[44:45]
	v_pk_add_f32 v[232:233], v[232:233], v[46:47]
	s_waitcnt lgkmcnt(0)
	v_mfma_f32_32x32x16_bf16 v[0:15], v[64:67], v[72:75], v[0:15]
	v_mfma_f32_32x32x16_bf16 v[16:31], v[64:67], v[76:79], v[16:31]
	v_mfma_f32_32x32x16_bf16 v[0:15], v[68:71], v[220:223], v[0:15]
	v_mfma_f32_32x32x16_bf16 v[16:31], v[68:71], v[224:227], v[16:31]
	global_load_dwordx4 v[188:191], v80, s[84:85]
	global_load_dwordx4 v[192:195], v80, s[84:85] offset:32
	global_load_dwordx4 v[196:199], v80, s[84:85] offset:64
	global_load_dwordx4 v[200:203], v80, s[84:85] offset:96
	global_load_dwordx4 v[204:207], v100, s[84:85] offset:768
	global_load_dwordx4 v[208:211], v149, s[84:85] offset:768
	global_load_dwordx4 v[212:215], v100, s[84:85] offset:832
	global_load_dwordx4 v[216:219], v149, s[84:85] offset:832
	s_add_u32 s84, s84, 0x30000
	s_addc_u32 s85, s85, 0
	s_waitcnt vmcnt(16)
	ds_write_b128 v112, v[132:135]
	ds_write_b128 v112, v[136:139] offset:1024
	ds_write_b128 v112, v[140:143] offset:2048
	ds_write_b128 v112, v[144:147] offset:3072
	ds_read2_b32 v[32:33], v115 offset0:68 offset1:69
	ds_read2_b32 v[34:35], v115 offset0:70 offset1:71
	ds_read2_b32 v[36:37], v115 offset0:76 offset1:77
	ds_read2_b32 v[38:39], v115 offset0:78 offset1:79
	ds_read2_b32 v[40:41], v115 offset0:85 offset1:86
	ds_read2_b32 v[42:43], v115 offset0:87 offset1:88
	ds_read2_b32 v[44:45], v115 offset0:93 offset1:94
	ds_read2_b32 v[46:47], v115 offset0:95 offset1:96
	s_waitcnt lgkmcnt(0)
	v_mfma_f32_32x32x16_bf16 v[32:47], v[116:119], v[48:51], v[32:47]
	ds_read_b64_tr_b16 v[72:73], v231
	ds_read_b64_tr_b16 v[74:75], v231 offset:512
	ds_read_b64_tr_b16 v[76:77], v231 offset:2048
	ds_read_b64_tr_b16 v[78:79], v231 offset:2560
	ds_read_b64_tr_b16 v[220:221], v231 offset:1024
	ds_read_b64_tr_b16 v[222:223], v231 offset:1536
	ds_read_b64_tr_b16 v[224:225], v231 offset:3072
	ds_read_b64_tr_b16 v[226:227], v231 offset:3584
	v_mfma_f32_32x32x16_bf16 v[32:47], v[120:123], v[52:55], v[32:47]
	v_mfma_f32_32x32x16_bf16 v[32:47], v[124:127], v[56:59], v[32:47]
	v_mfma_f32_32x32x16_bf16 v[32:47], v[128:131], v[60:63], v[32:47]
	s_nop 11
	v_exp_f32_e32 v32, v32
	v_exp_f32_e32 v33, v33
	v_exp_f32_e32 v34, v34
	v_exp_f32_e32 v35, v35
	v_exp_f32_e32 v36, v36
	v_exp_f32_e32 v37, v37
	v_exp_f32_e32 v38, v38
	v_exp_f32_e32 v39, v39
	v_exp_f32_e32 v40, v40
	v_exp_f32_e32 v41, v41
	v_exp_f32_e32 v42, v42
	v_exp_f32_e32 v43, v43
	v_exp_f32_e32 v44, v44
	v_exp_f32_e32 v45, v45
	v_exp_f32_e32 v46, v46
	v_exp_f32_e32 v47, v47
	v_cvt_pk_bf16_f32 v64, v32, v33
	v_cvt_pk_bf16_f32 v65, v34, v35
	v_cvt_pk_bf16_f32 v66, v36, v37
	v_cvt_pk_bf16_f32 v67, v38, v39
	v_cvt_pk_bf16_f32 v68, v40, v41
	v_cvt_pk_bf16_f32 v69, v42, v43
	v_cvt_pk_bf16_f32 v70, v44, v45
	v_cvt_pk_bf16_f32 v71, v46, v47
	v_pk_add_f32 v[232:233], v[232:233], v[32:33]
	v_pk_add_f32 v[232:233], v[232:233], v[34:35]
	v_pk_add_f32 v[232:233], v[232:233], v[36:37]
	v_pk_add_f32 v[232:233], v[232:233], v[38:39]
	v_pk_add_f32 v[232:233], v[232:233], v[40:41]
	v_pk_add_f32 v[232:233], v[232:233], v[42:43]
	v_pk_add_f32 v[232:233], v[232:233], v[44:45]
	v_pk_add_f32 v[232:233], v[232:233], v[46:47]
	s_waitcnt lgkmcnt(0)
	v_mfma_f32_32x32x16_bf16 v[0:15], v[64:67], v[72:75], v[0:15]
	v_mfma_f32_32x32x16_bf16 v[16:31], v[64:67], v[76:79], v[16:31]
	v_mfma_f32_32x32x16_bf16 v[0:15], v[68:71], v[220:223], v[0:15]
	v_mfma_f32_32x32x16_bf16 v[16:31], v[68:71], v[224:227], v[16:31]
	global_load_dwordx4 v[116:119], v80, s[84:85]
	global_load_dwordx4 v[120:123], v80, s[84:85] offset:32
	global_load_dwordx4 v[124:127], v80, s[84:85] offset:64
	global_load_dwordx4 v[128:131], v80, s[84:85] offset:96
	global_load_dwordx4 v[132:135], v100, s[84:85] offset:768
	global_load_dwordx4 v[136:139], v149, s[84:85] offset:768
	global_load_dwordx4 v[140:143], v100, s[84:85] offset:832
	global_load_dwordx4 v[144:147], v149, s[84:85] offset:832
	s_add_u32 s84, s84, 0x30000
	s_addc_u32 s85, s85, 0
	s_waitcnt vmcnt(16)
	ds_write_b128 v112, v[172:175]
	ds_write_b128 v112, v[176:179] offset:1024
	ds_write_b128 v112, v[180:183] offset:2048
	ds_write_b128 v112, v[184:187] offset:3072
	ds_read2_b32 v[32:33], v115 offset0:102 offset1:103
	ds_read2_b32 v[34:35], v115 offset0:104 offset1:105
	ds_read2_b32 v[36:37], v115 offset0:110 offset1:111
	ds_read2_b32 v[38:39], v115 offset0:112 offset1:113
	ds_read2_b32 v[40:41], v115 offset0:119 offset1:120
	ds_read2_b32 v[42:43], v115 offset0:121 offset1:122
	ds_read2_b32 v[44:45], v115 offset0:127 offset1:128
	ds_read2_b32 v[46:47], v115 offset0:129 offset1:130
	s_waitcnt lgkmcnt(0)
	v_mfma_f32_32x32x16_bf16 v[32:47], v[156:159], v[48:51], v[32:47]
	ds_read_b64_tr_b16 v[72:73], v231
	ds_read_b64_tr_b16 v[74:75], v231 offset:512
	ds_read_b64_tr_b16 v[76:77], v231 offset:2048
	ds_read_b64_tr_b16 v[78:79], v231 offset:2560
	ds_read_b64_tr_b16 v[220:221], v231 offset:1024
	ds_read_b64_tr_b16 v[222:223], v231 offset:1536
	ds_read_b64_tr_b16 v[224:225], v231 offset:3072
	ds_read_b64_tr_b16 v[226:227], v231 offset:3584
	v_mfma_f32_32x32x16_bf16 v[32:47], v[160:163], v[52:55], v[32:47]
	v_mfma_f32_32x32x16_bf16 v[32:47], v[164:167], v[56:59], v[32:47]
	v_mfma_f32_32x32x16_bf16 v[32:47], v[168:171], v[60:63], v[32:47]
	s_nop 11
	v_exp_f32_e32 v32, v32
	v_exp_f32_e32 v33, v33
	v_exp_f32_e32 v34, v34
	v_exp_f32_e32 v35, v35
	v_exp_f32_e32 v36, v36
	v_exp_f32_e32 v37, v37
	v_exp_f32_e32 v38, v38
	v_exp_f32_e32 v39, v39
	v_exp_f32_e32 v40, v40
	v_exp_f32_e32 v41, v41
	v_exp_f32_e32 v42, v42
	v_exp_f32_e32 v43, v43
	v_exp_f32_e32 v44, v44
	v_exp_f32_e32 v45, v45
	v_exp_f32_e32 v46, v46
	v_exp_f32_e32 v47, v47
	v_cvt_pk_bf16_f32 v64, v32, v33
	v_cvt_pk_bf16_f32 v65, v34, v35
	v_cvt_pk_bf16_f32 v66, v36, v37
	v_cvt_pk_bf16_f32 v67, v38, v39
	v_cvt_pk_bf16_f32 v68, v40, v41
	v_cvt_pk_bf16_f32 v69, v42, v43
	v_cvt_pk_bf16_f32 v70, v44, v45
	v_cvt_pk_bf16_f32 v71, v46, v47
	v_pk_add_f32 v[232:233], v[232:233], v[32:33]
	v_pk_add_f32 v[232:233], v[232:233], v[34:35]
	v_pk_add_f32 v[232:233], v[232:233], v[36:37]
	v_pk_add_f32 v[232:233], v[232:233], v[38:39]
	v_pk_add_f32 v[232:233], v[232:233], v[40:41]
	v_pk_add_f32 v[232:233], v[232:233], v[42:43]
	v_pk_add_f32 v[232:233], v[232:233], v[44:45]
	v_pk_add_f32 v[232:233], v[232:233], v[46:47]
	s_waitcnt lgkmcnt(0)
	v_mfma_f32_32x32x16_bf16 v[0:15], v[64:67], v[72:75], v[0:15]
	v_mfma_f32_32x32x16_bf16 v[16:31], v[64:67], v[76:79], v[16:31]
	v_mfma_f32_32x32x16_bf16 v[0:15], v[68:71], v[220:223], v[0:15]
	v_mfma_f32_32x32x16_bf16 v[16:31], v[68:71], v[224:227], v[16:31]
	global_load_dwordx4 v[156:159], v80, s[84:85]
	global_load_dwordx4 v[160:163], v80, s[84:85] offset:32
	global_load_dwordx4 v[164:167], v80, s[84:85] offset:64
	global_load_dwordx4 v[168:171], v80, s[84:85] offset:96
	global_load_dwordx4 v[172:175], v100, s[84:85] offset:768
	global_load_dwordx4 v[176:179], v149, s[84:85] offset:768
	global_load_dwordx4 v[180:183], v100, s[84:85] offset:832
	global_load_dwordx4 v[184:187], v149, s[84:85] offset:832
	s_add_u32 s84, s84, 0x30000
	s_addc_u32 s85, s85, 0
	s_waitcnt vmcnt(16)
	ds_write_b128 v112, v[204:207]
	ds_write_b128 v112, v[208:211] offset:1024
	ds_write_b128 v112, v[212:215] offset:2048
	ds_write_b128 v112, v[216:219] offset:3072
	ds_read2_b32 v[32:33], v115 offset0:136 offset1:137
	ds_read2_b32 v[34:35], v115 offset0:138 offset1:139
	ds_read2_b32 v[36:37], v115 offset0:144 offset1:145
	ds_read2_b32 v[38:39], v115 offset0:146 offset1:147
	ds_read2_b32 v[40:41], v115 offset0:153 offset1:154
	ds_read2_b32 v[42:43], v115 offset0:155 offset1:156
	ds_read2_b32 v[44:45], v115 offset0:161 offset1:162
	ds_read2_b32 v[46:47], v115 offset0:163 offset1:164
	s_waitcnt lgkmcnt(0)
	v_mfma_f32_32x32x16_bf16 v[32:47], v[188:191], v[48:51], v[32:47]
	ds_read_b64_tr_b16 v[72:73], v231
	ds_read_b64_tr_b16 v[74:75], v231 offset:512
	ds_read_b64_tr_b16 v[76:77], v231 offset:2048
	ds_read_b64_tr_b16 v[78:79], v231 offset:2560
	ds_read_b64_tr_b16 v[220:221], v231 offset:1024
	ds_read_b64_tr_b16 v[222:223], v231 offset:1536
	ds_read_b64_tr_b16 v[224:225], v231 offset:3072
	ds_read_b64_tr_b16 v[226:227], v231 offset:3584
	v_mfma_f32_32x32x16_bf16 v[32:47], v[192:195], v[52:55], v[32:47]
	v_mfma_f32_32x32x16_bf16 v[32:47], v[196:199], v[56:59], v[32:47]
	v_mfma_f32_32x32x16_bf16 v[32:47], v[200:203], v[60:63], v[32:47]
	s_nop 11
	v_exp_f32_e32 v32, v32
	v_exp_f32_e32 v33, v33
	v_exp_f32_e32 v34, v34
	v_exp_f32_e32 v35, v35
	v_exp_f32_e32 v36, v36
	v_exp_f32_e32 v37, v37
	v_exp_f32_e32 v38, v38
	v_exp_f32_e32 v39, v39
	v_exp_f32_e32 v40, v40
	v_exp_f32_e32 v41, v41
	v_exp_f32_e32 v42, v42
	v_exp_f32_e32 v43, v43
	v_exp_f32_e32 v44, v44
	v_exp_f32_e32 v45, v45
	v_exp_f32_e32 v46, v46
	v_exp_f32_e32 v47, v47
	v_cvt_pk_bf16_f32 v64, v32, v33
	v_cvt_pk_bf16_f32 v65, v34, v35
	v_cvt_pk_bf16_f32 v66, v36, v37
	v_cvt_pk_bf16_f32 v67, v38, v39
	v_cvt_pk_bf16_f32 v68, v40, v41
	v_cvt_pk_bf16_f32 v69, v42, v43
	v_cvt_pk_bf16_f32 v70, v44, v45
	v_cvt_pk_bf16_f32 v71, v46, v47
	v_pk_add_f32 v[232:233], v[232:233], v[32:33]
	v_pk_add_f32 v[232:233], v[232:233], v[34:35]
	v_pk_add_f32 v[232:233], v[232:233], v[36:37]
	v_pk_add_f32 v[232:233], v[232:233], v[38:39]
	v_pk_add_f32 v[232:233], v[232:233], v[40:41]
	v_pk_add_f32 v[232:233], v[232:233], v[42:43]
	v_pk_add_f32 v[232:233], v[232:233], v[44:45]
	v_pk_add_f32 v[232:233], v[232:233], v[46:47]
	s_waitcnt lgkmcnt(0)
	v_mfma_f32_32x32x16_bf16 v[0:15], v[64:67], v[72:75], v[0:15]
	v_mfma_f32_32x32x16_bf16 v[16:31], v[64:67], v[76:79], v[16:31]
	v_mfma_f32_32x32x16_bf16 v[0:15], v[68:71], v[220:223], v[0:15]
	v_mfma_f32_32x32x16_bf16 v[16:31], v[68:71], v[224:227], v[16:31]
	global_load_dwordx4 v[188:191], v80, s[84:85]
	global_load_dwordx4 v[192:195], v80, s[84:85] offset:32
	global_load_dwordx4 v[196:199], v80, s[84:85] offset:64
	global_load_dwordx4 v[200:203], v80, s[84:85] offset:96
	global_load_dwordx4 v[204:207], v100, s[84:85] offset:768
	global_load_dwordx4 v[208:211], v149, s[84:85] offset:768
	global_load_dwordx4 v[212:215], v100, s[84:85] offset:832
	global_load_dwordx4 v[216:219], v149, s[84:85] offset:832
	s_add_u32 s84, s84, 0x30000
	s_addc_u32 s85, s85, 0
	s_waitcnt vmcnt(16)
	ds_write_b128 v112, v[132:135]
	ds_write_b128 v112, v[136:139] offset:1024
	ds_write_b128 v112, v[140:143] offset:2048
	ds_write_b128 v112, v[144:147] offset:3072
	ds_read2_b32 v[32:33], v115 offset0:170 offset1:171
	ds_read2_b32 v[34:35], v115 offset0:172 offset1:173
	ds_read2_b32 v[36:37], v115 offset0:178 offset1:179
	ds_read2_b32 v[38:39], v115 offset0:180 offset1:181
	ds_read2_b32 v[40:41], v115 offset0:187 offset1:188
	ds_read2_b32 v[42:43], v115 offset0:189 offset1:190
	ds_read2_b32 v[44:45], v115 offset0:195 offset1:196
	ds_read2_b32 v[46:47], v115 offset0:197 offset1:198
	s_waitcnt lgkmcnt(0)
	v_mfma_f32_32x32x16_bf16 v[32:47], v[116:119], v[48:51], v[32:47]
	ds_read_b64_tr_b16 v[72:73], v231
	ds_read_b64_tr_b16 v[74:75], v231 offset:512
	ds_read_b64_tr_b16 v[76:77], v231 offset:2048
	ds_read_b64_tr_b16 v[78:79], v231 offset:2560
	ds_read_b64_tr_b16 v[220:221], v231 offset:1024
	ds_read_b64_tr_b16 v[222:223], v231 offset:1536
	ds_read_b64_tr_b16 v[224:225], v231 offset:3072
	ds_read_b64_tr_b16 v[226:227], v231 offset:3584
	v_mfma_f32_32x32x16_bf16 v[32:47], v[120:123], v[52:55], v[32:47]
	v_mfma_f32_32x32x16_bf16 v[32:47], v[124:127], v[56:59], v[32:47]
	v_mfma_f32_32x32x16_bf16 v[32:47], v[128:131], v[60:63], v[32:47]
	s_nop 11
	v_exp_f32_e32 v32, v32
	v_exp_f32_e32 v33, v33
	v_exp_f32_e32 v34, v34
	v_exp_f32_e32 v35, v35
	v_exp_f32_e32 v36, v36
	v_exp_f32_e32 v37, v37
	v_exp_f32_e32 v38, v38
	v_exp_f32_e32 v39, v39
	v_exp_f32_e32 v40, v40
	v_exp_f32_e32 v41, v41
	v_exp_f32_e32 v42, v42
	v_exp_f32_e32 v43, v43
	v_exp_f32_e32 v44, v44
	v_exp_f32_e32 v45, v45
	v_exp_f32_e32 v46, v46
	v_exp_f32_e32 v47, v47
	v_cvt_pk_bf16_f32 v64, v32, v33
	v_cvt_pk_bf16_f32 v65, v34, v35
	v_cvt_pk_bf16_f32 v66, v36, v37
	v_cvt_pk_bf16_f32 v67, v38, v39
	v_cvt_pk_bf16_f32 v68, v40, v41
	v_cvt_pk_bf16_f32 v69, v42, v43
	v_cvt_pk_bf16_f32 v70, v44, v45
	v_cvt_pk_bf16_f32 v71, v46, v47
	v_pk_add_f32 v[232:233], v[232:233], v[32:33]
	v_pk_add_f32 v[232:233], v[232:233], v[34:35]
	v_pk_add_f32 v[232:233], v[232:233], v[36:37]
	v_pk_add_f32 v[232:233], v[232:233], v[38:39]
	v_pk_add_f32 v[232:233], v[232:233], v[40:41]
	v_pk_add_f32 v[232:233], v[232:233], v[42:43]
	v_pk_add_f32 v[232:233], v[232:233], v[44:45]
	v_pk_add_f32 v[232:233], v[232:233], v[46:47]
	s_waitcnt lgkmcnt(0)
	v_mfma_f32_32x32x16_bf16 v[0:15], v[64:67], v[72:75], v[0:15]
	v_mfma_f32_32x32x16_bf16 v[16:31], v[64:67], v[76:79], v[16:31]
	v_mfma_f32_32x32x16_bf16 v[0:15], v[68:71], v[220:223], v[0:15]
	v_mfma_f32_32x32x16_bf16 v[16:31], v[68:71], v[224:227], v[16:31]
	global_load_dwordx4 v[116:119], v80, s[84:85]
	global_load_dwordx4 v[120:123], v80, s[84:85] offset:32
	global_load_dwordx4 v[124:127], v80, s[84:85] offset:64
	global_load_dwordx4 v[128:131], v80, s[84:85] offset:96
	global_load_dwordx4 v[132:135], v100, s[84:85] offset:768
	global_load_dwordx4 v[136:139], v149, s[84:85] offset:768
	global_load_dwordx4 v[140:143], v100, s[84:85] offset:832
	global_load_dwordx4 v[144:147], v149, s[84:85] offset:832
	s_add_u32 s84, s84, 0x30000
	s_addc_u32 s85, s85, 0
	s_waitcnt vmcnt(16)
	ds_write_b128 v112, v[172:175]
	ds_write_b128 v112, v[176:179] offset:1024
	ds_write_b128 v112, v[180:183] offset:2048
	ds_write_b128 v112, v[184:187] offset:3072
	ds_read2_b32 v[32:33], v115 offset0:204 offset1:205
	ds_read2_b32 v[34:35], v115 offset0:206 offset1:207
	ds_read2_b32 v[36:37], v115 offset0:212 offset1:213
	ds_read2_b32 v[38:39], v115 offset0:214 offset1:215
	ds_read2_b32 v[40:41], v115 offset0:221 offset1:222
	ds_read2_b32 v[42:43], v115 offset0:223 offset1:224
	ds_read2_b32 v[44:45], v115 offset0:229 offset1:230
	ds_read2_b32 v[46:47], v115 offset0:231 offset1:232
	s_waitcnt lgkmcnt(0)
	v_mfma_f32_32x32x16_bf16 v[32:47], v[156:159], v[48:51], v[32:47]
	ds_read_b64_tr_b16 v[72:73], v231
	ds_read_b64_tr_b16 v[74:75], v231 offset:512
	ds_read_b64_tr_b16 v[76:77], v231 offset:2048
	ds_read_b64_tr_b16 v[78:79], v231 offset:2560
	ds_read_b64_tr_b16 v[220:221], v231 offset:1024
	ds_read_b64_tr_b16 v[222:223], v231 offset:1536
	ds_read_b64_tr_b16 v[224:225], v231 offset:3072
	ds_read_b64_tr_b16 v[226:227], v231 offset:3584
	v_mfma_f32_32x32x16_bf16 v[32:47], v[160:163], v[52:55], v[32:47]
	v_mfma_f32_32x32x16_bf16 v[32:47], v[164:167], v[56:59], v[32:47]
	v_mfma_f32_32x32x16_bf16 v[32:47], v[168:171], v[60:63], v[32:47]
	s_nop 11
	v_exp_f32_e32 v32, v32
	v_exp_f32_e32 v33, v33
	v_exp_f32_e32 v34, v34
	v_exp_f32_e32 v35, v35
	v_exp_f32_e32 v36, v36
	v_exp_f32_e32 v37, v37
	v_exp_f32_e32 v38, v38
	v_exp_f32_e32 v39, v39
	v_exp_f32_e32 v40, v40
	v_exp_f32_e32 v41, v41
	v_exp_f32_e32 v42, v42
	v_exp_f32_e32 v43, v43
	v_exp_f32_e32 v44, v44
	v_exp_f32_e32 v45, v45
	v_exp_f32_e32 v46, v46
	v_exp_f32_e32 v47, v47
	v_cvt_pk_bf16_f32 v64, v32, v33
	v_cvt_pk_bf16_f32 v65, v34, v35
	v_cvt_pk_bf16_f32 v66, v36, v37
	v_cvt_pk_bf16_f32 v67, v38, v39
	v_cvt_pk_bf16_f32 v68, v40, v41
	v_cvt_pk_bf16_f32 v69, v42, v43
	v_cvt_pk_bf16_f32 v70, v44, v45
	v_cvt_pk_bf16_f32 v71, v46, v47
	v_pk_add_f32 v[232:233], v[232:233], v[32:33]
	v_pk_add_f32 v[232:233], v[232:233], v[34:35]
	v_pk_add_f32 v[232:233], v[232:233], v[36:37]
	v_pk_add_f32 v[232:233], v[232:233], v[38:39]
	v_pk_add_f32 v[232:233], v[232:233], v[40:41]
	v_pk_add_f32 v[232:233], v[232:233], v[42:43]
	v_pk_add_f32 v[232:233], v[232:233], v[44:45]
	v_pk_add_f32 v[232:233], v[232:233], v[46:47]
	s_waitcnt lgkmcnt(0)
	v_mfma_f32_32x32x16_bf16 v[0:15], v[64:67], v[72:75], v[0:15]
	v_mfma_f32_32x32x16_bf16 v[16:31], v[64:67], v[76:79], v[16:31]
	v_mfma_f32_32x32x16_bf16 v[0:15], v[68:71], v[220:223], v[0:15]
	v_mfma_f32_32x32x16_bf16 v[16:31], v[68:71], v[224:227], v[16:31]
	global_load_dwordx4 v[156:159], v80, s[84:85]
	global_load_dwordx4 v[160:163], v80, s[84:85] offset:32
	global_load_dwordx4 v[164:167], v80, s[84:85] offset:64
	global_load_dwordx4 v[168:171], v80, s[84:85] offset:96
	global_load_dwordx4 v[172:175], v100, s[84:85] offset:768
	global_load_dwordx4 v[176:179], v149, s[84:85] offset:768
	global_load_dwordx4 v[180:183], v100, s[84:85] offset:832
	global_load_dwordx4 v[184:187], v149, s[84:85] offset:832
	s_add_u32 s84, s84, 0x30000
	s_addc_u32 s85, s85, 0
	s_waitcnt vmcnt(16)
	ds_write_b128 v112, v[204:207]
	ds_write_b128 v112, v[208:211] offset:1024
	ds_write_b128 v112, v[212:215] offset:2048
	ds_write_b128 v112, v[216:219] offset:3072
	v_add_u32_e32 v115, 952, v115
	ds_read2_b32 v[32:33], v115 offset0:0 offset1:1
	ds_read2_b32 v[34:35], v115 offset0:2 offset1:3
	ds_read2_b32 v[36:37], v115 offset0:8 offset1:9
	ds_read2_b32 v[38:39], v115 offset0:10 offset1:11
	ds_read2_b32 v[40:41], v115 offset0:17 offset1:18
	ds_read2_b32 v[42:43], v115 offset0:19 offset1:20
	ds_read2_b32 v[44:45], v115 offset0:25 offset1:26
	ds_read2_b32 v[46:47], v115 offset0:27 offset1:28
	s_waitcnt lgkmcnt(0)
	v_mfma_f32_32x32x16_bf16 v[32:47], v[188:191], v[48:51], v[32:47]
	ds_read_b64_tr_b16 v[72:73], v231
	ds_read_b64_tr_b16 v[74:75], v231 offset:512
	ds_read_b64_tr_b16 v[76:77], v231 offset:2048
	ds_read_b64_tr_b16 v[78:79], v231 offset:2560
	ds_read_b64_tr_b16 v[220:221], v231 offset:1024
	ds_read_b64_tr_b16 v[222:223], v231 offset:1536
	ds_read_b64_tr_b16 v[224:225], v231 offset:3072
	ds_read_b64_tr_b16 v[226:227], v231 offset:3584
	v_mfma_f32_32x32x16_bf16 v[32:47], v[192:195], v[52:55], v[32:47]
	v_mfma_f32_32x32x16_bf16 v[32:47], v[196:199], v[56:59], v[32:47]
	v_mfma_f32_32x32x16_bf16 v[32:47], v[200:203], v[60:63], v[32:47]
	s_nop 11
	v_exp_f32_e32 v32, v32
	v_exp_f32_e32 v33, v33
	v_exp_f32_e32 v34, v34
	v_exp_f32_e32 v35, v35
	v_exp_f32_e32 v36, v36
	v_exp_f32_e32 v37, v37
	v_exp_f32_e32 v38, v38
	v_exp_f32_e32 v39, v39
	v_exp_f32_e32 v40, v40
	v_exp_f32_e32 v41, v41
	v_exp_f32_e32 v42, v42
	v_exp_f32_e32 v43, v43
	v_exp_f32_e32 v44, v44
	v_exp_f32_e32 v45, v45
	v_exp_f32_e32 v46, v46
	v_exp_f32_e32 v47, v47
	v_cvt_pk_bf16_f32 v64, v32, v33
	v_cvt_pk_bf16_f32 v65, v34, v35
	v_cvt_pk_bf16_f32 v66, v36, v37
	v_cvt_pk_bf16_f32 v67, v38, v39
	v_cvt_pk_bf16_f32 v68, v40, v41
	v_cvt_pk_bf16_f32 v69, v42, v43
	v_cvt_pk_bf16_f32 v70, v44, v45
	v_cvt_pk_bf16_f32 v71, v46, v47
	v_pk_add_f32 v[232:233], v[232:233], v[32:33]
	v_pk_add_f32 v[232:233], v[232:233], v[34:35]
	v_pk_add_f32 v[232:233], v[232:233], v[36:37]
	v_pk_add_f32 v[232:233], v[232:233], v[38:39]
	v_pk_add_f32 v[232:233], v[232:233], v[40:41]
	v_pk_add_f32 v[232:233], v[232:233], v[42:43]
	v_pk_add_f32 v[232:233], v[232:233], v[44:45]
	v_pk_add_f32 v[232:233], v[232:233], v[46:47]
	s_waitcnt lgkmcnt(0)
	v_mfma_f32_32x32x16_bf16 v[0:15], v[64:67], v[72:75], v[0:15]
	v_mfma_f32_32x32x16_bf16 v[16:31], v[64:67], v[76:79], v[16:31]
	v_mfma_f32_32x32x16_bf16 v[0:15], v[68:71], v[220:223], v[0:15]
	v_mfma_f32_32x32x16_bf16 v[16:31], v[68:71], v[224:227], v[16:31]
	global_load_dwordx4 v[188:191], v80, s[84:85]
	global_load_dwordx4 v[192:195], v80, s[84:85] offset:32
	global_load_dwordx4 v[196:199], v80, s[84:85] offset:64
	global_load_dwordx4 v[200:203], v80, s[84:85] offset:96
	global_load_dwordx4 v[204:207], v100, s[84:85] offset:768
	global_load_dwordx4 v[208:211], v149, s[84:85] offset:768
	global_load_dwordx4 v[212:215], v100, s[84:85] offset:832
	global_load_dwordx4 v[216:219], v149, s[84:85] offset:832
	s_add_u32 s84, s84, 0x30000
	s_addc_u32 s85, s85, 0
	s_waitcnt vmcnt(16)
	ds_write_b128 v112, v[132:135]
	ds_write_b128 v112, v[136:139] offset:1024
	ds_write_b128 v112, v[140:143] offset:2048
	ds_write_b128 v112, v[144:147] offset:3072
	ds_read2_b32 v[32:33], v115 offset0:34 offset1:35
	ds_read2_b32 v[34:35], v115 offset0:36 offset1:37
	ds_read2_b32 v[36:37], v115 offset0:42 offset1:43
	ds_read2_b32 v[38:39], v115 offset0:44 offset1:45
	ds_read2_b32 v[40:41], v115 offset0:51 offset1:52
	ds_read2_b32 v[42:43], v115 offset0:53 offset1:54
	ds_read2_b32 v[44:45], v115 offset0:59 offset1:60
	ds_read2_b32 v[46:47], v115 offset0:61 offset1:62
	s_waitcnt lgkmcnt(0)
	v_mfma_f32_32x32x16_bf16 v[32:47], v[116:119], v[48:51], v[32:47]
	ds_read_b64_tr_b16 v[72:73], v231
	ds_read_b64_tr_b16 v[74:75], v231 offset:512
	ds_read_b64_tr_b16 v[76:77], v231 offset:2048
	ds_read_b64_tr_b16 v[78:79], v231 offset:2560
	ds_read_b64_tr_b16 v[220:221], v231 offset:1024
	ds_read_b64_tr_b16 v[222:223], v231 offset:1536
	ds_read_b64_tr_b16 v[224:225], v231 offset:3072
	ds_read_b64_tr_b16 v[226:227], v231 offset:3584
	v_mfma_f32_32x32x16_bf16 v[32:47], v[120:123], v[52:55], v[32:47]
	v_mfma_f32_32x32x16_bf16 v[32:47], v[124:127], v[56:59], v[32:47]
	v_mfma_f32_32x32x16_bf16 v[32:47], v[128:131], v[60:63], v[32:47]
	s_nop 11
	v_exp_f32_e32 v32, v32
	v_exp_f32_e32 v33, v33
	v_exp_f32_e32 v34, v34
	v_exp_f32_e32 v35, v35
	v_exp_f32_e32 v36, v36
	v_exp_f32_e32 v37, v37
	v_exp_f32_e32 v38, v38
	v_exp_f32_e32 v39, v39
	v_exp_f32_e32 v40, v40
	v_exp_f32_e32 v41, v41
	v_exp_f32_e32 v42, v42
	v_exp_f32_e32 v43, v43
	v_exp_f32_e32 v44, v44
	v_exp_f32_e32 v45, v45
	v_exp_f32_e32 v46, v46
	v_exp_f32_e32 v47, v47
	v_cvt_pk_bf16_f32 v64, v32, v33
	v_cvt_pk_bf16_f32 v65, v34, v35
	v_cvt_pk_bf16_f32 v66, v36, v37
	v_cvt_pk_bf16_f32 v67, v38, v39
	v_cvt_pk_bf16_f32 v68, v40, v41
	v_cvt_pk_bf16_f32 v69, v42, v43
	v_cvt_pk_bf16_f32 v70, v44, v45
	v_cvt_pk_bf16_f32 v71, v46, v47
	v_pk_add_f32 v[232:233], v[232:233], v[32:33]
	v_pk_add_f32 v[232:233], v[232:233], v[34:35]
	v_pk_add_f32 v[232:233], v[232:233], v[36:37]
	v_pk_add_f32 v[232:233], v[232:233], v[38:39]
	v_pk_add_f32 v[232:233], v[232:233], v[40:41]
	v_pk_add_f32 v[232:233], v[232:233], v[42:43]
	v_pk_add_f32 v[232:233], v[232:233], v[44:45]
	v_pk_add_f32 v[232:233], v[232:233], v[46:47]
	s_waitcnt lgkmcnt(0)
	v_mfma_f32_32x32x16_bf16 v[0:15], v[64:67], v[72:75], v[0:15]
	v_mfma_f32_32x32x16_bf16 v[16:31], v[64:67], v[76:79], v[16:31]
	v_mfma_f32_32x32x16_bf16 v[0:15], v[68:71], v[220:223], v[0:15]
	v_mfma_f32_32x32x16_bf16 v[16:31], v[68:71], v[224:227], v[16:31]
	global_load_dwordx4 v[116:119], v80, s[84:85]
	global_load_dwordx4 v[120:123], v80, s[84:85] offset:32
	global_load_dwordx4 v[124:127], v80, s[84:85] offset:64
	global_load_dwordx4 v[128:131], v80, s[84:85] offset:96
	global_load_dwordx4 v[132:135], v100, s[84:85] offset:768
	global_load_dwordx4 v[136:139], v149, s[84:85] offset:768
	global_load_dwordx4 v[140:143], v100, s[84:85] offset:832
	global_load_dwordx4 v[144:147], v149, s[84:85] offset:832
	s_add_u32 s84, s84, 0x30000
	s_addc_u32 s85, s85, 0
	s_waitcnt vmcnt(16)
	ds_write_b128 v112, v[172:175]
	ds_write_b128 v112, v[176:179] offset:1024
	ds_write_b128 v112, v[180:183] offset:2048
	ds_write_b128 v112, v[184:187] offset:3072
	ds_read2_b32 v[32:33], v115 offset0:68 offset1:69
	ds_read2_b32 v[34:35], v115 offset0:70 offset1:71
	ds_read2_b32 v[36:37], v115 offset0:76 offset1:77
	ds_read2_b32 v[38:39], v115 offset0:78 offset1:79
	ds_read2_b32 v[40:41], v115 offset0:85 offset1:86
	ds_read2_b32 v[42:43], v115 offset0:87 offset1:88
	ds_read2_b32 v[44:45], v115 offset0:93 offset1:94
	ds_read2_b32 v[46:47], v115 offset0:95 offset1:96
	s_waitcnt lgkmcnt(0)
	v_mfma_f32_32x32x16_bf16 v[32:47], v[156:159], v[48:51], v[32:47]
	ds_read_b64_tr_b16 v[72:73], v231
	ds_read_b64_tr_b16 v[74:75], v231 offset:512
	ds_read_b64_tr_b16 v[76:77], v231 offset:2048
	ds_read_b64_tr_b16 v[78:79], v231 offset:2560
	ds_read_b64_tr_b16 v[220:221], v231 offset:1024
	ds_read_b64_tr_b16 v[222:223], v231 offset:1536
	ds_read_b64_tr_b16 v[224:225], v231 offset:3072
	ds_read_b64_tr_b16 v[226:227], v231 offset:3584
	v_mfma_f32_32x32x16_bf16 v[32:47], v[160:163], v[52:55], v[32:47]
	v_mfma_f32_32x32x16_bf16 v[32:47], v[164:167], v[56:59], v[32:47]
	v_mfma_f32_32x32x16_bf16 v[32:47], v[168:171], v[60:63], v[32:47]
	s_nop 11
	v_exp_f32_e32 v32, v32
	v_exp_f32_e32 v33, v33
	v_exp_f32_e32 v34, v34
	v_exp_f32_e32 v35, v35
	v_exp_f32_e32 v36, v36
	v_exp_f32_e32 v37, v37
	v_exp_f32_e32 v38, v38
	v_exp_f32_e32 v39, v39
	v_exp_f32_e32 v40, v40
	v_exp_f32_e32 v41, v41
	v_exp_f32_e32 v42, v42
	v_exp_f32_e32 v43, v43
	v_exp_f32_e32 v44, v44
	v_exp_f32_e32 v45, v45
	v_exp_f32_e32 v46, v46
	v_exp_f32_e32 v47, v47
	v_cvt_pk_bf16_f32 v64, v32, v33
	v_cvt_pk_bf16_f32 v65, v34, v35
	v_cvt_pk_bf16_f32 v66, v36, v37
	v_cvt_pk_bf16_f32 v67, v38, v39
	v_cvt_pk_bf16_f32 v68, v40, v41
	v_cvt_pk_bf16_f32 v69, v42, v43
	v_cvt_pk_bf16_f32 v70, v44, v45
	v_cvt_pk_bf16_f32 v71, v46, v47
	v_pk_add_f32 v[232:233], v[232:233], v[32:33]
	v_pk_add_f32 v[232:233], v[232:233], v[34:35]
	v_pk_add_f32 v[232:233], v[232:233], v[36:37]
	v_pk_add_f32 v[232:233], v[232:233], v[38:39]
	v_pk_add_f32 v[232:233], v[232:233], v[40:41]
	v_pk_add_f32 v[232:233], v[232:233], v[42:43]
	v_pk_add_f32 v[232:233], v[232:233], v[44:45]
	v_pk_add_f32 v[232:233], v[232:233], v[46:47]
	s_waitcnt lgkmcnt(0)
	v_mfma_f32_32x32x16_bf16 v[0:15], v[64:67], v[72:75], v[0:15]
	v_mfma_f32_32x32x16_bf16 v[16:31], v[64:67], v[76:79], v[16:31]
	v_mfma_f32_32x32x16_bf16 v[0:15], v[68:71], v[220:223], v[0:15]
	v_mfma_f32_32x32x16_bf16 v[16:31], v[68:71], v[224:227], v[16:31]
	global_load_dwordx4 v[156:159], v80, s[84:85]
	global_load_dwordx4 v[160:163], v80, s[84:85] offset:32
	global_load_dwordx4 v[164:167], v80, s[84:85] offset:64
	global_load_dwordx4 v[168:171], v80, s[84:85] offset:96
	global_load_dwordx4 v[172:175], v100, s[84:85] offset:768
	global_load_dwordx4 v[176:179], v149, s[84:85] offset:768
	global_load_dwordx4 v[180:183], v100, s[84:85] offset:832
	global_load_dwordx4 v[184:187], v149, s[84:85] offset:832
	s_waitcnt vmcnt(16)
	ds_write_b128 v112, v[204:207]
	ds_write_b128 v112, v[208:211] offset:1024
	ds_write_b128 v112, v[212:215] offset:2048
	ds_write_b128 v112, v[216:219] offset:3072
	ds_read2_b32 v[32:33], v115 offset0:102 offset1:103
	ds_read2_b32 v[34:35], v115 offset0:104 offset1:105
	ds_read2_b32 v[36:37], v115 offset0:110 offset1:111
	ds_read2_b32 v[38:39], v115 offset0:112 offset1:113
	ds_read2_b32 v[40:41], v115 offset0:119 offset1:120
	ds_read2_b32 v[42:43], v115 offset0:121 offset1:122
	ds_read2_b32 v[44:45], v115 offset0:127 offset1:128
	ds_read2_b32 v[46:47], v115 offset0:129 offset1:130
	s_waitcnt lgkmcnt(0)
	v_mfma_f32_32x32x16_bf16 v[32:47], v[188:191], v[48:51], v[32:47]
	ds_read_b64_tr_b16 v[72:73], v231
	ds_read_b64_tr_b16 v[74:75], v231 offset:512
	ds_read_b64_tr_b16 v[76:77], v231 offset:2048
	ds_read_b64_tr_b16 v[78:79], v231 offset:2560
	ds_read_b64_tr_b16 v[220:221], v231 offset:1024
	ds_read_b64_tr_b16 v[222:223], v231 offset:1536
	ds_read_b64_tr_b16 v[224:225], v231 offset:3072
	ds_read_b64_tr_b16 v[226:227], v231 offset:3584
	v_mfma_f32_32x32x16_bf16 v[32:47], v[192:195], v[52:55], v[32:47]
	v_mfma_f32_32x32x16_bf16 v[32:47], v[196:199], v[56:59], v[32:47]
	v_mfma_f32_32x32x16_bf16 v[32:47], v[200:203], v[60:63], v[32:47]
	s_nop 11
	v_exp_f32_e32 v32, v32
	v_exp_f32_e32 v33, v33
	v_exp_f32_e32 v34, v34
	v_exp_f32_e32 v35, v35
	v_exp_f32_e32 v36, v36
	v_exp_f32_e32 v37, v37
	v_exp_f32_e32 v38, v38
	v_exp_f32_e32 v39, v39
	v_exp_f32_e32 v40, v40
	v_exp_f32_e32 v41, v41
	v_exp_f32_e32 v42, v42
	v_exp_f32_e32 v43, v43
	v_exp_f32_e32 v44, v44
	v_exp_f32_e32 v45, v45
	v_exp_f32_e32 v46, v46
	v_exp_f32_e32 v47, v47
	v_cvt_pk_bf16_f32 v64, v32, v33
	v_cvt_pk_bf16_f32 v65, v34, v35
	v_cvt_pk_bf16_f32 v66, v36, v37
	v_cvt_pk_bf16_f32 v67, v38, v39
	v_cvt_pk_bf16_f32 v68, v40, v41
	v_cvt_pk_bf16_f32 v69, v42, v43
	v_cvt_pk_bf16_f32 v70, v44, v45
	v_cvt_pk_bf16_f32 v71, v46, v47
	v_pk_add_f32 v[232:233], v[232:233], v[32:33]
	v_pk_add_f32 v[232:233], v[232:233], v[34:35]
	v_pk_add_f32 v[232:233], v[232:233], v[36:37]
	v_pk_add_f32 v[232:233], v[232:233], v[38:39]
	v_pk_add_f32 v[232:233], v[232:233], v[40:41]
	v_pk_add_f32 v[232:233], v[232:233], v[42:43]
	v_pk_add_f32 v[232:233], v[232:233], v[44:45]
	v_pk_add_f32 v[232:233], v[232:233], v[46:47]
	s_waitcnt lgkmcnt(0)
	v_mfma_f32_32x32x16_bf16 v[0:15], v[64:67], v[72:75], v[0:15]
	v_mfma_f32_32x32x16_bf16 v[16:31], v[64:67], v[76:79], v[16:31]
	v_mfma_f32_32x32x16_bf16 v[0:15], v[68:71], v[220:223], v[0:15]
	v_mfma_f32_32x32x16_bf16 v[16:31], v[68:71], v[224:227], v[16:31]
	global_load_dwordx4 v[188:191], v83, s[86:87]
	global_load_dwordx4 v[192:195], v83, s[86:87] offset:32
	global_load_dwordx4 v[196:199], v83, s[86:87] offset:64
	global_load_dwordx4 v[200:203], v83, s[86:87] offset:96
	global_load_dwordx4 v[204:207], v101, s[86:87] offset:768
	global_load_dwordx4 v[208:211], v150, s[86:87] offset:768
	global_load_dwordx4 v[212:215], v101, s[86:87] offset:832
	global_load_dwordx4 v[216:219], v150, s[86:87] offset:832
	s_add_u32 s86, s86, 0xc0000
	s_addc_u32 s87, s87, 0
	s_waitcnt vmcnt(16)
	ds_write_b128 v112, v[132:135]
	ds_write_b128 v112, v[136:139] offset:1024
	ds_write_b128 v112, v[140:143] offset:2048
	ds_write_b128 v112, v[144:147] offset:3072
	ds_read2_b32 v[32:33], v115 offset0:136 offset1:137
	ds_read2_b32 v[34:35], v115 offset0:138 offset1:139
	ds_read2_b32 v[36:37], v115 offset0:144 offset1:145
	ds_read2_b32 v[38:39], v115 offset0:146 offset1:147
	ds_read2_b32 v[40:41], v115 offset0:153 offset1:154
	ds_read2_b32 v[42:43], v115 offset0:155 offset1:156
	ds_read2_b32 v[44:45], v115 offset0:161 offset1:162
	ds_read2_b32 v[46:47], v115 offset0:163 offset1:164
	s_waitcnt lgkmcnt(0)
	v_mfma_f32_32x32x16_bf16 v[32:47], v[116:119], v[48:51], v[32:47]
	ds_read_b64_tr_b16 v[72:73], v231
	ds_read_b64_tr_b16 v[74:75], v231 offset:512
	ds_read_b64_tr_b16 v[76:77], v231 offset:2048
	ds_read_b64_tr_b16 v[78:79], v231 offset:2560
	ds_read_b64_tr_b16 v[220:221], v231 offset:1024
	ds_read_b64_tr_b16 v[222:223], v231 offset:1536
	ds_read_b64_tr_b16 v[224:225], v231 offset:3072
	ds_read_b64_tr_b16 v[226:227], v231 offset:3584
	v_mfma_f32_32x32x16_bf16 v[32:47], v[120:123], v[52:55], v[32:47]
	v_mfma_f32_32x32x16_bf16 v[32:47], v[124:127], v[56:59], v[32:47]
	v_mfma_f32_32x32x16_bf16 v[32:47], v[128:131], v[60:63], v[32:47]
	s_nop 11
	v_exp_f32_e32 v32, v32
	v_exp_f32_e32 v33, v33
	v_exp_f32_e32 v34, v34
	v_exp_f32_e32 v35, v35
	v_exp_f32_e32 v36, v36
	v_exp_f32_e32 v37, v37
	v_exp_f32_e32 v38, v38
	v_exp_f32_e32 v39, v39
	v_exp_f32_e32 v40, v40
	v_exp_f32_e32 v41, v41
	v_exp_f32_e32 v42, v42
	v_exp_f32_e32 v43, v43
	v_exp_f32_e32 v44, v44
	v_exp_f32_e32 v45, v45
	v_exp_f32_e32 v46, v46
	v_exp_f32_e32 v47, v47
	v_cvt_pk_bf16_f32 v64, v32, v33
	v_cvt_pk_bf16_f32 v65, v34, v35
	v_cvt_pk_bf16_f32 v66, v36, v37
	v_cvt_pk_bf16_f32 v67, v38, v39
	v_cvt_pk_bf16_f32 v68, v40, v41
	v_cvt_pk_bf16_f32 v69, v42, v43
	v_cvt_pk_bf16_f32 v70, v44, v45
	v_cvt_pk_bf16_f32 v71, v46, v47
	v_pk_add_f32 v[232:233], v[232:233], v[32:33]
	v_pk_add_f32 v[232:233], v[232:233], v[34:35]
	v_pk_add_f32 v[232:233], v[232:233], v[36:37]
	v_pk_add_f32 v[232:233], v[232:233], v[38:39]
	v_pk_add_f32 v[232:233], v[232:233], v[40:41]
	v_pk_add_f32 v[232:233], v[232:233], v[42:43]
	v_pk_add_f32 v[232:233], v[232:233], v[44:45]
	v_pk_add_f32 v[232:233], v[232:233], v[46:47]
	s_waitcnt lgkmcnt(0)
	v_mfma_f32_32x32x16_bf16 v[0:15], v[64:67], v[72:75], v[0:15]
	v_mfma_f32_32x32x16_bf16 v[16:31], v[64:67], v[76:79], v[16:31]
	v_mfma_f32_32x32x16_bf16 v[0:15], v[68:71], v[220:223], v[0:15]
	v_mfma_f32_32x32x16_bf16 v[16:31], v[68:71], v[224:227], v[16:31]
	global_load_dwordx4 v[116:119], v83, s[86:87]
	global_load_dwordx4 v[120:123], v83, s[86:87] offset:32
	global_load_dwordx4 v[124:127], v83, s[86:87] offset:64
	global_load_dwordx4 v[128:131], v83, s[86:87] offset:96
	global_load_dwordx4 v[132:135], v101, s[86:87] offset:768
	global_load_dwordx4 v[136:139], v150, s[86:87] offset:768
	global_load_dwordx4 v[140:143], v101, s[86:87] offset:832
	global_load_dwordx4 v[144:147], v150, s[86:87] offset:832
	s_add_u32 s86, s86, 0xc0000
	s_addc_u32 s87, s87, 0
	s_waitcnt vmcnt(16)
	ds_write_b128 v112, v[172:175]
	ds_write_b128 v112, v[176:179] offset:1024
	ds_write_b128 v112, v[180:183] offset:2048
	ds_write_b128 v112, v[184:187] offset:3072
	ds_read2_b32 v[32:33], v115 offset0:170 offset1:171
	ds_read2_b32 v[34:35], v115 offset0:172 offset1:173
	ds_read2_b32 v[36:37], v115 offset0:178 offset1:179
	ds_read2_b32 v[38:39], v115 offset0:180 offset1:181
	ds_read2_b32 v[40:41], v115 offset0:187 offset1:188
	ds_read2_b32 v[42:43], v115 offset0:189 offset1:190
	ds_read2_b32 v[44:45], v115 offset0:195 offset1:196
	ds_read2_b32 v[46:47], v115 offset0:197 offset1:198
	s_waitcnt lgkmcnt(0)
	v_mfma_f32_32x32x16_bf16 v[32:47], v[156:159], v[48:51], v[32:47]
	ds_read_b64_tr_b16 v[72:73], v231
	ds_read_b64_tr_b16 v[74:75], v231 offset:512
	ds_read_b64_tr_b16 v[76:77], v231 offset:2048
	ds_read_b64_tr_b16 v[78:79], v231 offset:2560
	ds_read_b64_tr_b16 v[220:221], v231 offset:1024
	ds_read_b64_tr_b16 v[222:223], v231 offset:1536
	ds_read_b64_tr_b16 v[224:225], v231 offset:3072
	ds_read_b64_tr_b16 v[226:227], v231 offset:3584
	v_mfma_f32_32x32x16_bf16 v[32:47], v[160:163], v[52:55], v[32:47]
	v_mfma_f32_32x32x16_bf16 v[32:47], v[164:167], v[56:59], v[32:47]
	v_mfma_f32_32x32x16_bf16 v[32:47], v[168:171], v[60:63], v[32:47]
	s_nop 11
	v_exp_f32_e32 v32, v32
	v_exp_f32_e32 v33, v33
	v_exp_f32_e32 v34, v34
	v_exp_f32_e32 v35, v35
	v_exp_f32_e32 v36, v36
	v_exp_f32_e32 v37, v37
	v_exp_f32_e32 v38, v38
	v_exp_f32_e32 v39, v39
	v_exp_f32_e32 v40, v40
	v_exp_f32_e32 v41, v41
	v_exp_f32_e32 v42, v42
	v_exp_f32_e32 v43, v43
	v_exp_f32_e32 v44, v44
	v_exp_f32_e32 v45, v45
	v_exp_f32_e32 v46, v46
	v_exp_f32_e32 v47, v47
	v_cvt_pk_bf16_f32 v64, v32, v33
	v_cvt_pk_bf16_f32 v65, v34, v35
	v_cvt_pk_bf16_f32 v66, v36, v37
	v_cvt_pk_bf16_f32 v67, v38, v39
	v_cvt_pk_bf16_f32 v68, v40, v41
	v_cvt_pk_bf16_f32 v69, v42, v43
	v_cvt_pk_bf16_f32 v70, v44, v45
	v_cvt_pk_bf16_f32 v71, v46, v47
	v_pk_add_f32 v[232:233], v[232:233], v[32:33]
	v_pk_add_f32 v[232:233], v[232:233], v[34:35]
	v_pk_add_f32 v[232:233], v[232:233], v[36:37]
	v_pk_add_f32 v[232:233], v[232:233], v[38:39]
	v_pk_add_f32 v[232:233], v[232:233], v[40:41]
	v_pk_add_f32 v[232:233], v[232:233], v[42:43]
	v_pk_add_f32 v[232:233], v[232:233], v[44:45]
	v_pk_add_f32 v[232:233], v[232:233], v[46:47]
	s_waitcnt lgkmcnt(0)
	v_mfma_f32_32x32x16_bf16 v[0:15], v[64:67], v[72:75], v[0:15]
	v_mfma_f32_32x32x16_bf16 v[16:31], v[64:67], v[76:79], v[16:31]
	v_mfma_f32_32x32x16_bf16 v[0:15], v[68:71], v[220:223], v[0:15]
	v_mfma_f32_32x32x16_bf16 v[16:31], v[68:71], v[224:227], v[16:31]
	global_load_dwordx4 v[156:159], v83, s[86:87]
	global_load_dwordx4 v[160:163], v83, s[86:87] offset:32
	global_load_dwordx4 v[164:167], v83, s[86:87] offset:64
	global_load_dwordx4 v[168:171], v83, s[86:87] offset:96
	global_load_dwordx4 v[172:175], v101, s[86:87] offset:768
	global_load_dwordx4 v[176:179], v150, s[86:87] offset:768
	global_load_dwordx4 v[180:183], v101, s[86:87] offset:832
	global_load_dwordx4 v[184:187], v150, s[86:87] offset:832
	s_add_u32 s86, s86, 0xc0000
	s_addc_u32 s87, s87, 0
	s_waitcnt vmcnt(16)
	ds_write_b128 v112, v[204:207]
	ds_write_b128 v112, v[208:211] offset:1024
	ds_write_b128 v112, v[212:215] offset:2048
	ds_write_b128 v112, v[216:219] offset:3072
	v_mov_b32_e32 v115, v229
	ds_read2_b32 v[32:33], v115 offset0:0 offset1:1
	ds_read2_b32 v[34:35], v115 offset0:2 offset1:3
	ds_read2_b32 v[36:37], v115 offset0:8 offset1:9
	ds_read2_b32 v[38:39], v115 offset0:10 offset1:11
	ds_read2_b32 v[40:41], v115 offset0:16 offset1:17
	ds_read2_b32 v[42:43], v115 offset0:18 offset1:19
	ds_read2_b32 v[44:45], v115 offset0:24 offset1:25
	ds_read2_b32 v[46:47], v115 offset0:26 offset1:27
	s_waitcnt lgkmcnt(0)
	v_mfma_f32_32x32x16_bf16 v[32:47], v[188:191], v[48:51], v[32:47]
	ds_read_b64_tr_b16 v[72:73], v231
	ds_read_b64_tr_b16 v[74:75], v231 offset:512
	ds_read_b64_tr_b16 v[76:77], v231 offset:2048
	ds_read_b64_tr_b16 v[78:79], v231 offset:2560
	ds_read_b64_tr_b16 v[220:221], v231 offset:1024
	ds_read_b64_tr_b16 v[222:223], v231 offset:1536
	ds_read_b64_tr_b16 v[224:225], v231 offset:3072
	ds_read_b64_tr_b16 v[226:227], v231 offset:3584
	v_mfma_f32_32x32x16_bf16 v[32:47], v[192:195], v[52:55], v[32:47]
	v_mfma_f32_32x32x16_bf16 v[32:47], v[196:199], v[56:59], v[32:47]
	v_mfma_f32_32x32x16_bf16 v[32:47], v[200:203], v[60:63], v[32:47]
	s_nop 11
	v_exp_f32_e32 v32, v32
	v_exp_f32_e32 v33, v33
	v_exp_f32_e32 v34, v34
	v_exp_f32_e32 v35, v35
	v_exp_f32_e32 v36, v36
	v_exp_f32_e32 v37, v37
	v_exp_f32_e32 v38, v38
	v_exp_f32_e32 v39, v39
	v_exp_f32_e32 v40, v40
	v_exp_f32_e32 v41, v41
	v_exp_f32_e32 v42, v42
	v_exp_f32_e32 v43, v43
	v_exp_f32_e32 v44, v44
	v_exp_f32_e32 v45, v45
	v_exp_f32_e32 v46, v46
	v_exp_f32_e32 v47, v47
	v_cvt_pk_bf16_f32 v64, v32, v33
	v_cvt_pk_bf16_f32 v65, v34, v35
	v_cvt_pk_bf16_f32 v66, v36, v37
	v_cvt_pk_bf16_f32 v67, v38, v39
	v_cvt_pk_bf16_f32 v68, v40, v41
	v_cvt_pk_bf16_f32 v69, v42, v43
	v_cvt_pk_bf16_f32 v70, v44, v45
	v_cvt_pk_bf16_f32 v71, v46, v47
	v_pk_add_f32 v[232:233], v[232:233], v[32:33]
	v_pk_add_f32 v[232:233], v[232:233], v[34:35]
	v_pk_add_f32 v[232:233], v[232:233], v[36:37]
	v_pk_add_f32 v[232:233], v[232:233], v[38:39]
	v_pk_add_f32 v[232:233], v[232:233], v[40:41]
	v_pk_add_f32 v[232:233], v[232:233], v[42:43]
	v_pk_add_f32 v[232:233], v[232:233], v[44:45]
	v_pk_add_f32 v[232:233], v[232:233], v[46:47]
	s_waitcnt lgkmcnt(0)
	v_mfma_f32_32x32x16_bf16 v[0:15], v[64:67], v[72:75], v[0:15]
	v_mfma_f32_32x32x16_bf16 v[16:31], v[64:67], v[76:79], v[16:31]
	v_mfma_f32_32x32x16_bf16 v[0:15], v[68:71], v[220:223], v[0:15]
	v_mfma_f32_32x32x16_bf16 v[16:31], v[68:71], v[224:227], v[16:31]
	global_load_dwordx4 v[188:191], v83, s[86:87]
	global_load_dwordx4 v[192:195], v83, s[86:87] offset:32
	global_load_dwordx4 v[196:199], v83, s[86:87] offset:64
	global_load_dwordx4 v[200:203], v83, s[86:87] offset:96
	global_load_dwordx4 v[204:207], v101, s[86:87] offset:768
	global_load_dwordx4 v[208:211], v150, s[86:87] offset:768
	global_load_dwordx4 v[212:215], v101, s[86:87] offset:832
	global_load_dwordx4 v[216:219], v150, s[86:87] offset:832
	s_add_u32 s86, s86, 0xc0000
	s_addc_u32 s87, s87, 0
	s_waitcnt vmcnt(16)
	ds_write_b128 v112, v[132:135]
	ds_write_b128 v112, v[136:139] offset:1024
	ds_write_b128 v112, v[140:143] offset:2048
	ds_write_b128 v112, v[144:147] offset:3072
	ds_read2_b32 v[32:33], v115 offset0:32 offset1:33
	ds_read2_b32 v[34:35], v115 offset0:34 offset1:35
	ds_read2_b32 v[36:37], v115 offset0:40 offset1:41
	ds_read2_b32 v[38:39], v115 offset0:42 offset1:43
	ds_read2_b32 v[40:41], v115 offset0:48 offset1:49
	ds_read2_b32 v[42:43], v115 offset0:50 offset1:51
	ds_read2_b32 v[44:45], v115 offset0:56 offset1:57
	ds_read2_b32 v[46:47], v115 offset0:58 offset1:59
	s_waitcnt lgkmcnt(0)
	v_mfma_f32_32x32x16_bf16 v[32:47], v[116:119], v[48:51], v[32:47]
	ds_read_b64_tr_b16 v[72:73], v231
	ds_read_b64_tr_b16 v[74:75], v231 offset:512
	ds_read_b64_tr_b16 v[76:77], v231 offset:2048
	ds_read_b64_tr_b16 v[78:79], v231 offset:2560
	ds_read_b64_tr_b16 v[220:221], v231 offset:1024
	ds_read_b64_tr_b16 v[222:223], v231 offset:1536
	ds_read_b64_tr_b16 v[224:225], v231 offset:3072
	ds_read_b64_tr_b16 v[226:227], v231 offset:3584
	v_mfma_f32_32x32x16_bf16 v[32:47], v[120:123], v[52:55], v[32:47]
	v_mfma_f32_32x32x16_bf16 v[32:47], v[124:127], v[56:59], v[32:47]
	v_mfma_f32_32x32x16_bf16 v[32:47], v[128:131], v[60:63], v[32:47]
	s_nop 11
	v_exp_f32_e32 v32, v32
	v_exp_f32_e32 v33, v33
	v_exp_f32_e32 v34, v34
	v_exp_f32_e32 v35, v35
	v_exp_f32_e32 v36, v36
	v_exp_f32_e32 v37, v37
	v_exp_f32_e32 v38, v38
	v_exp_f32_e32 v39, v39
	v_exp_f32_e32 v40, v40
	v_exp_f32_e32 v41, v41
	v_exp_f32_e32 v42, v42
	v_exp_f32_e32 v43, v43
	v_exp_f32_e32 v44, v44
	v_exp_f32_e32 v45, v45
	v_exp_f32_e32 v46, v46
	v_exp_f32_e32 v47, v47
	v_cvt_pk_bf16_f32 v64, v32, v33
	v_cvt_pk_bf16_f32 v65, v34, v35
	v_cvt_pk_bf16_f32 v66, v36, v37
	v_cvt_pk_bf16_f32 v67, v38, v39
	v_cvt_pk_bf16_f32 v68, v40, v41
	v_cvt_pk_bf16_f32 v69, v42, v43
	v_cvt_pk_bf16_f32 v70, v44, v45
	v_cvt_pk_bf16_f32 v71, v46, v47
	v_pk_add_f32 v[232:233], v[232:233], v[32:33]
	v_pk_add_f32 v[232:233], v[232:233], v[34:35]
	v_pk_add_f32 v[232:233], v[232:233], v[36:37]
	v_pk_add_f32 v[232:233], v[232:233], v[38:39]
	v_pk_add_f32 v[232:233], v[232:233], v[40:41]
	v_pk_add_f32 v[232:233], v[232:233], v[42:43]
	v_pk_add_f32 v[232:233], v[232:233], v[44:45]
	v_pk_add_f32 v[232:233], v[232:233], v[46:47]
	s_waitcnt lgkmcnt(0)
	v_mfma_f32_32x32x16_bf16 v[0:15], v[64:67], v[72:75], v[0:15]
	v_mfma_f32_32x32x16_bf16 v[16:31], v[64:67], v[76:79], v[16:31]
	v_mfma_f32_32x32x16_bf16 v[0:15], v[68:71], v[220:223], v[0:15]
	v_mfma_f32_32x32x16_bf16 v[16:31], v[68:71], v[224:227], v[16:31]
	global_load_dwordx4 v[116:119], v83, s[86:87]
	global_load_dwordx4 v[120:123], v83, s[86:87] offset:32
	global_load_dwordx4 v[124:127], v83, s[86:87] offset:64
	global_load_dwordx4 v[128:131], v83, s[86:87] offset:96
	global_load_dwordx4 v[132:135], v101, s[86:87] offset:768
	global_load_dwordx4 v[136:139], v150, s[86:87] offset:768
	global_load_dwordx4 v[140:143], v101, s[86:87] offset:832
	global_load_dwordx4 v[144:147], v150, s[86:87] offset:832
	s_add_u32 s86, s86, 0xc0000
	s_addc_u32 s87, s87, 0
	s_waitcnt vmcnt(16)
	ds_write_b128 v112, v[172:175]
	ds_write_b128 v112, v[176:179] offset:1024
	ds_write_b128 v112, v[180:183] offset:2048
	ds_write_b128 v112, v[184:187] offset:3072
	ds_read2_b32 v[32:33], v115 offset0:64 offset1:65
	ds_read2_b32 v[34:35], v115 offset0:66 offset1:67
	ds_read2_b32 v[36:37], v115 offset0:72 offset1:73
	ds_read2_b32 v[38:39], v115 offset0:74 offset1:75
	ds_read2_b32 v[40:41], v115 offset0:80 offset1:81
	ds_read2_b32 v[42:43], v115 offset0:82 offset1:83
	ds_read2_b32 v[44:45], v115 offset0:88 offset1:89
	ds_read2_b32 v[46:47], v115 offset0:90 offset1:91
	s_waitcnt lgkmcnt(0)
	v_mfma_f32_32x32x16_bf16 v[32:47], v[156:159], v[48:51], v[32:47]
	ds_read_b64_tr_b16 v[72:73], v231
	ds_read_b64_tr_b16 v[74:75], v231 offset:512
	ds_read_b64_tr_b16 v[76:77], v231 offset:2048
	ds_read_b64_tr_b16 v[78:79], v231 offset:2560
	ds_read_b64_tr_b16 v[220:221], v231 offset:1024
	ds_read_b64_tr_b16 v[222:223], v231 offset:1536
	ds_read_b64_tr_b16 v[224:225], v231 offset:3072
	ds_read_b64_tr_b16 v[226:227], v231 offset:3584
	v_mfma_f32_32x32x16_bf16 v[32:47], v[160:163], v[52:55], v[32:47]
	v_mfma_f32_32x32x16_bf16 v[32:47], v[164:167], v[56:59], v[32:47]
	v_mfma_f32_32x32x16_bf16 v[32:47], v[168:171], v[60:63], v[32:47]
	s_nop 11
	v_exp_f32_e32 v32, v32
	v_exp_f32_e32 v33, v33
	v_exp_f32_e32 v34, v34
	v_exp_f32_e32 v35, v35
	v_exp_f32_e32 v36, v36
	v_exp_f32_e32 v37, v37
	v_exp_f32_e32 v38, v38
	v_exp_f32_e32 v39, v39
	v_exp_f32_e32 v40, v40
	v_exp_f32_e32 v41, v41
	v_exp_f32_e32 v42, v42
	v_exp_f32_e32 v43, v43
	v_exp_f32_e32 v44, v44
	v_exp_f32_e32 v45, v45
	v_exp_f32_e32 v46, v46
	v_exp_f32_e32 v47, v47
	v_cvt_pk_bf16_f32 v64, v32, v33
	v_cvt_pk_bf16_f32 v65, v34, v35
	v_cvt_pk_bf16_f32 v66, v36, v37
	v_cvt_pk_bf16_f32 v67, v38, v39
	v_cvt_pk_bf16_f32 v68, v40, v41
	v_cvt_pk_bf16_f32 v69, v42, v43
	v_cvt_pk_bf16_f32 v70, v44, v45
	v_cvt_pk_bf16_f32 v71, v46, v47
	v_pk_add_f32 v[232:233], v[232:233], v[32:33]
	v_pk_add_f32 v[232:233], v[232:233], v[34:35]
	v_pk_add_f32 v[232:233], v[232:233], v[36:37]
	v_pk_add_f32 v[232:233], v[232:233], v[38:39]
	v_pk_add_f32 v[232:233], v[232:233], v[40:41]
	v_pk_add_f32 v[232:233], v[232:233], v[42:43]
	v_pk_add_f32 v[232:233], v[232:233], v[44:45]
	v_pk_add_f32 v[232:233], v[232:233], v[46:47]
	s_waitcnt lgkmcnt(0)
	v_mfma_f32_32x32x16_bf16 v[0:15], v[64:67], v[72:75], v[0:15]
	v_mfma_f32_32x32x16_bf16 v[16:31], v[64:67], v[76:79], v[16:31]
	v_mfma_f32_32x32x16_bf16 v[0:15], v[68:71], v[220:223], v[0:15]
	v_mfma_f32_32x32x16_bf16 v[16:31], v[68:71], v[224:227], v[16:31]
	global_load_dwordx4 v[156:159], v83, s[86:87]
	global_load_dwordx4 v[160:163], v83, s[86:87] offset:32
	global_load_dwordx4 v[164:167], v83, s[86:87] offset:64
	global_load_dwordx4 v[168:171], v83, s[86:87] offset:96
	global_load_dwordx4 v[172:175], v101, s[86:87] offset:768
	global_load_dwordx4 v[176:179], v150, s[86:87] offset:768
	global_load_dwordx4 v[180:183], v101, s[86:87] offset:832
	global_load_dwordx4 v[184:187], v150, s[86:87] offset:832
	s_add_u32 s86, s86, 0xc0000
	s_addc_u32 s87, s87, 0
	s_waitcnt vmcnt(16)
	ds_write_b128 v112, v[204:207]
	ds_write_b128 v112, v[208:211] offset:1024
	ds_write_b128 v112, v[212:215] offset:2048
	ds_write_b128 v112, v[216:219] offset:3072
	ds_read2_b32 v[32:33], v115 offset0:96 offset1:97
	ds_read2_b32 v[34:35], v115 offset0:98 offset1:99
	ds_read2_b32 v[36:37], v115 offset0:104 offset1:105
	ds_read2_b32 v[38:39], v115 offset0:106 offset1:107
	ds_read2_b32 v[40:41], v115 offset0:112 offset1:113
	ds_read2_b32 v[42:43], v115 offset0:114 offset1:115
	ds_read2_b32 v[44:45], v115 offset0:120 offset1:121
	ds_read2_b32 v[46:47], v115 offset0:122 offset1:123
	s_waitcnt lgkmcnt(0)
	v_mfma_f32_32x32x16_bf16 v[32:47], v[188:191], v[48:51], v[32:47]
	ds_read_b64_tr_b16 v[72:73], v231
	ds_read_b64_tr_b16 v[74:75], v231 offset:512
	ds_read_b64_tr_b16 v[76:77], v231 offset:2048
	ds_read_b64_tr_b16 v[78:79], v231 offset:2560
	ds_read_b64_tr_b16 v[220:221], v231 offset:1024
	ds_read_b64_tr_b16 v[222:223], v231 offset:1536
	ds_read_b64_tr_b16 v[224:225], v231 offset:3072
	ds_read_b64_tr_b16 v[226:227], v231 offset:3584
	v_mfma_f32_32x32x16_bf16 v[32:47], v[192:195], v[52:55], v[32:47]
	v_mfma_f32_32x32x16_bf16 v[32:47], v[196:199], v[56:59], v[32:47]
	v_mfma_f32_32x32x16_bf16 v[32:47], v[200:203], v[60:63], v[32:47]
	s_nop 11
	v_exp_f32_e32 v32, v32
	v_exp_f32_e32 v33, v33
	v_exp_f32_e32 v34, v34
	v_exp_f32_e32 v35, v35
	v_exp_f32_e32 v36, v36
	v_exp_f32_e32 v37, v37
	v_exp_f32_e32 v38, v38
	v_exp_f32_e32 v39, v39
	v_exp_f32_e32 v40, v40
	v_exp_f32_e32 v41, v41
	v_exp_f32_e32 v42, v42
	v_exp_f32_e32 v43, v43
	v_exp_f32_e32 v44, v44
	v_exp_f32_e32 v45, v45
	v_exp_f32_e32 v46, v46
	v_exp_f32_e32 v47, v47
	v_cvt_pk_bf16_f32 v64, v32, v33
	v_cvt_pk_bf16_f32 v65, v34, v35
	v_cvt_pk_bf16_f32 v66, v36, v37
	v_cvt_pk_bf16_f32 v67, v38, v39
	v_cvt_pk_bf16_f32 v68, v40, v41
	v_cvt_pk_bf16_f32 v69, v42, v43
	v_cvt_pk_bf16_f32 v70, v44, v45
	v_cvt_pk_bf16_f32 v71, v46, v47
	v_pk_add_f32 v[232:233], v[232:233], v[32:33]
	v_pk_add_f32 v[232:233], v[232:233], v[34:35]
	v_pk_add_f32 v[232:233], v[232:233], v[36:37]
	v_pk_add_f32 v[232:233], v[232:233], v[38:39]
	v_pk_add_f32 v[232:233], v[232:233], v[40:41]
	v_pk_add_f32 v[232:233], v[232:233], v[42:43]
	v_pk_add_f32 v[232:233], v[232:233], v[44:45]
	v_pk_add_f32 v[232:233], v[232:233], v[46:47]
	s_waitcnt lgkmcnt(0)
	v_mfma_f32_32x32x16_bf16 v[0:15], v[64:67], v[72:75], v[0:15]
	v_mfma_f32_32x32x16_bf16 v[16:31], v[64:67], v[76:79], v[16:31]
	v_mfma_f32_32x32x16_bf16 v[0:15], v[68:71], v[220:223], v[0:15]
	v_mfma_f32_32x32x16_bf16 v[16:31], v[68:71], v[224:227], v[16:31]
	global_load_dwordx4 v[188:191], v83, s[86:87]
	global_load_dwordx4 v[192:195], v83, s[86:87] offset:32
	global_load_dwordx4 v[196:199], v83, s[86:87] offset:64
	global_load_dwordx4 v[200:203], v83, s[86:87] offset:96
	global_load_dwordx4 v[204:207], v101, s[86:87] offset:768
	global_load_dwordx4 v[208:211], v150, s[86:87] offset:768
	global_load_dwordx4 v[212:215], v101, s[86:87] offset:832
	global_load_dwordx4 v[216:219], v150, s[86:87] offset:832
	s_add_u32 s86, s86, 0xc0000
	s_addc_u32 s87, s87, 0
	s_waitcnt vmcnt(16)
	ds_write_b128 v112, v[132:135]
	ds_write_b128 v112, v[136:139] offset:1024
	ds_write_b128 v112, v[140:143] offset:2048
	ds_write_b128 v112, v[144:147] offset:3072
	ds_read2_b32 v[32:33], v115 offset0:128 offset1:129
	ds_read2_b32 v[34:35], v115 offset0:130 offset1:131
	ds_read2_b32 v[36:37], v115 offset0:136 offset1:137
	ds_read2_b32 v[38:39], v115 offset0:138 offset1:139
	ds_read2_b32 v[40:41], v115 offset0:144 offset1:145
	ds_read2_b32 v[42:43], v115 offset0:146 offset1:147
	ds_read2_b32 v[44:45], v115 offset0:152 offset1:153
	ds_read2_b32 v[46:47], v115 offset0:154 offset1:155
	s_waitcnt lgkmcnt(0)
	v_mfma_f32_32x32x16_bf16 v[32:47], v[116:119], v[48:51], v[32:47]
	ds_read_b64_tr_b16 v[72:73], v231
	ds_read_b64_tr_b16 v[74:75], v231 offset:512
	ds_read_b64_tr_b16 v[76:77], v231 offset:2048
	ds_read_b64_tr_b16 v[78:79], v231 offset:2560
	ds_read_b64_tr_b16 v[220:221], v231 offset:1024
	ds_read_b64_tr_b16 v[222:223], v231 offset:1536
	ds_read_b64_tr_b16 v[224:225], v231 offset:3072
	ds_read_b64_tr_b16 v[226:227], v231 offset:3584
	v_mfma_f32_32x32x16_bf16 v[32:47], v[120:123], v[52:55], v[32:47]
	v_mfma_f32_32x32x16_bf16 v[32:47], v[124:127], v[56:59], v[32:47]
	v_mfma_f32_32x32x16_bf16 v[32:47], v[128:131], v[60:63], v[32:47]
	s_nop 11
	v_exp_f32_e32 v32, v32
	v_exp_f32_e32 v33, v33
	v_exp_f32_e32 v34, v34
	v_exp_f32_e32 v35, v35
	v_exp_f32_e32 v36, v36
	v_exp_f32_e32 v37, v37
	v_exp_f32_e32 v38, v38
	v_exp_f32_e32 v39, v39
	v_exp_f32_e32 v40, v40
	v_exp_f32_e32 v41, v41
	v_exp_f32_e32 v42, v42
	v_exp_f32_e32 v43, v43
	v_exp_f32_e32 v44, v44
	v_exp_f32_e32 v45, v45
	v_exp_f32_e32 v46, v46
	v_exp_f32_e32 v47, v47
	v_cvt_pk_bf16_f32 v64, v32, v33
	v_cvt_pk_bf16_f32 v65, v34, v35
	v_cvt_pk_bf16_f32 v66, v36, v37
	v_cvt_pk_bf16_f32 v67, v38, v39
	v_cvt_pk_bf16_f32 v68, v40, v41
	v_cvt_pk_bf16_f32 v69, v42, v43
	v_cvt_pk_bf16_f32 v70, v44, v45
	v_cvt_pk_bf16_f32 v71, v46, v47
	v_pk_add_f32 v[232:233], v[232:233], v[32:33]
	v_pk_add_f32 v[232:233], v[232:233], v[34:35]
	v_pk_add_f32 v[232:233], v[232:233], v[36:37]
	v_pk_add_f32 v[232:233], v[232:233], v[38:39]
	v_pk_add_f32 v[232:233], v[232:233], v[40:41]
	v_pk_add_f32 v[232:233], v[232:233], v[42:43]
	v_pk_add_f32 v[232:233], v[232:233], v[44:45]
	v_pk_add_f32 v[232:233], v[232:233], v[46:47]
	s_waitcnt lgkmcnt(0)
	v_mfma_f32_32x32x16_bf16 v[0:15], v[64:67], v[72:75], v[0:15]
	v_mfma_f32_32x32x16_bf16 v[16:31], v[64:67], v[76:79], v[16:31]
	v_mfma_f32_32x32x16_bf16 v[0:15], v[68:71], v[220:223], v[0:15]
	v_mfma_f32_32x32x16_bf16 v[16:31], v[68:71], v[224:227], v[16:31]
	global_load_dwordx4 v[116:119], v83, s[86:87]
	global_load_dwordx4 v[120:123], v83, s[86:87] offset:32
	global_load_dwordx4 v[124:127], v83, s[86:87] offset:64
	global_load_dwordx4 v[128:131], v83, s[86:87] offset:96
	global_load_dwordx4 v[132:135], v101, s[86:87] offset:768
	global_load_dwordx4 v[136:139], v150, s[86:87] offset:768
	global_load_dwordx4 v[140:143], v101, s[86:87] offset:832
	global_load_dwordx4 v[144:147], v150, s[86:87] offset:832
	s_waitcnt vmcnt(16)
	ds_write_b128 v112, v[172:175]
	ds_write_b128 v112, v[176:179] offset:1024
	ds_write_b128 v112, v[180:183] offset:2048
	ds_write_b128 v112, v[184:187] offset:3072
	ds_read2_b32 v[32:33], v115 offset0:160 offset1:161
	ds_read2_b32 v[34:35], v115 offset0:162 offset1:163
	ds_read2_b32 v[36:37], v115 offset0:168 offset1:169
	ds_read2_b32 v[38:39], v115 offset0:170 offset1:171
	ds_read2_b32 v[40:41], v115 offset0:176 offset1:177
	ds_read2_b32 v[42:43], v115 offset0:178 offset1:179
	ds_read2_b32 v[44:45], v115 offset0:184 offset1:185
	ds_read2_b32 v[46:47], v115 offset0:186 offset1:187
	s_waitcnt lgkmcnt(0)
	v_mfma_f32_32x32x16_bf16 v[32:47], v[156:159], v[48:51], v[32:47]
	ds_read_b64_tr_b16 v[72:73], v231
	ds_read_b64_tr_b16 v[74:75], v231 offset:512
	ds_read_b64_tr_b16 v[76:77], v231 offset:2048
	ds_read_b64_tr_b16 v[78:79], v231 offset:2560
	ds_read_b64_tr_b16 v[220:221], v231 offset:1024
	ds_read_b64_tr_b16 v[222:223], v231 offset:1536
	ds_read_b64_tr_b16 v[224:225], v231 offset:3072
	ds_read_b64_tr_b16 v[226:227], v231 offset:3584
	v_mfma_f32_32x32x16_bf16 v[32:47], v[160:163], v[52:55], v[32:47]
	v_mfma_f32_32x32x16_bf16 v[32:47], v[164:167], v[56:59], v[32:47]
	v_mfma_f32_32x32x16_bf16 v[32:47], v[168:171], v[60:63], v[32:47]
	s_nop 11
	v_exp_f32_e32 v32, v32
	v_exp_f32_e32 v33, v33
	v_exp_f32_e32 v34, v34
	v_exp_f32_e32 v35, v35
	v_exp_f32_e32 v36, v36
	v_exp_f32_e32 v37, v37
	v_exp_f32_e32 v38, v38
	v_exp_f32_e32 v39, v39
	v_exp_f32_e32 v40, v40
	v_exp_f32_e32 v41, v41
	v_exp_f32_e32 v42, v42
	v_exp_f32_e32 v43, v43
	v_exp_f32_e32 v44, v44
	v_exp_f32_e32 v45, v45
	v_exp_f32_e32 v46, v46
	v_exp_f32_e32 v47, v47
	v_cvt_pk_bf16_f32 v64, v32, v33
	v_cvt_pk_bf16_f32 v65, v34, v35
	v_cvt_pk_bf16_f32 v66, v36, v37
	v_cvt_pk_bf16_f32 v67, v38, v39
	v_cvt_pk_bf16_f32 v68, v40, v41
	v_cvt_pk_bf16_f32 v69, v42, v43
	v_cvt_pk_bf16_f32 v70, v44, v45
	v_cvt_pk_bf16_f32 v71, v46, v47
	v_pk_add_f32 v[232:233], v[232:233], v[32:33]
	v_pk_add_f32 v[232:233], v[232:233], v[34:35]
	v_pk_add_f32 v[232:233], v[232:233], v[36:37]
	v_pk_add_f32 v[232:233], v[232:233], v[38:39]
	v_pk_add_f32 v[232:233], v[232:233], v[40:41]
	v_pk_add_f32 v[232:233], v[232:233], v[42:43]
	v_pk_add_f32 v[232:233], v[232:233], v[44:45]
	v_pk_add_f32 v[232:233], v[232:233], v[46:47]
	s_waitcnt lgkmcnt(0)
	v_mfma_f32_32x32x16_bf16 v[0:15], v[64:67], v[72:75], v[0:15]
	v_mfma_f32_32x32x16_bf16 v[16:31], v[64:67], v[76:79], v[16:31]
	v_mfma_f32_32x32x16_bf16 v[0:15], v[68:71], v[220:223], v[0:15]
	v_mfma_f32_32x32x16_bf16 v[16:31], v[68:71], v[224:227], v[16:31]
	global_load_dwordx4 v[156:159], v99, s[88:89]
	global_load_dwordx4 v[160:163], v99, s[88:89] offset:32
	global_load_dwordx4 v[164:167], v99, s[88:89] offset:64
	global_load_dwordx4 v[168:171], v99, s[88:89] offset:96
	global_load_dwordx4 v[172:175], v148, s[88:89] offset:768
	global_load_dwordx4 v[176:179], v151, s[88:89] offset:768
	global_load_dwordx4 v[180:183], v148, s[88:89] offset:832
	global_load_dwordx4 v[184:187], v151, s[88:89] offset:832
	s_add_u32 s88, s88, 0x300000
	s_addc_u32 s89, s89, 0
	s_waitcnt vmcnt(16)
	ds_write_b128 v112, v[204:207]
	ds_write_b128 v112, v[208:211] offset:1024
	ds_write_b128 v112, v[212:215] offset:2048
	ds_write_b128 v112, v[216:219] offset:3072
	ds_read2_b32 v[32:33], v115 offset0:192 offset1:193
	ds_read2_b32 v[34:35], v115 offset0:194 offset1:195
	ds_read2_b32 v[36:37], v115 offset0:200 offset1:201
	ds_read2_b32 v[38:39], v115 offset0:202 offset1:203
	ds_read2_b32 v[40:41], v115 offset0:208 offset1:209
	ds_read2_b32 v[42:43], v115 offset0:210 offset1:211
	ds_read2_b32 v[44:45], v115 offset0:216 offset1:217
	ds_read2_b32 v[46:47], v115 offset0:218 offset1:219
	s_waitcnt lgkmcnt(0)
	v_mfma_f32_32x32x16_bf16 v[32:47], v[188:191], v[48:51], v[32:47]
	ds_read_b64_tr_b16 v[72:73], v231
	ds_read_b64_tr_b16 v[74:75], v231 offset:512
	ds_read_b64_tr_b16 v[76:77], v231 offset:2048
	ds_read_b64_tr_b16 v[78:79], v231 offset:2560
	ds_read_b64_tr_b16 v[220:221], v231 offset:1024
	ds_read_b64_tr_b16 v[222:223], v231 offset:1536
	ds_read_b64_tr_b16 v[224:225], v231 offset:3072
	ds_read_b64_tr_b16 v[226:227], v231 offset:3584
	v_mfma_f32_32x32x16_bf16 v[32:47], v[192:195], v[52:55], v[32:47]
	v_mfma_f32_32x32x16_bf16 v[32:47], v[196:199], v[56:59], v[32:47]
	v_mfma_f32_32x32x16_bf16 v[32:47], v[200:203], v[60:63], v[32:47]
	s_nop 11
	v_exp_f32_e32 v32, v32
	v_exp_f32_e32 v33, v33
	v_exp_f32_e32 v34, v34
	v_exp_f32_e32 v35, v35
	v_exp_f32_e32 v36, v36
	v_exp_f32_e32 v37, v37
	v_exp_f32_e32 v38, v38
	v_exp_f32_e32 v39, v39
	v_exp_f32_e32 v40, v40
	v_exp_f32_e32 v41, v41
	v_exp_f32_e32 v42, v42
	v_exp_f32_e32 v43, v43
	v_exp_f32_e32 v44, v44
	v_exp_f32_e32 v45, v45
	v_exp_f32_e32 v46, v46
	v_exp_f32_e32 v47, v47
	v_cvt_pk_bf16_f32 v64, v32, v33
	v_cvt_pk_bf16_f32 v65, v34, v35
	v_cvt_pk_bf16_f32 v66, v36, v37
	v_cvt_pk_bf16_f32 v67, v38, v39
	v_cvt_pk_bf16_f32 v68, v40, v41
	v_cvt_pk_bf16_f32 v69, v42, v43
	v_cvt_pk_bf16_f32 v70, v44, v45
	v_cvt_pk_bf16_f32 v71, v46, v47
	v_pk_add_f32 v[232:233], v[232:233], v[32:33]
	v_pk_add_f32 v[232:233], v[232:233], v[34:35]
	v_pk_add_f32 v[232:233], v[232:233], v[36:37]
	v_pk_add_f32 v[232:233], v[232:233], v[38:39]
	v_pk_add_f32 v[232:233], v[232:233], v[40:41]
	v_pk_add_f32 v[232:233], v[232:233], v[42:43]
	v_pk_add_f32 v[232:233], v[232:233], v[44:45]
	v_pk_add_f32 v[232:233], v[232:233], v[46:47]
	s_waitcnt lgkmcnt(0)
	v_mfma_f32_32x32x16_bf16 v[0:15], v[64:67], v[72:75], v[0:15]
	v_mfma_f32_32x32x16_bf16 v[16:31], v[64:67], v[76:79], v[16:31]
	v_mfma_f32_32x32x16_bf16 v[0:15], v[68:71], v[220:223], v[0:15]
	v_mfma_f32_32x32x16_bf16 v[16:31], v[68:71], v[224:227], v[16:31]
	global_load_dwordx4 v[188:191], v99, s[88:89]
	global_load_dwordx4 v[192:195], v99, s[88:89] offset:32
	global_load_dwordx4 v[196:199], v99, s[88:89] offset:64
	global_load_dwordx4 v[200:203], v99, s[88:89] offset:96
	global_load_dwordx4 v[204:207], v148, s[88:89] offset:768
	global_load_dwordx4 v[208:211], v151, s[88:89] offset:768
	global_load_dwordx4 v[212:215], v148, s[88:89] offset:832
	global_load_dwordx4 v[216:219], v151, s[88:89] offset:832
	s_add_u32 s88, s88, 0x300000
	s_addc_u32 s89, s89, 0
	s_waitcnt vmcnt(16)
	ds_write_b128 v112, v[132:135]
	ds_write_b128 v112, v[136:139] offset:1024
	ds_write_b128 v112, v[140:143] offset:2048
	ds_write_b128 v112, v[144:147] offset:3072
	ds_read2_b32 v[32:33], v115 offset0:224 offset1:225
	ds_read2_b32 v[34:35], v115 offset0:226 offset1:227
	ds_read2_b32 v[36:37], v115 offset0:232 offset1:233
	ds_read2_b32 v[38:39], v115 offset0:234 offset1:235
	ds_read2_b32 v[40:41], v115 offset0:240 offset1:241
	ds_read2_b32 v[42:43], v115 offset0:242 offset1:243
	ds_read2_b32 v[44:45], v115 offset0:248 offset1:249
	ds_read2_b32 v[46:47], v115 offset0:250 offset1:251
	s_waitcnt lgkmcnt(0)
	v_mfma_f32_32x32x16_bf16 v[32:47], v[116:119], v[48:51], v[32:47]
	ds_read_b64_tr_b16 v[72:73], v231
	ds_read_b64_tr_b16 v[74:75], v231 offset:512
	ds_read_b64_tr_b16 v[76:77], v231 offset:2048
	ds_read_b64_tr_b16 v[78:79], v231 offset:2560
	ds_read_b64_tr_b16 v[220:221], v231 offset:1024
	ds_read_b64_tr_b16 v[222:223], v231 offset:1536
	ds_read_b64_tr_b16 v[224:225], v231 offset:3072
	ds_read_b64_tr_b16 v[226:227], v231 offset:3584
	v_mfma_f32_32x32x16_bf16 v[32:47], v[120:123], v[52:55], v[32:47]
	v_mfma_f32_32x32x16_bf16 v[32:47], v[124:127], v[56:59], v[32:47]
	v_mfma_f32_32x32x16_bf16 v[32:47], v[128:131], v[60:63], v[32:47]
	s_nop 11
	v_exp_f32_e32 v32, v32
	v_exp_f32_e32 v33, v33
	v_exp_f32_e32 v34, v34
	v_exp_f32_e32 v35, v35
	v_exp_f32_e32 v36, v36
	v_exp_f32_e32 v37, v37
	v_exp_f32_e32 v38, v38
	v_exp_f32_e32 v39, v39
	v_exp_f32_e32 v40, v40
	v_exp_f32_e32 v41, v41
	v_exp_f32_e32 v42, v42
	v_exp_f32_e32 v43, v43
	v_exp_f32_e32 v44, v44
	v_exp_f32_e32 v45, v45
	v_exp_f32_e32 v46, v46
	v_exp_f32_e32 v47, v47
	v_cvt_pk_bf16_f32 v64, v32, v33
	v_cvt_pk_bf16_f32 v65, v34, v35
	v_cvt_pk_bf16_f32 v66, v36, v37
	v_cvt_pk_bf16_f32 v67, v38, v39
	v_cvt_pk_bf16_f32 v68, v40, v41
	v_cvt_pk_bf16_f32 v69, v42, v43
	v_cvt_pk_bf16_f32 v70, v44, v45
	v_cvt_pk_bf16_f32 v71, v46, v47
	v_pk_add_f32 v[232:233], v[232:233], v[32:33]
	v_pk_add_f32 v[232:233], v[232:233], v[34:35]
	v_pk_add_f32 v[232:233], v[232:233], v[36:37]
	v_pk_add_f32 v[232:233], v[232:233], v[38:39]
	v_pk_add_f32 v[232:233], v[232:233], v[40:41]
	v_pk_add_f32 v[232:233], v[232:233], v[42:43]
	v_pk_add_f32 v[232:233], v[232:233], v[44:45]
	v_pk_add_f32 v[232:233], v[232:233], v[46:47]
	s_waitcnt lgkmcnt(0)
	v_mfma_f32_32x32x16_bf16 v[0:15], v[64:67], v[72:75], v[0:15]
	v_mfma_f32_32x32x16_bf16 v[16:31], v[64:67], v[76:79], v[16:31]
	v_mfma_f32_32x32x16_bf16 v[0:15], v[68:71], v[220:223], v[0:15]
	v_mfma_f32_32x32x16_bf16 v[16:31], v[68:71], v[224:227], v[16:31]
	global_load_dwordx4 v[116:119], v99, s[88:89]
	global_load_dwordx4 v[120:123], v99, s[88:89] offset:32
	global_load_dwordx4 v[124:127], v99, s[88:89] offset:64
	global_load_dwordx4 v[128:131], v99, s[88:89] offset:96
	global_load_dwordx4 v[132:135], v148, s[88:89] offset:768
	global_load_dwordx4 v[136:139], v151, s[88:89] offset:768
	global_load_dwordx4 v[140:143], v148, s[88:89] offset:832
	global_load_dwordx4 v[144:147], v151, s[88:89] offset:832
	s_add_u32 s88, s88, 0x300000
	s_addc_u32 s89, s89, 0
	s_waitcnt vmcnt(16)
	ds_write_b128 v112, v[172:175]
	ds_write_b128 v112, v[176:179] offset:1024
	ds_write_b128 v112, v[180:183] offset:2048
	ds_write_b128 v112, v[184:187] offset:3072
	v_mov_b32_e32 v115, v230
	ds_read2_b32 v[32:33], v115 offset0:0 offset1:1
	ds_read2_b32 v[34:35], v115 offset0:2 offset1:3
	ds_read2_b32 v[36:37], v115 offset0:8 offset1:9
	ds_read2_b32 v[38:39], v115 offset0:10 offset1:11
	ds_read2_b32 v[40:41], v115 offset0:16 offset1:17
	ds_read2_b32 v[42:43], v115 offset0:18 offset1:19
	ds_read2_b32 v[44:45], v115 offset0:24 offset1:25
	ds_read2_b32 v[46:47], v115 offset0:26 offset1:27
	s_waitcnt lgkmcnt(0)
	v_mfma_f32_32x32x16_bf16 v[32:47], v[156:159], v[48:51], v[32:47]
	ds_read_b64_tr_b16 v[72:73], v231
	ds_read_b64_tr_b16 v[74:75], v231 offset:512
	ds_read_b64_tr_b16 v[76:77], v231 offset:2048
	ds_read_b64_tr_b16 v[78:79], v231 offset:2560
	ds_read_b64_tr_b16 v[220:221], v231 offset:1024
	ds_read_b64_tr_b16 v[222:223], v231 offset:1536
	ds_read_b64_tr_b16 v[224:225], v231 offset:3072
	ds_read_b64_tr_b16 v[226:227], v231 offset:3584
	v_mfma_f32_32x32x16_bf16 v[32:47], v[160:163], v[52:55], v[32:47]
	v_mfma_f32_32x32x16_bf16 v[32:47], v[164:167], v[56:59], v[32:47]
	v_mfma_f32_32x32x16_bf16 v[32:47], v[168:171], v[60:63], v[32:47]
	s_nop 11
	v_exp_f32_e32 v32, v32
	v_exp_f32_e32 v33, v33
	v_exp_f32_e32 v34, v34
	v_exp_f32_e32 v35, v35
	v_exp_f32_e32 v36, v36
	v_exp_f32_e32 v37, v37
	v_exp_f32_e32 v38, v38
	v_exp_f32_e32 v39, v39
	v_exp_f32_e32 v40, v40
	v_exp_f32_e32 v41, v41
	v_exp_f32_e32 v42, v42
	v_exp_f32_e32 v43, v43
	v_exp_f32_e32 v44, v44
	v_exp_f32_e32 v45, v45
	v_exp_f32_e32 v46, v46
	v_exp_f32_e32 v47, v47
	v_cvt_pk_bf16_f32 v64, v32, v33
	v_cvt_pk_bf16_f32 v65, v34, v35
	v_cvt_pk_bf16_f32 v66, v36, v37
	v_cvt_pk_bf16_f32 v67, v38, v39
	v_cvt_pk_bf16_f32 v68, v40, v41
	v_cvt_pk_bf16_f32 v69, v42, v43
	v_cvt_pk_bf16_f32 v70, v44, v45
	v_cvt_pk_bf16_f32 v71, v46, v47
	v_pk_add_f32 v[232:233], v[232:233], v[32:33]
	v_pk_add_f32 v[232:233], v[232:233], v[34:35]
	v_pk_add_f32 v[232:233], v[232:233], v[36:37]
	v_pk_add_f32 v[232:233], v[232:233], v[38:39]
	v_pk_add_f32 v[232:233], v[232:233], v[40:41]
	v_pk_add_f32 v[232:233], v[232:233], v[42:43]
	v_pk_add_f32 v[232:233], v[232:233], v[44:45]
	v_pk_add_f32 v[232:233], v[232:233], v[46:47]
	s_waitcnt lgkmcnt(0)
	v_mfma_f32_32x32x16_bf16 v[0:15], v[64:67], v[72:75], v[0:15]
	v_mfma_f32_32x32x16_bf16 v[16:31], v[64:67], v[76:79], v[16:31]
	v_mfma_f32_32x32x16_bf16 v[0:15], v[68:71], v[220:223], v[0:15]
	v_mfma_f32_32x32x16_bf16 v[16:31], v[68:71], v[224:227], v[16:31]
	global_load_dwordx4 v[156:159], v99, s[88:89]
	global_load_dwordx4 v[160:163], v99, s[88:89] offset:32
	global_load_dwordx4 v[164:167], v99, s[88:89] offset:64
	global_load_dwordx4 v[168:171], v99, s[88:89] offset:96
	global_load_dwordx4 v[172:175], v148, s[88:89] offset:768
	global_load_dwordx4 v[176:179], v151, s[88:89] offset:768
	global_load_dwordx4 v[180:183], v148, s[88:89] offset:832
	global_load_dwordx4 v[184:187], v151, s[88:89] offset:832
	s_add_u32 s88, s88, 0x300000
	s_addc_u32 s89, s89, 0
	s_waitcnt vmcnt(16)
	ds_write_b128 v112, v[204:207]
	ds_write_b128 v112, v[208:211] offset:1024
	ds_write_b128 v112, v[212:215] offset:2048
	ds_write_b128 v112, v[216:219] offset:3072
	ds_read2_b32 v[32:33], v115 offset0:32 offset1:33
	ds_read2_b32 v[34:35], v115 offset0:34 offset1:35
	ds_read2_b32 v[36:37], v115 offset0:40 offset1:41
	ds_read2_b32 v[38:39], v115 offset0:42 offset1:43
	ds_read2_b32 v[40:41], v115 offset0:48 offset1:49
	ds_read2_b32 v[42:43], v115 offset0:50 offset1:51
	ds_read2_b32 v[44:45], v115 offset0:56 offset1:57
	ds_read2_b32 v[46:47], v115 offset0:58 offset1:59
	s_waitcnt lgkmcnt(0)
	v_mfma_f32_32x32x16_bf16 v[32:47], v[188:191], v[48:51], v[32:47]
	ds_read_b64_tr_b16 v[72:73], v231
	ds_read_b64_tr_b16 v[74:75], v231 offset:512
	ds_read_b64_tr_b16 v[76:77], v231 offset:2048
	ds_read_b64_tr_b16 v[78:79], v231 offset:2560
	ds_read_b64_tr_b16 v[220:221], v231 offset:1024
	ds_read_b64_tr_b16 v[222:223], v231 offset:1536
	ds_read_b64_tr_b16 v[224:225], v231 offset:3072
	ds_read_b64_tr_b16 v[226:227], v231 offset:3584
	v_mfma_f32_32x32x16_bf16 v[32:47], v[192:195], v[52:55], v[32:47]
	v_mfma_f32_32x32x16_bf16 v[32:47], v[196:199], v[56:59], v[32:47]
	v_mfma_f32_32x32x16_bf16 v[32:47], v[200:203], v[60:63], v[32:47]
	s_nop 11
	v_exp_f32_e32 v32, v32
	v_exp_f32_e32 v33, v33
	v_exp_f32_e32 v34, v34
	v_exp_f32_e32 v35, v35
	v_exp_f32_e32 v36, v36
	v_exp_f32_e32 v37, v37
	v_exp_f32_e32 v38, v38
	v_exp_f32_e32 v39, v39
	v_exp_f32_e32 v40, v40
	v_exp_f32_e32 v41, v41
	v_exp_f32_e32 v42, v42
	v_exp_f32_e32 v43, v43
	v_exp_f32_e32 v44, v44
	v_exp_f32_e32 v45, v45
	v_exp_f32_e32 v46, v46
	v_exp_f32_e32 v47, v47
	v_cvt_pk_bf16_f32 v64, v32, v33
	v_cvt_pk_bf16_f32 v65, v34, v35
	v_cvt_pk_bf16_f32 v66, v36, v37
	v_cvt_pk_bf16_f32 v67, v38, v39
	v_cvt_pk_bf16_f32 v68, v40, v41
	v_cvt_pk_bf16_f32 v69, v42, v43
	v_cvt_pk_bf16_f32 v70, v44, v45
	v_cvt_pk_bf16_f32 v71, v46, v47
	v_pk_add_f32 v[232:233], v[232:233], v[32:33]
	v_pk_add_f32 v[232:233], v[232:233], v[34:35]
	v_pk_add_f32 v[232:233], v[232:233], v[36:37]
	v_pk_add_f32 v[232:233], v[232:233], v[38:39]
	v_pk_add_f32 v[232:233], v[232:233], v[40:41]
	v_pk_add_f32 v[232:233], v[232:233], v[42:43]
	v_pk_add_f32 v[232:233], v[232:233], v[44:45]
	v_pk_add_f32 v[232:233], v[232:233], v[46:47]
	s_waitcnt lgkmcnt(0)
	v_mfma_f32_32x32x16_bf16 v[0:15], v[64:67], v[72:75], v[0:15]
	v_mfma_f32_32x32x16_bf16 v[16:31], v[64:67], v[76:79], v[16:31]
	v_mfma_f32_32x32x16_bf16 v[0:15], v[68:71], v[220:223], v[0:15]
	v_mfma_f32_32x32x16_bf16 v[16:31], v[68:71], v[224:227], v[16:31]
	global_load_dwordx4 v[188:191], v99, s[88:89]
	global_load_dwordx4 v[192:195], v99, s[88:89] offset:32
	global_load_dwordx4 v[196:199], v99, s[88:89] offset:64
	global_load_dwordx4 v[200:203], v99, s[88:89] offset:96
	global_load_dwordx4 v[204:207], v148, s[88:89] offset:768
	global_load_dwordx4 v[208:211], v151, s[88:89] offset:768
	global_load_dwordx4 v[212:215], v148, s[88:89] offset:832
	global_load_dwordx4 v[216:219], v151, s[88:89] offset:832
	s_waitcnt vmcnt(16)
	ds_write_b128 v112, v[132:135]
	ds_write_b128 v112, v[136:139] offset:1024
	ds_write_b128 v112, v[140:143] offset:2048
	ds_write_b128 v112, v[144:147] offset:3072
	ds_read2_b32 v[32:33], v115 offset0:64 offset1:65
	ds_read2_b32 v[34:35], v115 offset0:66 offset1:67
	ds_read2_b32 v[36:37], v115 offset0:72 offset1:73
	ds_read2_b32 v[38:39], v115 offset0:74 offset1:75
	ds_read2_b32 v[40:41], v115 offset0:80 offset1:81
	ds_read2_b32 v[42:43], v115 offset0:82 offset1:83
	ds_read2_b32 v[44:45], v115 offset0:88 offset1:89
	ds_read2_b32 v[46:47], v115 offset0:90 offset1:91
	s_waitcnt lgkmcnt(0)
	v_mfma_f32_32x32x16_bf16 v[32:47], v[116:119], v[48:51], v[32:47]
	ds_read_b64_tr_b16 v[72:73], v231
	ds_read_b64_tr_b16 v[74:75], v231 offset:512
	ds_read_b64_tr_b16 v[76:77], v231 offset:2048
	ds_read_b64_tr_b16 v[78:79], v231 offset:2560
	ds_read_b64_tr_b16 v[220:221], v231 offset:1024
	ds_read_b64_tr_b16 v[222:223], v231 offset:1536
	ds_read_b64_tr_b16 v[224:225], v231 offset:3072
	ds_read_b64_tr_b16 v[226:227], v231 offset:3584
	v_mfma_f32_32x32x16_bf16 v[32:47], v[120:123], v[52:55], v[32:47]
	v_mfma_f32_32x32x16_bf16 v[32:47], v[124:127], v[56:59], v[32:47]
	v_mfma_f32_32x32x16_bf16 v[32:47], v[128:131], v[60:63], v[32:47]
	s_nop 11
	v_exp_f32_e32 v32, v32
	v_exp_f32_e32 v33, v33
	v_exp_f32_e32 v34, v34
	v_exp_f32_e32 v35, v35
	v_exp_f32_e32 v36, v36
	v_exp_f32_e32 v37, v37
	v_exp_f32_e32 v38, v38
	v_exp_f32_e32 v39, v39
	v_exp_f32_e32 v40, v40
	v_exp_f32_e32 v41, v41
	v_exp_f32_e32 v42, v42
	v_exp_f32_e32 v43, v43
	v_exp_f32_e32 v44, v44
	v_exp_f32_e32 v45, v45
	v_exp_f32_e32 v46, v46
	v_exp_f32_e32 v47, v47
	v_cvt_pk_bf16_f32 v64, v32, v33
	v_cvt_pk_bf16_f32 v65, v34, v35
	v_cvt_pk_bf16_f32 v66, v36, v37
	v_cvt_pk_bf16_f32 v67, v38, v39
	v_cvt_pk_bf16_f32 v68, v40, v41
	v_cvt_pk_bf16_f32 v69, v42, v43
	v_cvt_pk_bf16_f32 v70, v44, v45
	v_cvt_pk_bf16_f32 v71, v46, v47
	v_pk_add_f32 v[232:233], v[232:233], v[32:33]
	v_pk_add_f32 v[232:233], v[232:233], v[34:35]
	v_pk_add_f32 v[232:233], v[232:233], v[36:37]
	v_pk_add_f32 v[232:233], v[232:233], v[38:39]
	v_pk_add_f32 v[232:233], v[232:233], v[40:41]
	v_pk_add_f32 v[232:233], v[232:233], v[42:43]
	v_pk_add_f32 v[232:233], v[232:233], v[44:45]
	v_pk_add_f32 v[232:233], v[232:233], v[46:47]
	s_waitcnt lgkmcnt(0)
	v_mfma_f32_32x32x16_bf16 v[0:15], v[64:67], v[72:75], v[0:15]
	v_mfma_f32_32x32x16_bf16 v[16:31], v[64:67], v[76:79], v[16:31]
	v_mfma_f32_32x32x16_bf16 v[0:15], v[68:71], v[220:223], v[0:15]
	v_mfma_f32_32x32x16_bf16 v[16:31], v[68:71], v[224:227], v[16:31]
	s_waitcnt vmcnt(8)
	ds_write_b128 v112, v[172:175]
	ds_write_b128 v112, v[176:179] offset:1024
	ds_write_b128 v112, v[180:183] offset:2048
	ds_write_b128 v112, v[184:187] offset:3072
	ds_read2_b32 v[32:33], v115 offset0:96 offset1:97
	ds_read2_b32 v[34:35], v115 offset0:98 offset1:99
	ds_read2_b32 v[36:37], v115 offset0:104 offset1:105
	ds_read2_b32 v[38:39], v115 offset0:106 offset1:107
	ds_read2_b32 v[40:41], v115 offset0:112 offset1:113
	ds_read2_b32 v[42:43], v115 offset0:114 offset1:115
	ds_read2_b32 v[44:45], v115 offset0:120 offset1:121
	ds_read2_b32 v[46:47], v115 offset0:122 offset1:123
	s_waitcnt lgkmcnt(0)
; __device__ __forceinline__ int crow(int r, int hi) { return (r & 3) + 8 * (r >> 2) + 4 * hi; }
; __device__ __forceinline__ void dil_unit(LAS unsigned char* lds, bf16_t* proj, int seq, int hd, int T0, int rho) {
;     ...
;     l += __shfl_xor(l, 32);
; #pragma unroll
;     for (int rr = 0; rr < 16; ++rr) {
;         const int j = crow(rr, hi);
;         const float il = __builtin_amdgcn_rcpf(__shfl(l, j));
	v_mfma_f32_32x32x16_bf16 v[32:47], v[156:159], v[48:51], v[32:47]
	ds_read_b64_tr_b16 v[72:73], v231
	ds_read_b64_tr_b16 v[74:75], v231 offset:512
	ds_read_b64_tr_b16 v[76:77], v231 offset:2048
	ds_read_b64_tr_b16 v[78:79], v231 offset:2560
	ds_read_b64_tr_b16 v[220:221], v231 offset:1024
	ds_read_b64_tr_b16 v[222:223], v231 offset:1536
	ds_read_b64_tr_b16 v[224:225], v231 offset:3072
	ds_read_b64_tr_b16 v[226:227], v231 offset:3584
	v_mfma_f32_32x32x16_bf16 v[32:47], v[160:163], v[52:55], v[32:47]
	v_mfma_f32_32x32x16_bf16 v[32:47], v[164:167], v[56:59], v[32:47]
	v_mfma_f32_32x32x16_bf16 v[32:47], v[168:171], v[60:63], v[32:47]
	s_nop 11
	v_exp_f32_e32 v32, v32
	v_exp_f32_e32 v33, v33
	v_exp_f32_e32 v34, v34
	v_exp_f32_e32 v35, v35
	v_exp_f32_e32 v36, v36
	v_exp_f32_e32 v37, v37
	v_exp_f32_e32 v38, v38
	v_exp_f32_e32 v39, v39
	v_exp_f32_e32 v40, v40
	v_exp_f32_e32 v41, v41
	v_exp_f32_e32 v42, v42
	v_exp_f32_e32 v43, v43
	v_exp_f32_e32 v44, v44
	v_exp_f32_e32 v45, v45
	v_exp_f32_e32 v46, v46
	v_exp_f32_e32 v47, v47
	v_cvt_pk_bf16_f32 v64, v32, v33
	v_cvt_pk_bf16_f32 v65, v34, v35
	v_cvt_pk_bf16_f32 v66, v36, v37
	v_cvt_pk_bf16_f32 v67, v38, v39
	v_cvt_pk_bf16_f32 v68, v40, v41
	v_cvt_pk_bf16_f32 v69, v42, v43
	v_cvt_pk_bf16_f32 v70, v44, v45
	v_cvt_pk_bf16_f32 v71, v46, v47
	v_pk_add_f32 v[232:233], v[232:233], v[32:33]
	v_pk_add_f32 v[232:233], v[232:233], v[34:35]
	v_pk_add_f32 v[232:233], v[232:233], v[36:37]
	v_pk_add_f32 v[232:233], v[232:233], v[38:39]
	v_pk_add_f32 v[232:233], v[232:233], v[40:41]
	v_pk_add_f32 v[232:233], v[232:233], v[42:43]
	v_pk_add_f32 v[232:233], v[232:233], v[44:45]
	v_pk_add_f32 v[232:233], v[232:233], v[46:47]
	s_waitcnt lgkmcnt(0)
	v_mfma_f32_32x32x16_bf16 v[0:15], v[64:67], v[72:75], v[0:15]
	v_mfma_f32_32x32x16_bf16 v[16:31], v[64:67], v[76:79], v[16:31]
	v_mfma_f32_32x32x16_bf16 v[0:15], v[68:71], v[220:223], v[0:15]
	v_mfma_f32_32x32x16_bf16 v[16:31], v[68:71], v[224:227], v[16:31]
	s_waitcnt vmcnt(0)
	ds_write_b128 v112, v[204:207]
	ds_write_b128 v112, v[208:211] offset:1024
	ds_write_b128 v112, v[212:215] offset:2048
	ds_write_b128 v112, v[216:219] offset:3072
	ds_read2_b32 v[32:33], v115 offset0:128 offset1:129
	ds_read2_b32 v[34:35], v115 offset0:130 offset1:131
	ds_read2_b32 v[36:37], v115 offset0:136 offset1:137
	ds_read2_b32 v[38:39], v115 offset0:138 offset1:139
	ds_read2_b32 v[40:41], v115 offset0:144 offset1:145
	ds_read2_b32 v[42:43], v115 offset0:146 offset1:147
	ds_read2_b32 v[44:45], v115 offset0:152 offset1:153
	ds_read2_b32 v[46:47], v115 offset0:154 offset1:155
	s_waitcnt lgkmcnt(0)
	v_mfma_f32_32x32x16_bf16 v[32:47], v[188:191], v[48:51], v[32:47]
	ds_read_b64_tr_b16 v[72:73], v231
	ds_read_b64_tr_b16 v[74:75], v231 offset:512
	ds_read_b64_tr_b16 v[76:77], v231 offset:2048
	ds_read_b64_tr_b16 v[78:79], v231 offset:2560
	ds_read_b64_tr_b16 v[220:221], v231 offset:1024
	ds_read_b64_tr_b16 v[222:223], v231 offset:1536
	ds_read_b64_tr_b16 v[224:225], v231 offset:3072
	ds_read_b64_tr_b16 v[226:227], v231 offset:3584
	v_mfma_f32_32x32x16_bf16 v[32:47], v[192:195], v[52:55], v[32:47]
	v_mfma_f32_32x32x16_bf16 v[32:47], v[196:199], v[56:59], v[32:47]
	v_mfma_f32_32x32x16_bf16 v[32:47], v[200:203], v[60:63], v[32:47]
	s_nop 11
	v_exp_f32_e32 v32, v32
	v_exp_f32_e32 v33, v33
	v_exp_f32_e32 v34, v34
	v_exp_f32_e32 v35, v35
	v_exp_f32_e32 v36, v36
	v_exp_f32_e32 v37, v37
	v_exp_f32_e32 v38, v38
	v_exp_f32_e32 v39, v39
	v_exp_f32_e32 v40, v40
	v_exp_f32_e32 v41, v41
	v_exp_f32_e32 v42, v42
	v_exp_f32_e32 v43, v43
	v_exp_f32_e32 v44, v44
	v_exp_f32_e32 v45, v45
	v_exp_f32_e32 v46, v46
	v_exp_f32_e32 v47, v47
	v_cvt_pk_bf16_f32 v64, v32, v33
	v_cvt_pk_bf16_f32 v65, v34, v35
	v_cvt_pk_bf16_f32 v66, v36, v37
	v_cvt_pk_bf16_f32 v67, v38, v39
	v_cvt_pk_bf16_f32 v68, v40, v41
	v_cvt_pk_bf16_f32 v69, v42, v43
	v_cvt_pk_bf16_f32 v70, v44, v45
	v_cvt_pk_bf16_f32 v71, v46, v47
	v_pk_add_f32 v[232:233], v[232:233], v[32:33]
	v_pk_add_f32 v[232:233], v[232:233], v[34:35]
	v_pk_add_f32 v[232:233], v[232:233], v[36:37]
	v_pk_add_f32 v[232:233], v[232:233], v[38:39]
	v_pk_add_f32 v[232:233], v[232:233], v[40:41]
	v_pk_add_f32 v[232:233], v[232:233], v[42:43]
	v_pk_add_f32 v[232:233], v[232:233], v[44:45]
	v_pk_add_f32 v[232:233], v[232:233], v[46:47]
	s_waitcnt lgkmcnt(0)
	v_mfma_f32_32x32x16_bf16 v[0:15], v[64:67], v[72:75], v[0:15]
	v_mfma_f32_32x32x16_bf16 v[16:31], v[64:67], v[76:79], v[16:31]
	v_mfma_f32_32x32x16_bf16 v[0:15], v[68:71], v[220:223], v[0:15]
	v_mfma_f32_32x32x16_bf16 v[16:31], v[68:71], v[224:227], v[16:31]
	v_add_f32_e32 v113, v232, v233
	v_or_b32_e32 v114, 1, v107
	v_or_b32_e32 v97, 2, v107
	v_or_b32_e32 v96, 3, v107
	v_or_b32_e32 v95, 8, v107
	v_or_b32_e32 v94, 9, v107
	v_or_b32_e32 v93, 10, v107
	v_or_b32_e32 v92, 11, v107
	v_or_b32_e32 v91, 16, v107
	v_or_b32_e32 v90, 17, v107
	v_or_b32_e32 v89, 18, v107
	v_or_b32_e32 v88, 19, v107
	v_or_b32_e32 v87, 24, v107
	v_or_b32_e32 v86, 25, v107
	v_or_b32_e32 v85, 26, v107
	v_or_b32_e32 v84, 27, v107
	s_nop 11
	s_branch .LBB0_1265
